# v43 + no per-segment s_setprio flips in the GEMM K-loops (all waves stay at priority 0)
# baseline (speedup 1.0000x reference)
.LBB0_394:
	s_add_u32 s0, s24, 0xfff80080
	s_addc_u32 s1, s25, -1
	s_add_i32 s33, 0, 0x10000
	s_cmp_eq_u32 s60, 28
	s_cselect_b32 s29, s7, s1
	s_cselect_b32 s28, s19, s0
	s_cselect_b32 s27, s17, s59
	s_cselect_b32 s26, s49, s58
	s_add_i32 s55, 0, 0x14000
	ds_read_b128 v[142:145], v151
	ds_read_b128 v[146:149], v151 offset:1024
	ds_read_b128 v[154:157], v151 offset:2048
	ds_read_b128 v[158:161], v151 offset:3072
	ds_read_b128 v[162:165], v151 offset:16384
	ds_read_b128 v[166:169], v151 offset:17408
	ds_read_b128 v[170:173], v151 offset:18432
	ds_read_b128 v[174:177], v151 offset:19456
	s_add_i32 m0, s9, 0xc000
	ds_read_b128 v[178:181], v153
	ds_read_b128 v[182:185], v153 offset:1024
	ds_read_b128 v[186:189], v153 offset:2048
	ds_read_b128 v[190:193], v153 offset:3072
	ds_read_b128 v[194:197], v153 offset:4096
	ds_read_b128 v[198:201], v153 offset:5120
	ds_read_b128 v[208:211], v153 offset:6144
	ds_read_b128 v[212:215], v153 offset:7168
	global_load_lds_dwordx4 v138, s[24:25]
	s_add_i32 m0, s9, 0xe000
	s_nop 0
	global_load_lds_dwordx4 v140, s[24:25]
	s_waitcnt vmcnt(8)
	s_waitcnt lgkmcnt(0)
	s_barrier
	v_mfma_f32_16x16x32_bf16 v[126:129], v[142:145], v[178:181], v[126:129]
	v_mfma_f32_16x16x32_bf16 v[122:125], v[154:157], v[178:181], v[122:125]
	v_mfma_f32_16x16x32_bf16 v[110:113], v[142:145], v[186:189], v[110:113]
	v_mfma_f32_16x16x32_bf16 v[106:109], v[154:157], v[186:189], v[106:109]
	v_mfma_f32_16x16x32_bf16 v[94:97], v[142:145], v[194:197], v[94:97]
	v_mfma_f32_16x16x32_bf16 v[90:93], v[154:157], v[194:197], v[90:93]
	v_mfma_f32_16x16x32_bf16 v[78:81], v[142:145], v[208:211], v[78:81]
	v_mfma_f32_16x16x32_bf16 v[74:77], v[154:157], v[208:211], v[74:77]
	v_mfma_f32_16x16x32_bf16 v[126:129], v[146:149], v[182:185], v[126:129]
	v_mfma_f32_16x16x32_bf16 v[122:125], v[158:161], v[182:185], v[122:125]
	v_mfma_f32_16x16x32_bf16 v[110:113], v[146:149], v[190:193], v[110:113]
	v_mfma_f32_16x16x32_bf16 v[106:109], v[158:161], v[190:193], v[106:109]
	v_mfma_f32_16x16x32_bf16 v[94:97], v[146:149], v[198:201], v[94:97]
	v_mfma_f32_16x16x32_bf16 v[90:93], v[158:161], v[198:201], v[90:93]
	v_mfma_f32_16x16x32_bf16 v[78:81], v[146:149], v[212:215], v[78:81]
	v_mfma_f32_16x16x32_bf16 v[74:77], v[158:161], v[212:215], v[74:77]
	v_mfma_f32_16x16x32_bf16 v[118:121], v[162:165], v[178:181], v[118:121]
	v_mfma_f32_16x16x32_bf16 v[114:117], v[170:173], v[178:181], v[114:117]
	v_mfma_f32_16x16x32_bf16 v[102:105], v[162:165], v[186:189], v[102:105]
	v_mfma_f32_16x16x32_bf16 v[98:101], v[170:173], v[186:189], v[98:101]
	v_mfma_f32_16x16x32_bf16 v[86:89], v[162:165], v[194:197], v[86:89]
	v_mfma_f32_16x16x32_bf16 v[82:85], v[170:173], v[194:197], v[82:85]
	v_mfma_f32_16x16x32_bf16 v[70:73], v[162:165], v[208:211], v[70:73]
	v_mfma_f32_16x16x32_bf16 v[66:69], v[170:173], v[208:211], v[66:69]
	v_mfma_f32_16x16x32_bf16 v[118:121], v[166:169], v[182:185], v[118:121]
	v_mfma_f32_16x16x32_bf16 v[114:117], v[174:177], v[182:185], v[114:117]
	v_mfma_f32_16x16x32_bf16 v[102:105], v[166:169], v[190:193], v[102:105]
	v_mfma_f32_16x16x32_bf16 v[98:101], v[174:177], v[190:193], v[98:101]
	v_mfma_f32_16x16x32_bf16 v[86:89], v[166:169], v[198:201], v[86:89]
	v_mfma_f32_16x16x32_bf16 v[82:85], v[174:177], v[198:201], v[82:85]
	v_mfma_f32_16x16x32_bf16 v[70:73], v[166:169], v[212:215], v[70:73]
	v_mfma_f32_16x16x32_bf16 v[66:69], v[174:177], v[212:215], v[66:69]
	s_barrier
	s_add_i32 s0, s33, s34
	s_mov_b32 m0, s0
	ds_read_b128 v[178:181], v153 offset:16384
	ds_read_b128 v[182:185], v153 offset:17408
	ds_read_b128 v[186:189], v153 offset:18432
	ds_read_b128 v[190:193], v153 offset:19456
	ds_read_b128 v[194:197], v153 offset:20480
	ds_read_b128 v[198:201], v153 offset:21504
	ds_read_b128 v[208:211], v153 offset:22528
	ds_read_b128 v[212:215], v153 offset:23552
	global_load_lds_dwordx4 v132, s[26:27]
	s_add_i32 m0, s0, 0x2000
	s_add_u32 s0, s26, 0x80000
	s_addc_u32 s1, s27, 0
	s_add_i32 s33, s55, s34
	global_load_lds_dwordx4 v136, s[26:27]
	s_mov_b32 m0, s33
	s_nop 0
	global_load_lds_dwordx4 v132, s[0:1]
	s_add_i32 m0, s33, 0x2000
	s_nop 0
	global_load_lds_dwordx4 v136, s[0:1]
	s_mov_b32 m0, s9
	s_nop 0
	global_load_lds_dwordx4 v130, s[28:29]
	s_mov_b32 m0, s35
	s_nop 0
	global_load_lds_dwordx4 v134, s[28:29]
	s_waitcnt vmcnt(8)
	s_waitcnt lgkmcnt(0)
	s_barrier
	v_mfma_f32_16x16x32_bf16 v[62:65], v[142:145], v[178:181], v[62:65]
	v_mfma_f32_16x16x32_bf16 v[58:61], v[154:157], v[178:181], v[58:61]
	v_mfma_f32_16x16x32_bf16 v[46:49], v[142:145], v[186:189], v[46:49]
	v_mfma_f32_16x16x32_bf16 v[42:45], v[154:157], v[186:189], v[42:45]
	v_mfma_f32_16x16x32_bf16 v[30:33], v[142:145], v[194:197], v[30:33]
	v_mfma_f32_16x16x32_bf16 v[26:29], v[154:157], v[194:197], v[26:29]
	v_mfma_f32_16x16x32_bf16 v[14:17], v[142:145], v[208:211], v[14:17]
	v_mfma_f32_16x16x32_bf16 v[10:13], v[154:157], v[208:211], v[10:13]
	v_mfma_f32_16x16x32_bf16 v[62:65], v[146:149], v[182:185], v[62:65]
	v_mfma_f32_16x16x32_bf16 v[58:61], v[158:161], v[182:185], v[58:61]
	v_mfma_f32_16x16x32_bf16 v[46:49], v[146:149], v[190:193], v[46:49]
	v_mfma_f32_16x16x32_bf16 v[42:45], v[158:161], v[190:193], v[42:45]
	v_mfma_f32_16x16x32_bf16 v[30:33], v[146:149], v[198:201], v[30:33]
	v_mfma_f32_16x16x32_bf16 v[26:29], v[158:161], v[198:201], v[26:29]
	v_mfma_f32_16x16x32_bf16 v[14:17], v[146:149], v[212:215], v[14:17]
	v_mfma_f32_16x16x32_bf16 v[10:13], v[158:161], v[212:215], v[10:13]
	v_mfma_f32_16x16x32_bf16 v[54:57], v[162:165], v[178:181], v[54:57]
	v_mfma_f32_16x16x32_bf16 v[50:53], v[170:173], v[178:181], v[50:53]
	v_mfma_f32_16x16x32_bf16 v[38:41], v[162:165], v[186:189], v[38:41]
	v_mfma_f32_16x16x32_bf16 v[34:37], v[170:173], v[186:189], v[34:37]
	v_mfma_f32_16x16x32_bf16 v[22:25], v[162:165], v[194:197], v[22:25]
	v_mfma_f32_16x16x32_bf16 v[18:21], v[170:173], v[194:197], v[18:21]
	v_mfma_f32_16x16x32_bf16 v[6:9], v[162:165], v[208:211], v[6:9]
	v_mfma_f32_16x16x32_bf16 v[2:5], v[170:173], v[208:211], v[2:5]
	v_mfma_f32_16x16x32_bf16 v[54:57], v[166:169], v[182:185], v[54:57]
	v_mfma_f32_16x16x32_bf16 v[50:53], v[174:177], v[182:185], v[50:53]
	v_mfma_f32_16x16x32_bf16 v[38:41], v[166:169], v[190:193], v[38:41]
	v_mfma_f32_16x16x32_bf16 v[34:37], v[174:177], v[190:193], v[34:37]
	v_mfma_f32_16x16x32_bf16 v[22:25], v[166:169], v[198:201], v[22:25]
	v_mfma_f32_16x16x32_bf16 v[18:21], v[174:177], v[198:201], v[18:21]
	v_mfma_f32_16x16x32_bf16 v[6:9], v[166:169], v[212:215], v[6:9]
	v_mfma_f32_16x16x32_bf16 v[2:5], v[174:177], v[212:215], v[2:5]
	s_barrier
	s_add_i32 s33, 0, 0x18000
	s_add_i32 s55, 0, 0x1c000
	ds_read_b128 v[142:145], v151 offset:32768
	ds_read_b128 v[146:149], v151 offset:33792
	ds_read_b128 v[154:157], v151 offset:34816
	ds_read_b128 v[158:161], v151 offset:35840
	ds_read_b128 v[162:165], v151 offset:49152
	ds_read_b128 v[166:169], v151 offset:50176
	ds_read_b128 v[170:173], v151 offset:51200
	ds_read_b128 v[174:177], v151 offset:52224
	s_add_u32 s0, s28, 0x80000
	s_addc_u32 s1, s29, 0
	s_mov_b32 m0, s36
	ds_read_b128 v[178:181], v153 offset:32768
	ds_read_b128 v[182:185], v153 offset:33792
	ds_read_b128 v[186:189], v153 offset:34816
	ds_read_b128 v[190:193], v153 offset:35840
	ds_read_b128 v[194:197], v153 offset:36864
	ds_read_b128 v[198:201], v153 offset:37888
	ds_read_b128 v[208:211], v153 offset:38912
	ds_read_b128 v[212:215], v153 offset:39936
	global_load_lds_dwordx4 v130, s[0:1]
	s_mov_b32 m0, s37
	s_nop 0
	global_load_lds_dwordx4 v134, s[0:1]
	s_waitcnt vmcnt(8)
	s_waitcnt lgkmcnt(0)
	s_barrier
	v_mfma_f32_16x16x32_bf16 v[126:129], v[142:145], v[178:181], v[126:129]
	v_mfma_f32_16x16x32_bf16 v[122:125], v[154:157], v[178:181], v[122:125]
	v_mfma_f32_16x16x32_bf16 v[110:113], v[142:145], v[186:189], v[110:113]
	v_mfma_f32_16x16x32_bf16 v[106:109], v[154:157], v[186:189], v[106:109]
	v_mfma_f32_16x16x32_bf16 v[94:97], v[142:145], v[194:197], v[94:97]
	v_mfma_f32_16x16x32_bf16 v[90:93], v[154:157], v[194:197], v[90:93]
	v_mfma_f32_16x16x32_bf16 v[78:81], v[142:145], v[208:211], v[78:81]
	v_mfma_f32_16x16x32_bf16 v[74:77], v[154:157], v[208:211], v[74:77]
	v_mfma_f32_16x16x32_bf16 v[126:129], v[146:149], v[182:185], v[126:129]
	v_mfma_f32_16x16x32_bf16 v[122:125], v[158:161], v[182:185], v[122:125]
	v_mfma_f32_16x16x32_bf16 v[110:113], v[146:149], v[190:193], v[110:113]
	v_mfma_f32_16x16x32_bf16 v[106:109], v[158:161], v[190:193], v[106:109]
	v_mfma_f32_16x16x32_bf16 v[94:97], v[146:149], v[198:201], v[94:97]
	v_mfma_f32_16x16x32_bf16 v[90:93], v[158:161], v[198:201], v[90:93]
	v_mfma_f32_16x16x32_bf16 v[78:81], v[146:149], v[212:215], v[78:81]
	v_mfma_f32_16x16x32_bf16 v[74:77], v[158:161], v[212:215], v[74:77]
	v_mfma_f32_16x16x32_bf16 v[118:121], v[162:165], v[178:181], v[118:121]
	v_mfma_f32_16x16x32_bf16 v[114:117], v[170:173], v[178:181], v[114:117]
	v_mfma_f32_16x16x32_bf16 v[102:105], v[162:165], v[186:189], v[102:105]
	v_mfma_f32_16x16x32_bf16 v[98:101], v[170:173], v[186:189], v[98:101]
	v_mfma_f32_16x16x32_bf16 v[86:89], v[162:165], v[194:197], v[86:89]
	v_mfma_f32_16x16x32_bf16 v[82:85], v[170:173], v[194:197], v[82:85]
	v_mfma_f32_16x16x32_bf16 v[70:73], v[162:165], v[208:211], v[70:73]
	v_mfma_f32_16x16x32_bf16 v[66:69], v[170:173], v[208:211], v[66:69]
	v_mfma_f32_16x16x32_bf16 v[118:121], v[166:169], v[182:185], v[118:121]
	v_mfma_f32_16x16x32_bf16 v[114:117], v[174:177], v[182:185], v[114:117]
	v_mfma_f32_16x16x32_bf16 v[102:105], v[166:169], v[190:193], v[102:105]
	v_mfma_f32_16x16x32_bf16 v[98:101], v[174:177], v[190:193], v[98:101]
	v_mfma_f32_16x16x32_bf16 v[86:89], v[166:169], v[198:201], v[86:89]
	v_mfma_f32_16x16x32_bf16 v[82:85], v[174:177], v[198:201], v[82:85]
	v_mfma_f32_16x16x32_bf16 v[70:73], v[166:169], v[212:215], v[70:73]
	v_mfma_f32_16x16x32_bf16 v[66:69], v[174:177], v[212:215], v[66:69]
	s_barrier
	s_add_i32 s0, s33, s34
	s_add_u32 s100, s26, 0x80
	s_addc_u32 s101, s27, 0
	s_mov_b32 m0, s0
	ds_read_b128 v[178:181], v153 offset:49152
	ds_read_b128 v[182:185], v153 offset:50176
	ds_read_b128 v[186:189], v153 offset:51200
	ds_read_b128 v[190:193], v153 offset:52224
	ds_read_b128 v[194:197], v153 offset:53248
	ds_read_b128 v[198:201], v153 offset:54272
	ds_read_b128 v[208:211], v153 offset:55296
	ds_read_b128 v[212:215], v153 offset:56320
	global_load_lds_dwordx4 v132, s[100:101]
	s_add_i32 m0, s0, 0x2000
	s_add_u32 s100, s26, 0x80
	s_addc_u32 s101, s27, 0
	s_add_u32 s0, s26, 0x80080
	s_addc_u32 s1, s27, 0
	s_add_i32 s26, s55, s34
	global_load_lds_dwordx4 v136, s[100:101]
	s_mov_b32 m0, s26
	s_nop 0
	global_load_lds_dwordx4 v132, s[0:1]
	s_add_i32 m0, s26, 0x2000
	s_nop 0
	global_load_lds_dwordx4 v136, s[0:1]
	s_add_u32 s100, s28, 0x80
	s_addc_u32 s101, s29, 0
	s_mov_b32 m0, s39
	s_nop 0
	global_load_lds_dwordx4 v130, s[100:101]
	s_add_u32 s100, s28, 0x80
	s_addc_u32 s101, s29, 0
	s_mov_b32 m0, s40
	s_nop 0
	global_load_lds_dwordx4 v134, s[100:101]
	s_waitcnt vmcnt(8)
	s_waitcnt lgkmcnt(0)
	s_barrier
	v_mfma_f32_16x16x32_bf16 v[62:65], v[142:145], v[178:181], v[62:65]
	v_mfma_f32_16x16x32_bf16 v[58:61], v[154:157], v[178:181], v[58:61]
	v_mfma_f32_16x16x32_bf16 v[46:49], v[142:145], v[186:189], v[46:49]
	v_mfma_f32_16x16x32_bf16 v[42:45], v[154:157], v[186:189], v[42:45]
	v_mfma_f32_16x16x32_bf16 v[30:33], v[142:145], v[194:197], v[30:33]
	v_mfma_f32_16x16x32_bf16 v[26:29], v[154:157], v[194:197], v[26:29]
	v_mfma_f32_16x16x32_bf16 v[14:17], v[142:145], v[208:211], v[14:17]
	v_mfma_f32_16x16x32_bf16 v[10:13], v[154:157], v[208:211], v[10:13]
	v_mfma_f32_16x16x32_bf16 v[62:65], v[146:149], v[182:185], v[62:65]
	v_mfma_f32_16x16x32_bf16 v[58:61], v[158:161], v[182:185], v[58:61]
	v_mfma_f32_16x16x32_bf16 v[46:49], v[146:149], v[190:193], v[46:49]
	v_mfma_f32_16x16x32_bf16 v[42:45], v[158:161], v[190:193], v[42:45]
	v_mfma_f32_16x16x32_bf16 v[30:33], v[146:149], v[198:201], v[30:33]
	v_mfma_f32_16x16x32_bf16 v[26:29], v[158:161], v[198:201], v[26:29]
	v_mfma_f32_16x16x32_bf16 v[14:17], v[146:149], v[212:215], v[14:17]
	v_mfma_f32_16x16x32_bf16 v[10:13], v[158:161], v[212:215], v[10:13]
	v_mfma_f32_16x16x32_bf16 v[54:57], v[162:165], v[178:181], v[54:57]
	v_mfma_f32_16x16x32_bf16 v[50:53], v[170:173], v[178:181], v[50:53]
	v_mfma_f32_16x16x32_bf16 v[38:41], v[162:165], v[186:189], v[38:41]
	v_mfma_f32_16x16x32_bf16 v[34:37], v[170:173], v[186:189], v[34:37]
	v_mfma_f32_16x16x32_bf16 v[22:25], v[162:165], v[194:197], v[22:25]
	v_mfma_f32_16x16x32_bf16 v[18:21], v[170:173], v[194:197], v[18:21]
	v_mfma_f32_16x16x32_bf16 v[6:9], v[162:165], v[208:211], v[6:9]
	v_mfma_f32_16x16x32_bf16 v[2:5], v[170:173], v[208:211], v[2:5]
	v_mfma_f32_16x16x32_bf16 v[54:57], v[166:169], v[182:185], v[54:57]
	v_mfma_f32_16x16x32_bf16 v[50:53], v[174:177], v[182:185], v[50:53]
	v_mfma_f32_16x16x32_bf16 v[38:41], v[166:169], v[190:193], v[38:41]
	v_mfma_f32_16x16x32_bf16 v[34:37], v[174:177], v[190:193], v[34:37]
	v_mfma_f32_16x16x32_bf16 v[22:25], v[166:169], v[198:201], v[22:25]
	v_mfma_f32_16x16x32_bf16 v[18:21], v[174:177], v[198:201], v[18:21]
	v_mfma_f32_16x16x32_bf16 v[6:9], v[166:169], v[212:215], v[6:9]
	v_mfma_f32_16x16x32_bf16 v[2:5], v[174:177], v[212:215], v[2:5]
	s_barrier
	s_add_i32 s60, s60, 2
	s_add_u32 s24, s24, 0x100
	s_addc_u32 s25, s25, 0
	s_add_u32 s58, s58, 0x100
	s_addc_u32 s59, s59, 0
	s_cmp_gt_u32 s60, 29
	s_cbranch_scc0 .LBB0_394
	s_and_b64 vcc, exec, s[14:15]
	s_cbranch_vccz .LBB0_397
	s_barrier

.LBB0_692:
	s_add_u32 s0, s18, 0xfff00080
	s_addc_u32 s1, s19, -1
	s_add_i32 s33, 0, 0x10000
	s_cmp_eq_u32 s61, 60
	s_cselect_b32 s23, s11, s1
	s_cselect_b32 s22, s49, s0
	s_cselect_b32 s21, s9, s60
	s_cselect_b32 s20, s58, s59
	s_add_i32 s55, 0, 0x14000
	ds_read_b128 v[78:81], v205
	ds_read_b128 v[86:89], v205 offset:1024
	ds_read_b128 v[94:97], v205 offset:2048
	ds_read_b128 v[98:101], v205 offset:3072
	ds_read_b128 v[106:109], v205 offset:16384
	ds_read_b128 v[110:113], v205 offset:17408
	ds_read_b128 v[126:129], v205 offset:18432
	ds_read_b128 v[134:137], v205 offset:19456
	s_add_i32 m0, s27, 0xc000
	ds_read_b128 v[146:149], v239
	ds_read_b128 v[158:161], v239 offset:1024
	ds_read_b128 v[166:169], v239 offset:2048
	ds_read_b128 v[174:177], v239 offset:3072
	ds_read_b128 v[178:181], v239 offset:4096
	ds_read_b128 v[182:185], v239 offset:5120
	ds_read_b128 v[186:189], v239 offset:6144
	ds_read_b128 v[190:193], v239 offset:7168
	global_load_lds_dwordx4 v214, s[18:19]
	s_add_i32 m0, s27, 0xe000
	s_nop 0
	global_load_lds_dwordx4 v216, s[18:19]
	s_waitcnt vmcnt(8)
	s_waitcnt lgkmcnt(0)
	s_barrier
	v_mfma_f32_16x16x32_bf16 v[170:173], v[78:81], v[146:149], v[170:173]
	v_mfma_f32_16x16x32_bf16 v[162:165], v[94:97], v[146:149], v[162:165]
	v_mfma_f32_16x16x32_bf16 v[142:145], v[78:81], v[166:169], v[142:145]
	v_mfma_f32_16x16x32_bf16 v[138:141], v[94:97], v[166:169], v[138:141]
	v_mfma_f32_16x16x32_bf16 v[118:121], v[78:81], v[178:181], v[118:121]
	v_mfma_f32_16x16x32_bf16 v[114:117], v[94:97], v[178:181], v[114:117]
	v_mfma_f32_16x16x32_bf16 v[82:85], v[78:81], v[186:189], v[82:85]
	v_mfma_f32_16x16x32_bf16 v[74:77], v[94:97], v[186:189], v[74:77]
	v_mfma_f32_16x16x32_bf16 v[170:173], v[86:89], v[158:161], v[170:173]
	v_mfma_f32_16x16x32_bf16 v[162:165], v[98:101], v[158:161], v[162:165]
	v_mfma_f32_16x16x32_bf16 v[142:145], v[86:89], v[174:177], v[142:145]
	v_mfma_f32_16x16x32_bf16 v[138:141], v[98:101], v[174:177], v[138:141]
	v_mfma_f32_16x16x32_bf16 v[118:121], v[86:89], v[182:185], v[118:121]
	v_mfma_f32_16x16x32_bf16 v[114:117], v[98:101], v[182:185], v[114:117]
	v_mfma_f32_16x16x32_bf16 v[82:85], v[86:89], v[190:193], v[82:85]
	v_mfma_f32_16x16x32_bf16 v[74:77], v[98:101], v[190:193], v[74:77]
	v_mfma_f32_16x16x32_bf16 v[154:157], v[106:109], v[146:149], v[154:157]
	v_mfma_f32_16x16x32_bf16 v[130:133], v[106:109], v[166:169], v[130:133]
	v_mfma_f32_16x16x32_bf16 v[122:125], v[126:129], v[166:169], v[122:125]
	v_mfma_f32_16x16x32_bf16 v[102:105], v[106:109], v[178:181], v[102:105]
	v_mfma_f32_16x16x32_bf16 v[90:93], v[126:129], v[178:181], v[90:93]
	v_mfma_f32_16x16x32_bf16 v[70:73], v[106:109], v[186:189], v[70:73]
	v_mfma_f32_16x16x32_bf16 v[66:69], v[126:129], v[186:189], v[66:69]
	v_mfma_f32_16x16x32_bf16 v[154:157], v[110:113], v[158:161], v[154:157]
	v_mfma_f32_16x16x32_bf16 v[146:149], v[126:129], v[146:149], v[150:153]
	v_mfma_f32_16x16x32_bf16 v[130:133], v[110:113], v[174:177], v[130:133]
	v_mfma_f32_16x16x32_bf16 v[122:125], v[134:137], v[174:177], v[122:125]
	v_mfma_f32_16x16x32_bf16 v[102:105], v[110:113], v[182:185], v[102:105]
	v_mfma_f32_16x16x32_bf16 v[90:93], v[134:137], v[182:185], v[90:93]
	v_mfma_f32_16x16x32_bf16 v[70:73], v[110:113], v[190:193], v[70:73]
	v_mfma_f32_16x16x32_bf16 v[66:69], v[134:137], v[190:193], v[66:69]
	v_mfma_f32_16x16x32_bf16 v[146:149], v[134:137], v[158:161], v[146:149]
	s_barrier
	s_add_i32 s0, s33, s26
	s_mov_b32 m0, s0
	ds_read_b128 v[150:153], v239 offset:16384
	ds_read_b128 v[158:161], v239 offset:17408
	ds_read_b128 v[166:169], v239 offset:18432
	ds_read_b128 v[174:177], v239 offset:19456
	ds_read_b128 v[178:181], v239 offset:20480
	ds_read_b128 v[182:185], v239 offset:21504
	ds_read_b128 v[186:189], v239 offset:22528
	ds_read_b128 v[190:193], v239 offset:23552
	global_load_lds_dwordx4 v202, s[20:21]
	s_add_i32 m0, s0, 0x2000
	s_add_u32 s0, s20, 0x100000
	s_addc_u32 s1, s21, 0
	s_add_i32 s33, s55, s26
	global_load_lds_dwordx4 v208, s[20:21]
	s_mov_b32 m0, s33
	s_nop 0
	global_load_lds_dwordx4 v202, s[0:1]
	s_add_i32 m0, s33, 0x2000
	s_nop 0
	global_load_lds_dwordx4 v208, s[0:1]
	s_mov_b32 m0, s27
	s_nop 0
	global_load_lds_dwordx4 v212, s[22:23]
	s_mov_b32 m0, s28
	s_nop 0
	global_load_lds_dwordx4 v210, s[22:23]
	s_waitcnt vmcnt(8)
	s_waitcnt lgkmcnt(0)
	s_barrier
	v_mfma_f32_16x16x32_bf16 v[62:65], v[78:81], v[150:153], v[62:65]
	v_mfma_f32_16x16x32_bf16 v[58:61], v[94:97], v[150:153], v[58:61]
	v_mfma_f32_16x16x32_bf16 v[46:49], v[78:81], v[166:169], v[46:49]
	v_mfma_f32_16x16x32_bf16 v[42:45], v[94:97], v[166:169], v[42:45]
	v_mfma_f32_16x16x32_bf16 v[30:33], v[78:81], v[178:181], v[30:33]
	v_mfma_f32_16x16x32_bf16 v[26:29], v[94:97], v[178:181], v[26:29]
	v_mfma_f32_16x16x32_bf16 v[14:17], v[78:81], v[186:189], v[14:17]
	v_mfma_f32_16x16x32_bf16 v[10:13], v[94:97], v[186:189], v[10:13]
	v_mfma_f32_16x16x32_bf16 v[62:65], v[86:89], v[158:161], v[62:65]
	v_mfma_f32_16x16x32_bf16 v[58:61], v[98:101], v[158:161], v[58:61]
	v_mfma_f32_16x16x32_bf16 v[46:49], v[86:89], v[174:177], v[46:49]
	v_mfma_f32_16x16x32_bf16 v[42:45], v[98:101], v[174:177], v[42:45]
	v_mfma_f32_16x16x32_bf16 v[30:33], v[86:89], v[182:185], v[30:33]
	v_mfma_f32_16x16x32_bf16 v[26:29], v[98:101], v[182:185], v[26:29]
	v_mfma_f32_16x16x32_bf16 v[14:17], v[86:89], v[190:193], v[14:17]
	v_mfma_f32_16x16x32_bf16 v[10:13], v[98:101], v[190:193], v[10:13]
	v_mfma_f32_16x16x32_bf16 v[54:57], v[106:109], v[150:153], v[54:57]
	v_mfma_f32_16x16x32_bf16 v[50:53], v[126:129], v[150:153], v[50:53]
	v_mfma_f32_16x16x32_bf16 v[38:41], v[106:109], v[166:169], v[38:41]
	v_mfma_f32_16x16x32_bf16 v[34:37], v[126:129], v[166:169], v[34:37]
	v_mfma_f32_16x16x32_bf16 v[22:25], v[106:109], v[178:181], v[22:25]
	v_mfma_f32_16x16x32_bf16 v[18:21], v[126:129], v[178:181], v[18:21]
	v_mfma_f32_16x16x32_bf16 v[6:9], v[106:109], v[186:189], v[6:9]
	v_mfma_f32_16x16x32_bf16 v[2:5], v[126:129], v[186:189], v[2:5]
	v_mfma_f32_16x16x32_bf16 v[54:57], v[110:113], v[158:161], v[54:57]
	v_mfma_f32_16x16x32_bf16 v[50:53], v[134:137], v[158:161], v[50:53]
	v_mfma_f32_16x16x32_bf16 v[38:41], v[110:113], v[174:177], v[38:41]
	v_mfma_f32_16x16x32_bf16 v[34:37], v[134:137], v[174:177], v[34:37]
	v_mfma_f32_16x16x32_bf16 v[22:25], v[110:113], v[182:185], v[22:25]
	v_mfma_f32_16x16x32_bf16 v[18:21], v[134:137], v[182:185], v[18:21]
	v_mfma_f32_16x16x32_bf16 v[6:9], v[110:113], v[190:193], v[6:9]
	v_mfma_f32_16x16x32_bf16 v[2:5], v[134:137], v[190:193], v[2:5]
	s_barrier
	s_add_i32 s33, 0, 0x18000
	s_add_i32 s55, 0, 0x1c000
	ds_read_b128 v[78:81], v205 offset:32768
	ds_read_b128 v[86:89], v205 offset:33792
	ds_read_b128 v[94:97], v205 offset:34816
	ds_read_b128 v[98:101], v205 offset:35840
	ds_read_b128 v[106:109], v205 offset:49152
	ds_read_b128 v[110:113], v205 offset:50176
	ds_read_b128 v[126:129], v205 offset:51200
	ds_read_b128 v[134:137], v205 offset:52224
	s_add_u32 s0, s22, 0x100000
	s_addc_u32 s1, s23, 0
	s_mov_b32 m0, s29
	ds_read_b128 v[150:153], v239 offset:32768
	ds_read_b128 v[158:161], v239 offset:33792
	ds_read_b128 v[166:169], v239 offset:34816
	ds_read_b128 v[174:177], v239 offset:35840
	ds_read_b128 v[178:181], v239 offset:36864
	ds_read_b128 v[182:185], v239 offset:37888
	ds_read_b128 v[186:189], v239 offset:38912
	ds_read_b128 v[190:193], v239 offset:39936
	global_load_lds_dwordx4 v212, s[0:1]
	s_mov_b32 m0, s30
	s_nop 0
	global_load_lds_dwordx4 v210, s[0:1]
	s_waitcnt vmcnt(8)
	s_waitcnt lgkmcnt(0)
	s_barrier
	v_mfma_f32_16x16x32_bf16 v[170:173], v[78:81], v[150:153], v[170:173]
	v_mfma_f32_16x16x32_bf16 v[162:165], v[94:97], v[150:153], v[162:165]
	v_mfma_f32_16x16x32_bf16 v[142:145], v[78:81], v[166:169], v[142:145]
	v_mfma_f32_16x16x32_bf16 v[138:141], v[94:97], v[166:169], v[138:141]
	v_mfma_f32_16x16x32_bf16 v[118:121], v[78:81], v[178:181], v[118:121]
	v_mfma_f32_16x16x32_bf16 v[114:117], v[94:97], v[178:181], v[114:117]
	v_mfma_f32_16x16x32_bf16 v[82:85], v[78:81], v[186:189], v[82:85]
	v_mfma_f32_16x16x32_bf16 v[74:77], v[94:97], v[186:189], v[74:77]
	v_mfma_f32_16x16x32_bf16 v[170:173], v[86:89], v[158:161], v[170:173]
	v_mfma_f32_16x16x32_bf16 v[162:165], v[98:101], v[158:161], v[162:165]
	v_mfma_f32_16x16x32_bf16 v[142:145], v[86:89], v[174:177], v[142:145]
	v_mfma_f32_16x16x32_bf16 v[138:141], v[98:101], v[174:177], v[138:141]
	v_mfma_f32_16x16x32_bf16 v[118:121], v[86:89], v[182:185], v[118:121]
	v_mfma_f32_16x16x32_bf16 v[114:117], v[98:101], v[182:185], v[114:117]
	v_mfma_f32_16x16x32_bf16 v[82:85], v[86:89], v[190:193], v[82:85]
	v_mfma_f32_16x16x32_bf16 v[74:77], v[98:101], v[190:193], v[74:77]
	v_mfma_f32_16x16x32_bf16 v[154:157], v[106:109], v[150:153], v[154:157]
	v_mfma_f32_16x16x32_bf16 v[146:149], v[126:129], v[150:153], v[146:149]
	v_mfma_f32_16x16x32_bf16 v[130:133], v[106:109], v[166:169], v[130:133]
	v_mfma_f32_16x16x32_bf16 v[122:125], v[126:129], v[166:169], v[122:125]
	v_mfma_f32_16x16x32_bf16 v[102:105], v[106:109], v[178:181], v[102:105]
	v_mfma_f32_16x16x32_bf16 v[90:93], v[126:129], v[178:181], v[90:93]
	v_mfma_f32_16x16x32_bf16 v[70:73], v[106:109], v[186:189], v[70:73]
	v_mfma_f32_16x16x32_bf16 v[66:69], v[126:129], v[186:189], v[66:69]
	v_mfma_f32_16x16x32_bf16 v[154:157], v[110:113], v[158:161], v[154:157]
	v_mfma_f32_16x16x32_bf16 v[150:153], v[134:137], v[158:161], v[146:149]
	v_mfma_f32_16x16x32_bf16 v[130:133], v[110:113], v[174:177], v[130:133]
	v_mfma_f32_16x16x32_bf16 v[122:125], v[134:137], v[174:177], v[122:125]
	v_mfma_f32_16x16x32_bf16 v[102:105], v[110:113], v[182:185], v[102:105]
	v_mfma_f32_16x16x32_bf16 v[90:93], v[134:137], v[182:185], v[90:93]
	v_mfma_f32_16x16x32_bf16 v[70:73], v[110:113], v[190:193], v[70:73]
	v_mfma_f32_16x16x32_bf16 v[66:69], v[134:137], v[190:193], v[66:69]
	s_barrier
	s_add_i32 s0, s33, s26
	s_add_u32 s100, s20, 0x80
	s_addc_u32 s101, s21, 0
	s_mov_b32 m0, s0
	ds_read_b128 v[146:149], v239 offset:49152
	ds_read_b128 v[158:161], v239 offset:50176
	ds_read_b128 v[166:169], v239 offset:51200
	ds_read_b128 v[174:177], v239 offset:52224
	ds_read_b128 v[178:181], v239 offset:53248
	ds_read_b128 v[182:185], v239 offset:54272
	ds_read_b128 v[186:189], v239 offset:55296
	ds_read_b128 v[190:193], v239 offset:56320
	global_load_lds_dwordx4 v202, s[100:101]
	s_add_i32 m0, s0, 0x2000
	s_add_u32 s100, s20, 0x80
	s_addc_u32 s101, s21, 0
	s_add_u32 s0, s20, 0x100080
	s_addc_u32 s1, s21, 0
	s_add_i32 s20, s55, s26
	global_load_lds_dwordx4 v208, s[100:101]
	s_mov_b32 m0, s20
	s_nop 0
	global_load_lds_dwordx4 v202, s[0:1]
	s_add_i32 m0, s20, 0x2000
	s_nop 0
	global_load_lds_dwordx4 v208, s[0:1]
	s_add_u32 s100, s22, 0x80
	s_addc_u32 s101, s23, 0
	s_mov_b32 m0, s35
	s_nop 0
	global_load_lds_dwordx4 v212, s[100:101]
	s_add_u32 s100, s22, 0x80
	s_addc_u32 s101, s23, 0
	s_mov_b32 m0, s36
	s_nop 0
	global_load_lds_dwordx4 v210, s[100:101]
	s_waitcnt vmcnt(8)
	s_waitcnt lgkmcnt(0)
	s_barrier
	v_mfma_f32_16x16x32_bf16 v[62:65], v[78:81], v[146:149], v[62:65]
	v_mfma_f32_16x16x32_bf16 v[58:61], v[94:97], v[146:149], v[58:61]
	v_mfma_f32_16x16x32_bf16 v[46:49], v[78:81], v[166:169], v[46:49]
	v_mfma_f32_16x16x32_bf16 v[42:45], v[94:97], v[166:169], v[42:45]
	v_mfma_f32_16x16x32_bf16 v[30:33], v[78:81], v[178:181], v[30:33]
	v_mfma_f32_16x16x32_bf16 v[26:29], v[94:97], v[178:181], v[26:29]
	v_mfma_f32_16x16x32_bf16 v[14:17], v[78:81], v[186:189], v[14:17]
	v_mfma_f32_16x16x32_bf16 v[10:13], v[94:97], v[186:189], v[10:13]
	v_mfma_f32_16x16x32_bf16 v[62:65], v[86:89], v[158:161], v[62:65]
	v_mfma_f32_16x16x32_bf16 v[58:61], v[98:101], v[158:161], v[58:61]
	v_mfma_f32_16x16x32_bf16 v[46:49], v[86:89], v[174:177], v[46:49]
	v_mfma_f32_16x16x32_bf16 v[42:45], v[98:101], v[174:177], v[42:45]
	v_mfma_f32_16x16x32_bf16 v[30:33], v[86:89], v[182:185], v[30:33]
	v_mfma_f32_16x16x32_bf16 v[26:29], v[98:101], v[182:185], v[26:29]
	v_mfma_f32_16x16x32_bf16 v[14:17], v[86:89], v[190:193], v[14:17]
	v_mfma_f32_16x16x32_bf16 v[10:13], v[98:101], v[190:193], v[10:13]
	v_mfma_f32_16x16x32_bf16 v[54:57], v[106:109], v[146:149], v[54:57]
	v_mfma_f32_16x16x32_bf16 v[50:53], v[126:129], v[146:149], v[50:53]
	v_mfma_f32_16x16x32_bf16 v[38:41], v[106:109], v[166:169], v[38:41]
	v_mfma_f32_16x16x32_bf16 v[34:37], v[126:129], v[166:169], v[34:37]
	v_mfma_f32_16x16x32_bf16 v[22:25], v[106:109], v[178:181], v[22:25]
	v_mfma_f32_16x16x32_bf16 v[18:21], v[126:129], v[178:181], v[18:21]
	v_mfma_f32_16x16x32_bf16 v[6:9], v[106:109], v[186:189], v[6:9]
	v_mfma_f32_16x16x32_bf16 v[2:5], v[126:129], v[186:189], v[2:5]
	v_mfma_f32_16x16x32_bf16 v[54:57], v[110:113], v[158:161], v[54:57]
	v_mfma_f32_16x16x32_bf16 v[50:53], v[134:137], v[158:161], v[50:53]
	v_mfma_f32_16x16x32_bf16 v[38:41], v[110:113], v[174:177], v[38:41]
	v_mfma_f32_16x16x32_bf16 v[34:37], v[134:137], v[174:177], v[34:37]
	v_mfma_f32_16x16x32_bf16 v[22:25], v[110:113], v[182:185], v[22:25]
	v_mfma_f32_16x16x32_bf16 v[18:21], v[134:137], v[182:185], v[18:21]
	v_mfma_f32_16x16x32_bf16 v[6:9], v[110:113], v[190:193], v[6:9]
	v_mfma_f32_16x16x32_bf16 v[2:5], v[134:137], v[190:193], v[2:5]
	s_barrier
	s_add_i32 s61, s61, 2
	s_add_u32 s18, s18, 0x100
	s_addc_u32 s19, s19, 0
	s_add_u32 s59, s59, 0x100
	s_addc_u32 s60, s60, 0
	s_cmp_gt_u32 s61, 61
	s_cbranch_scc0 .LBB0_692
	s_and_b64 vcc, exec, s[6:7]
	s_cbranch_vccz .LBB0_695
	s_barrier

.LBB0_712:
	s_add_u32 s0, s18, 0xfff00080
	s_addc_u32 s1, s19, -1
	s_add_i32 s33, 0, 0x10000
	s_cmp_eq_u32 s49, 4
	s_cselect_b32 s23, s15, s1
	s_cselect_b32 s22, s14, s0
	s_cselect_b32 s21, s17, s11
	s_cselect_b32 s20, s16, s9
	s_add_i32 s55, 0, 0x14000
	ds_read_b128 v[140:143], v136
	ds_read_b128 v[144:147], v136 offset:1024
	ds_read_b128 v[148:151], v136 offset:2048
	ds_read_b128 v[152:155], v136 offset:3072
	ds_read_b128 v[156:159], v136 offset:16384
	ds_read_b128 v[160:163], v136 offset:17408
	ds_read_b128 v[164:167], v136 offset:18432
	ds_read_b128 v[168:171], v136 offset:19456
	s_add_i32 m0, s27, 0xc000
	ds_read_b128 v[172:175], v139
	ds_read_b128 v[176:179], v139 offset:1024
	ds_read_b128 v[180:183], v139 offset:2048
	ds_read_b128 v[184:187], v139 offset:3072
	ds_read_b128 v[188:191], v139 offset:4096
	ds_read_b128 v[192:195], v139 offset:5120
	ds_read_b128 v[196:199], v139 offset:6144
	ds_read_b128 v[208:211], v139 offset:7168
	global_load_lds_dwordx4 v132, s[18:19]
	s_add_i32 m0, s27, 0xe000
	s_nop 0
	global_load_lds_dwordx4 v134, s[18:19]
	s_waitcnt vmcnt(8)
	s_waitcnt lgkmcnt(0)
	s_barrier
	v_mfma_f32_16x16x32_bf16 v[126:129], v[140:143], v[172:175], v[126:129]
	v_mfma_f32_16x16x32_bf16 v[122:125], v[148:151], v[172:175], v[122:125]
	v_mfma_f32_16x16x32_bf16 v[118:121], v[140:143], v[180:183], v[118:121]
	v_mfma_f32_16x16x32_bf16 v[114:117], v[148:151], v[180:183], v[114:117]
	v_mfma_f32_16x16x32_bf16 v[106:109], v[140:143], v[188:191], v[106:109]
	v_mfma_f32_16x16x32_bf16 v[98:101], v[148:151], v[188:191], v[98:101]
	v_mfma_f32_16x16x32_bf16 v[90:93], v[140:143], v[196:199], v[90:93]
	v_mfma_f32_16x16x32_bf16 v[82:85], v[148:151], v[196:199], v[82:85]
	v_mfma_f32_16x16x32_bf16 v[126:129], v[144:147], v[176:179], v[126:129]
	v_mfma_f32_16x16x32_bf16 v[122:125], v[152:155], v[176:179], v[122:125]
	v_mfma_f32_16x16x32_bf16 v[118:121], v[144:147], v[184:187], v[118:121]
	v_mfma_f32_16x16x32_bf16 v[114:117], v[152:155], v[184:187], v[114:117]
	v_mfma_f32_16x16x32_bf16 v[106:109], v[144:147], v[192:195], v[106:109]
	v_mfma_f32_16x16x32_bf16 v[98:101], v[152:155], v[192:195], v[98:101]
	v_mfma_f32_16x16x32_bf16 v[90:93], v[144:147], v[208:211], v[90:93]
	v_mfma_f32_16x16x32_bf16 v[82:85], v[152:155], v[208:211], v[82:85]
	v_mfma_f32_16x16x32_bf16 v[110:113], v[156:159], v[172:175], v[110:113]
	v_mfma_f32_16x16x32_bf16 v[102:105], v[164:167], v[172:175], v[102:105]
	v_mfma_f32_16x16x32_bf16 v[94:97], v[156:159], v[180:183], v[94:97]
	v_mfma_f32_16x16x32_bf16 v[86:89], v[164:167], v[180:183], v[86:89]
	v_mfma_f32_16x16x32_bf16 v[78:81], v[156:159], v[188:191], v[78:81]
	v_mfma_f32_16x16x32_bf16 v[74:77], v[164:167], v[188:191], v[74:77]
	v_mfma_f32_16x16x32_bf16 v[70:73], v[156:159], v[196:199], v[70:73]
	v_mfma_f32_16x16x32_bf16 v[66:69], v[164:167], v[196:199], v[66:69]
	v_mfma_f32_16x16x32_bf16 v[110:113], v[160:163], v[176:179], v[110:113]
	v_mfma_f32_16x16x32_bf16 v[102:105], v[168:171], v[176:179], v[102:105]
	v_mfma_f32_16x16x32_bf16 v[94:97], v[160:163], v[184:187], v[94:97]
	v_mfma_f32_16x16x32_bf16 v[86:89], v[168:171], v[184:187], v[86:89]
	v_mfma_f32_16x16x32_bf16 v[78:81], v[160:163], v[192:195], v[78:81]
	v_mfma_f32_16x16x32_bf16 v[74:77], v[168:171], v[192:195], v[74:77]
	v_mfma_f32_16x16x32_bf16 v[70:73], v[160:163], v[208:211], v[70:73]
	v_mfma_f32_16x16x32_bf16 v[66:69], v[168:171], v[208:211], v[66:69]
	s_barrier
	s_add_i32 s0, s33, s26
	s_mov_b32 m0, s0
	ds_read_b128 v[172:175], v139 offset:16384
	ds_read_b128 v[176:179], v139 offset:17408
	ds_read_b128 v[180:183], v139 offset:18432
	ds_read_b128 v[184:187], v139 offset:19456
	ds_read_b128 v[188:191], v139 offset:20480
	ds_read_b128 v[192:195], v139 offset:21504
	ds_read_b128 v[196:199], v139 offset:22528
	ds_read_b128 v[208:211], v139 offset:23552
	global_load_lds_dwordx4 v202, s[20:21]
	s_add_i32 m0, s0, 0x2000
	s_add_u32 s0, s20, 0x100000
	s_addc_u32 s1, s21, 0
	s_add_i32 s33, s55, s26
	global_load_lds_dwordx4 v130, s[20:21]
	s_mov_b32 m0, s33
	s_nop 0
	global_load_lds_dwordx4 v202, s[0:1]
	s_add_i32 m0, s33, 0x2000
	s_nop 0
	global_load_lds_dwordx4 v130, s[0:1]
	s_mov_b32 m0, s27
	s_nop 0
	global_load_lds_dwordx4 v202, s[22:23]
	s_mov_b32 m0, s28
	s_nop 0
	global_load_lds_dwordx4 v130, s[22:23]
	s_waitcnt vmcnt(8)
	s_waitcnt lgkmcnt(0)
	s_barrier
	v_mfma_f32_16x16x32_bf16 v[62:65], v[140:143], v[172:175], v[62:65]
	v_mfma_f32_16x16x32_bf16 v[58:61], v[148:151], v[172:175], v[58:61]
	v_mfma_f32_16x16x32_bf16 v[54:57], v[140:143], v[180:183], v[54:57]
	v_mfma_f32_16x16x32_bf16 v[50:53], v[148:151], v[180:183], v[50:53]
	v_mfma_f32_16x16x32_bf16 v[38:41], v[140:143], v[188:191], v[38:41]
	v_mfma_f32_16x16x32_bf16 v[34:37], v[148:151], v[188:191], v[34:37]
	v_mfma_f32_16x16x32_bf16 v[22:25], v[140:143], v[196:199], v[22:25]
	v_mfma_f32_16x16x32_bf16 v[18:21], v[148:151], v[196:199], v[18:21]
	v_mfma_f32_16x16x32_bf16 v[62:65], v[144:147], v[176:179], v[62:65]
	v_mfma_f32_16x16x32_bf16 v[58:61], v[152:155], v[176:179], v[58:61]
	v_mfma_f32_16x16x32_bf16 v[54:57], v[144:147], v[184:187], v[54:57]
	v_mfma_f32_16x16x32_bf16 v[50:53], v[152:155], v[184:187], v[50:53]
	v_mfma_f32_16x16x32_bf16 v[38:41], v[144:147], v[192:195], v[38:41]
	v_mfma_f32_16x16x32_bf16 v[34:37], v[152:155], v[192:195], v[34:37]
	v_mfma_f32_16x16x32_bf16 v[22:25], v[144:147], v[208:211], v[22:25]
	v_mfma_f32_16x16x32_bf16 v[18:21], v[152:155], v[208:211], v[18:21]
	v_mfma_f32_16x16x32_bf16 v[46:49], v[156:159], v[172:175], v[46:49]
	v_mfma_f32_16x16x32_bf16 v[42:45], v[164:167], v[172:175], v[42:45]
	v_mfma_f32_16x16x32_bf16 v[30:33], v[156:159], v[180:183], v[30:33]
	v_mfma_f32_16x16x32_bf16 v[26:29], v[164:167], v[180:183], v[26:29]
	v_mfma_f32_16x16x32_bf16 v[14:17], v[156:159], v[188:191], v[14:17]
	v_mfma_f32_16x16x32_bf16 v[10:13], v[164:167], v[188:191], v[10:13]
	v_mfma_f32_16x16x32_bf16 v[6:9], v[156:159], v[196:199], v[6:9]
	v_mfma_f32_16x16x32_bf16 v[2:5], v[164:167], v[196:199], v[2:5]
	v_mfma_f32_16x16x32_bf16 v[46:49], v[160:163], v[176:179], v[46:49]
	v_mfma_f32_16x16x32_bf16 v[42:45], v[168:171], v[176:179], v[42:45]
	v_mfma_f32_16x16x32_bf16 v[30:33], v[160:163], v[184:187], v[30:33]
	v_mfma_f32_16x16x32_bf16 v[26:29], v[168:171], v[184:187], v[26:29]
	v_mfma_f32_16x16x32_bf16 v[14:17], v[160:163], v[192:195], v[14:17]
	v_mfma_f32_16x16x32_bf16 v[10:13], v[168:171], v[192:195], v[10:13]
	v_mfma_f32_16x16x32_bf16 v[6:9], v[160:163], v[208:211], v[6:9]
	v_mfma_f32_16x16x32_bf16 v[2:5], v[168:171], v[208:211], v[2:5]
	s_barrier
	s_add_i32 s33, 0, 0x18000
	s_add_i32 s55, 0, 0x1c000
	ds_read_b128 v[140:143], v136 offset:32768
	ds_read_b128 v[144:147], v136 offset:33792
	ds_read_b128 v[148:151], v136 offset:34816
	ds_read_b128 v[152:155], v136 offset:35840
	ds_read_b128 v[156:159], v136 offset:49152
	ds_read_b128 v[160:163], v136 offset:50176
	ds_read_b128 v[164:167], v136 offset:51200
	ds_read_b128 v[168:171], v136 offset:52224
	s_add_u32 s0, s22, 0x100000
	s_addc_u32 s1, s23, 0
	s_mov_b32 m0, s29
	ds_read_b128 v[172:175], v139 offset:32768
	ds_read_b128 v[176:179], v139 offset:33792
	ds_read_b128 v[180:183], v139 offset:34816
	ds_read_b128 v[184:187], v139 offset:35840
	ds_read_b128 v[188:191], v139 offset:36864
	ds_read_b128 v[192:195], v139 offset:37888
	ds_read_b128 v[196:199], v139 offset:38912
	ds_read_b128 v[208:211], v139 offset:39936
	global_load_lds_dwordx4 v202, s[0:1]
	s_mov_b32 m0, s30
	s_nop 0
	global_load_lds_dwordx4 v130, s[0:1]
	s_waitcnt vmcnt(8)
	s_waitcnt lgkmcnt(0)
	s_barrier
	v_mfma_f32_16x16x32_bf16 v[126:129], v[140:143], v[172:175], v[126:129]
	v_mfma_f32_16x16x32_bf16 v[122:125], v[148:151], v[172:175], v[122:125]
	v_mfma_f32_16x16x32_bf16 v[118:121], v[140:143], v[180:183], v[118:121]
	v_mfma_f32_16x16x32_bf16 v[114:117], v[148:151], v[180:183], v[114:117]
	v_mfma_f32_16x16x32_bf16 v[106:109], v[140:143], v[188:191], v[106:109]
	v_mfma_f32_16x16x32_bf16 v[98:101], v[148:151], v[188:191], v[98:101]
	v_mfma_f32_16x16x32_bf16 v[90:93], v[140:143], v[196:199], v[90:93]
	v_mfma_f32_16x16x32_bf16 v[82:85], v[148:151], v[196:199], v[82:85]
	v_mfma_f32_16x16x32_bf16 v[126:129], v[144:147], v[176:179], v[126:129]
	v_mfma_f32_16x16x32_bf16 v[122:125], v[152:155], v[176:179], v[122:125]
	v_mfma_f32_16x16x32_bf16 v[118:121], v[144:147], v[184:187], v[118:121]
	v_mfma_f32_16x16x32_bf16 v[114:117], v[152:155], v[184:187], v[114:117]
	v_mfma_f32_16x16x32_bf16 v[106:109], v[144:147], v[192:195], v[106:109]
	v_mfma_f32_16x16x32_bf16 v[98:101], v[152:155], v[192:195], v[98:101]
	v_mfma_f32_16x16x32_bf16 v[90:93], v[144:147], v[208:211], v[90:93]
	v_mfma_f32_16x16x32_bf16 v[82:85], v[152:155], v[208:211], v[82:85]
	v_mfma_f32_16x16x32_bf16 v[110:113], v[156:159], v[172:175], v[110:113]
	v_mfma_f32_16x16x32_bf16 v[102:105], v[164:167], v[172:175], v[102:105]
	v_mfma_f32_16x16x32_bf16 v[94:97], v[156:159], v[180:183], v[94:97]
	v_mfma_f32_16x16x32_bf16 v[86:89], v[164:167], v[180:183], v[86:89]
	v_mfma_f32_16x16x32_bf16 v[78:81], v[156:159], v[188:191], v[78:81]
	v_mfma_f32_16x16x32_bf16 v[74:77], v[164:167], v[188:191], v[74:77]
	v_mfma_f32_16x16x32_bf16 v[70:73], v[156:159], v[196:199], v[70:73]
	v_mfma_f32_16x16x32_bf16 v[66:69], v[164:167], v[196:199], v[66:69]
	v_mfma_f32_16x16x32_bf16 v[110:113], v[160:163], v[176:179], v[110:113]
	v_mfma_f32_16x16x32_bf16 v[102:105], v[168:171], v[176:179], v[102:105]
	v_mfma_f32_16x16x32_bf16 v[94:97], v[160:163], v[184:187], v[94:97]
	v_mfma_f32_16x16x32_bf16 v[86:89], v[168:171], v[184:187], v[86:89]
	v_mfma_f32_16x16x32_bf16 v[78:81], v[160:163], v[192:195], v[78:81]
	v_mfma_f32_16x16x32_bf16 v[74:77], v[168:171], v[192:195], v[74:77]
	v_mfma_f32_16x16x32_bf16 v[70:73], v[160:163], v[208:211], v[70:73]
	v_mfma_f32_16x16x32_bf16 v[66:69], v[168:171], v[208:211], v[66:69]
	s_barrier
	s_add_i32 s0, s33, s26
	s_add_u32 s100, s20, 0x80
	s_addc_u32 s101, s21, 0
	s_mov_b32 m0, s0
	ds_read_b128 v[172:175], v139 offset:49152
	ds_read_b128 v[176:179], v139 offset:50176
	ds_read_b128 v[180:183], v139 offset:51200
	ds_read_b128 v[184:187], v139 offset:52224
	ds_read_b128 v[188:191], v139 offset:53248
	ds_read_b128 v[192:195], v139 offset:54272
	ds_read_b128 v[196:199], v139 offset:55296
	ds_read_b128 v[208:211], v139 offset:56320
	global_load_lds_dwordx4 v202, s[100:101]
	s_add_i32 m0, s0, 0x2000
	s_add_u32 s100, s20, 0x80
	s_addc_u32 s101, s21, 0
	s_add_u32 s0, s20, 0x100080
	s_addc_u32 s1, s21, 0
	s_add_i32 s20, s55, s26
	global_load_lds_dwordx4 v130, s[100:101]
	s_mov_b32 m0, s20
	s_nop 0
	global_load_lds_dwordx4 v202, s[0:1]
	s_add_i32 m0, s20, 0x2000
	s_nop 0
	global_load_lds_dwordx4 v130, s[0:1]
	s_add_u32 s100, s22, 0x80
	s_addc_u32 s101, s23, 0
	s_mov_b32 m0, s31
	s_nop 0
	global_load_lds_dwordx4 v202, s[100:101]
	s_add_u32 s100, s22, 0x80
	s_addc_u32 s101, s23, 0
	s_mov_b32 m0, s34
	s_nop 0
	global_load_lds_dwordx4 v130, s[100:101]
	s_waitcnt vmcnt(8)
	s_waitcnt lgkmcnt(0)
	s_barrier
	v_mfma_f32_16x16x32_bf16 v[62:65], v[140:143], v[172:175], v[62:65]
	v_mfma_f32_16x16x32_bf16 v[58:61], v[148:151], v[172:175], v[58:61]
	v_mfma_f32_16x16x32_bf16 v[54:57], v[140:143], v[180:183], v[54:57]
	v_mfma_f32_16x16x32_bf16 v[50:53], v[148:151], v[180:183], v[50:53]
	v_mfma_f32_16x16x32_bf16 v[38:41], v[140:143], v[188:191], v[38:41]
	v_mfma_f32_16x16x32_bf16 v[34:37], v[148:151], v[188:191], v[34:37]
	v_mfma_f32_16x16x32_bf16 v[22:25], v[140:143], v[196:199], v[22:25]
	v_mfma_f32_16x16x32_bf16 v[18:21], v[148:151], v[196:199], v[18:21]
	v_mfma_f32_16x16x32_bf16 v[62:65], v[144:147], v[176:179], v[62:65]
	v_mfma_f32_16x16x32_bf16 v[58:61], v[152:155], v[176:179], v[58:61]
	v_mfma_f32_16x16x32_bf16 v[54:57], v[144:147], v[184:187], v[54:57]
	v_mfma_f32_16x16x32_bf16 v[50:53], v[152:155], v[184:187], v[50:53]
	v_mfma_f32_16x16x32_bf16 v[38:41], v[144:147], v[192:195], v[38:41]
	v_mfma_f32_16x16x32_bf16 v[34:37], v[152:155], v[192:195], v[34:37]
	v_mfma_f32_16x16x32_bf16 v[22:25], v[144:147], v[208:211], v[22:25]
	v_mfma_f32_16x16x32_bf16 v[18:21], v[152:155], v[208:211], v[18:21]
	v_mfma_f32_16x16x32_bf16 v[46:49], v[156:159], v[172:175], v[46:49]
	v_mfma_f32_16x16x32_bf16 v[42:45], v[164:167], v[172:175], v[42:45]
	v_mfma_f32_16x16x32_bf16 v[30:33], v[156:159], v[180:183], v[30:33]
	v_mfma_f32_16x16x32_bf16 v[26:29], v[164:167], v[180:183], v[26:29]
	v_mfma_f32_16x16x32_bf16 v[14:17], v[156:159], v[188:191], v[14:17]
	v_mfma_f32_16x16x32_bf16 v[10:13], v[164:167], v[188:191], v[10:13]
	v_mfma_f32_16x16x32_bf16 v[6:9], v[156:159], v[196:199], v[6:9]
	v_mfma_f32_16x16x32_bf16 v[2:5], v[164:167], v[196:199], v[2:5]
	v_mfma_f32_16x16x32_bf16 v[46:49], v[160:163], v[176:179], v[46:49]
	v_mfma_f32_16x16x32_bf16 v[42:45], v[168:171], v[176:179], v[42:45]
	v_mfma_f32_16x16x32_bf16 v[30:33], v[160:163], v[184:187], v[30:33]
	v_mfma_f32_16x16x32_bf16 v[26:29], v[168:171], v[184:187], v[26:29]
	v_mfma_f32_16x16x32_bf16 v[14:17], v[160:163], v[192:195], v[14:17]
	v_mfma_f32_16x16x32_bf16 v[10:13], v[168:171], v[192:195], v[10:13]
	v_mfma_f32_16x16x32_bf16 v[6:9], v[160:163], v[208:211], v[6:9]
	v_mfma_f32_16x16x32_bf16 v[2:5], v[168:171], v[208:211], v[2:5]
	s_barrier
	s_add_i32 s49, s49, 2
	s_add_u32 s18, s18, 0x100
	s_addc_u32 s19, s19, 0
	s_add_u32 s9, s9, 0x100
	s_addc_u32 s11, s11, 0
	s_cmp_gt_u32 s49, 5
	s_cbranch_scc0 .LBB0_712
	s_and_b64 vcc, exec, s[6:7]
	s_cbranch_vccz .LBB0_715
	s_barrier

.LBB0_837:
	s_add_u32 s0, s18, 0xfff80080
	s_addc_u32 s1, s19, -1
	s_add_i32 s33, 0, 0x10000
	s_cmp_eq_u32 s59, 28
	s_cselect_b32 s23, s11, s1
	s_cselect_b32 s22, s38, s0
	s_cselect_b32 s21, s9, s58
	s_cselect_b32 s20, s39, s49
	s_add_i32 s55, 0, 0x14000
	ds_read_b128 v[146:149], v143
	ds_read_b128 v[150:153], v143 offset:1024
	ds_read_b128 v[154:157], v143 offset:2048
	ds_read_b128 v[158:161], v143 offset:3072
	ds_read_b128 v[162:165], v143 offset:16384
	ds_read_b128 v[166:169], v143 offset:17408
	ds_read_b128 v[170:173], v143 offset:18432
	ds_read_b128 v[174:177], v143 offset:19456
	s_add_i32 m0, s27, 0xc000
	ds_read_b128 v[178:181], v145
	ds_read_b128 v[182:185], v145 offset:1024
	ds_read_b128 v[186:189], v145 offset:2048
	ds_read_b128 v[190:193], v145 offset:3072
	ds_read_b128 v[194:197], v145 offset:4096
	ds_read_b128 v[198:201], v145 offset:5120
	ds_read_b128 v[208:211], v145 offset:6144
	ds_read_b128 v[212:215], v145 offset:7168
	global_load_lds_dwordx4 v136, s[18:19]
	s_add_i32 m0, s27, 0xe000
	s_nop 0
	global_load_lds_dwordx4 v138, s[18:19]
	s_waitcnt vmcnt(8)
	s_waitcnt lgkmcnt(0)
	s_barrier
	v_mfma_f32_16x16x32_bf16 v[126:129], v[146:149], v[178:181], v[126:129]
	v_mfma_f32_16x16x32_bf16 v[118:121], v[154:157], v[178:181], v[118:121]
	v_mfma_f32_16x16x32_bf16 v[110:113], v[146:149], v[186:189], v[110:113]
	v_mfma_f32_16x16x32_bf16 v[102:105], v[154:157], v[186:189], v[102:105]
	v_mfma_f32_16x16x32_bf16 v[94:97], v[146:149], v[194:197], v[94:97]
	v_mfma_f32_16x16x32_bf16 v[86:89], v[154:157], v[194:197], v[86:89]
	v_mfma_f32_16x16x32_bf16 v[78:81], v[146:149], v[208:211], v[78:81]
	v_mfma_f32_16x16x32_bf16 v[70:73], v[154:157], v[208:211], v[70:73]
	v_mfma_f32_16x16x32_bf16 v[126:129], v[150:153], v[182:185], v[126:129]
	v_mfma_f32_16x16x32_bf16 v[118:121], v[158:161], v[182:185], v[118:121]
	v_mfma_f32_16x16x32_bf16 v[110:113], v[150:153], v[190:193], v[110:113]
	v_mfma_f32_16x16x32_bf16 v[102:105], v[158:161], v[190:193], v[102:105]
	v_mfma_f32_16x16x32_bf16 v[94:97], v[150:153], v[198:201], v[94:97]
	v_mfma_f32_16x16x32_bf16 v[86:89], v[158:161], v[198:201], v[86:89]
	v_mfma_f32_16x16x32_bf16 v[78:81], v[150:153], v[212:215], v[78:81]
	v_mfma_f32_16x16x32_bf16 v[70:73], v[158:161], v[212:215], v[70:73]
	v_mfma_f32_16x16x32_bf16 v[122:125], v[162:165], v[178:181], v[122:125]
	v_mfma_f32_16x16x32_bf16 v[114:117], v[170:173], v[178:181], v[114:117]
	v_mfma_f32_16x16x32_bf16 v[106:109], v[162:165], v[186:189], v[106:109]
	v_mfma_f32_16x16x32_bf16 v[98:101], v[170:173], v[186:189], v[98:101]
	v_mfma_f32_16x16x32_bf16 v[90:93], v[162:165], v[194:197], v[90:93]
	v_mfma_f32_16x16x32_bf16 v[82:85], v[170:173], v[194:197], v[82:85]
	v_mfma_f32_16x16x32_bf16 v[74:77], v[162:165], v[208:211], v[74:77]
	v_mfma_f32_16x16x32_bf16 v[66:69], v[170:173], v[208:211], v[66:69]
	v_mfma_f32_16x16x32_bf16 v[122:125], v[166:169], v[182:185], v[122:125]
	v_mfma_f32_16x16x32_bf16 v[114:117], v[174:177], v[182:185], v[114:117]
	v_mfma_f32_16x16x32_bf16 v[106:109], v[166:169], v[190:193], v[106:109]
	v_mfma_f32_16x16x32_bf16 v[98:101], v[174:177], v[190:193], v[98:101]
	v_mfma_f32_16x16x32_bf16 v[90:93], v[166:169], v[198:201], v[90:93]
	v_mfma_f32_16x16x32_bf16 v[82:85], v[174:177], v[198:201], v[82:85]
	v_mfma_f32_16x16x32_bf16 v[74:77], v[166:169], v[212:215], v[74:77]
	v_mfma_f32_16x16x32_bf16 v[66:69], v[174:177], v[212:215], v[66:69]
	s_barrier
	s_add_i32 s0, s33, s26
	s_mov_b32 m0, s0
	ds_read_b128 v[178:181], v145 offset:16384
	ds_read_b128 v[182:185], v145 offset:17408
	ds_read_b128 v[186:189], v145 offset:18432
	ds_read_b128 v[190:193], v145 offset:19456
	ds_read_b128 v[194:197], v145 offset:20480
	ds_read_b128 v[198:201], v145 offset:21504
	ds_read_b128 v[208:211], v145 offset:22528
	ds_read_b128 v[212:215], v145 offset:23552
	global_load_lds_dwordx4 v202, s[20:21]
	s_add_i32 m0, s0, 0x2000
	s_add_u32 s0, s20, 0x80000
	s_addc_u32 s1, s21, 0
	s_add_i32 s33, s55, s26
	global_load_lds_dwordx4 v130, s[20:21]
	s_mov_b32 m0, s33
	s_nop 0
	global_load_lds_dwordx4 v202, s[0:1]
	s_add_i32 m0, s33, 0x2000
	s_nop 0
	global_load_lds_dwordx4 v130, s[0:1]
	s_mov_b32 m0, s27
	s_nop 0
	global_load_lds_dwordx4 v134, s[22:23]
	s_mov_b32 m0, s28
	s_nop 0
	global_load_lds_dwordx4 v132, s[22:23]
	s_waitcnt vmcnt(8)
	s_waitcnt lgkmcnt(0)
	s_barrier
	v_mfma_f32_16x16x32_bf16 v[62:65], v[146:149], v[178:181], v[62:65]
	v_mfma_f32_16x16x32_bf16 v[54:57], v[154:157], v[178:181], v[54:57]
	v_mfma_f32_16x16x32_bf16 v[46:49], v[146:149], v[186:189], v[46:49]
	v_mfma_f32_16x16x32_bf16 v[38:41], v[154:157], v[186:189], v[38:41]
	v_mfma_f32_16x16x32_bf16 v[30:33], v[146:149], v[194:197], v[30:33]
	v_mfma_f32_16x16x32_bf16 v[22:25], v[154:157], v[194:197], v[22:25]
	v_mfma_f32_16x16x32_bf16 v[14:17], v[146:149], v[208:211], v[14:17]
	v_mfma_f32_16x16x32_bf16 v[6:9], v[154:157], v[208:211], v[6:9]
	v_mfma_f32_16x16x32_bf16 v[62:65], v[150:153], v[182:185], v[62:65]
	v_mfma_f32_16x16x32_bf16 v[54:57], v[158:161], v[182:185], v[54:57]
	v_mfma_f32_16x16x32_bf16 v[46:49], v[150:153], v[190:193], v[46:49]
	v_mfma_f32_16x16x32_bf16 v[38:41], v[158:161], v[190:193], v[38:41]
	v_mfma_f32_16x16x32_bf16 v[30:33], v[150:153], v[198:201], v[30:33]
	v_mfma_f32_16x16x32_bf16 v[22:25], v[158:161], v[198:201], v[22:25]
	v_mfma_f32_16x16x32_bf16 v[14:17], v[150:153], v[212:215], v[14:17]
	v_mfma_f32_16x16x32_bf16 v[6:9], v[158:161], v[212:215], v[6:9]
	v_mfma_f32_16x16x32_bf16 v[58:61], v[162:165], v[178:181], v[58:61]
	v_mfma_f32_16x16x32_bf16 v[50:53], v[170:173], v[178:181], v[50:53]
	v_mfma_f32_16x16x32_bf16 v[42:45], v[162:165], v[186:189], v[42:45]
	v_mfma_f32_16x16x32_bf16 v[34:37], v[170:173], v[186:189], v[34:37]
	v_mfma_f32_16x16x32_bf16 v[26:29], v[162:165], v[194:197], v[26:29]
	v_mfma_f32_16x16x32_bf16 v[18:21], v[170:173], v[194:197], v[18:21]
	v_mfma_f32_16x16x32_bf16 v[10:13], v[162:165], v[208:211], v[10:13]
	v_mfma_f32_16x16x32_bf16 v[2:5], v[170:173], v[208:211], v[2:5]
	v_mfma_f32_16x16x32_bf16 v[58:61], v[166:169], v[182:185], v[58:61]
	v_mfma_f32_16x16x32_bf16 v[50:53], v[174:177], v[182:185], v[50:53]
	v_mfma_f32_16x16x32_bf16 v[42:45], v[166:169], v[190:193], v[42:45]
	v_mfma_f32_16x16x32_bf16 v[34:37], v[174:177], v[190:193], v[34:37]
	v_mfma_f32_16x16x32_bf16 v[26:29], v[166:169], v[198:201], v[26:29]
	v_mfma_f32_16x16x32_bf16 v[18:21], v[174:177], v[198:201], v[18:21]
	v_mfma_f32_16x16x32_bf16 v[10:13], v[166:169], v[212:215], v[10:13]
	v_mfma_f32_16x16x32_bf16 v[2:5], v[174:177], v[212:215], v[2:5]
	s_barrier
	s_add_i32 s33, 0, 0x18000
	s_add_i32 s55, 0, 0x1c000
	ds_read_b128 v[146:149], v143 offset:32768
	ds_read_b128 v[150:153], v143 offset:33792
	ds_read_b128 v[154:157], v143 offset:34816
	ds_read_b128 v[158:161], v143 offset:35840
	ds_read_b128 v[162:165], v143 offset:49152
	ds_read_b128 v[166:169], v143 offset:50176
	ds_read_b128 v[170:173], v143 offset:51200
	ds_read_b128 v[174:177], v143 offset:52224
	s_add_u32 s0, s22, 0x80000
	s_addc_u32 s1, s23, 0
	s_mov_b32 m0, s29
	ds_read_b128 v[178:181], v145 offset:32768
	ds_read_b128 v[182:185], v145 offset:33792
	ds_read_b128 v[186:189], v145 offset:34816
	ds_read_b128 v[190:193], v145 offset:35840
	ds_read_b128 v[194:197], v145 offset:36864
	ds_read_b128 v[198:201], v145 offset:37888
	ds_read_b128 v[208:211], v145 offset:38912
	ds_read_b128 v[212:215], v145 offset:39936
	global_load_lds_dwordx4 v134, s[0:1]
	s_mov_b32 m0, s30
	s_nop 0
	global_load_lds_dwordx4 v132, s[0:1]
	s_waitcnt vmcnt(8)
	s_waitcnt lgkmcnt(0)
	s_barrier
	v_mfma_f32_16x16x32_bf16 v[126:129], v[146:149], v[178:181], v[126:129]
	v_mfma_f32_16x16x32_bf16 v[118:121], v[154:157], v[178:181], v[118:121]
	v_mfma_f32_16x16x32_bf16 v[110:113], v[146:149], v[186:189], v[110:113]
	v_mfma_f32_16x16x32_bf16 v[102:105], v[154:157], v[186:189], v[102:105]
	v_mfma_f32_16x16x32_bf16 v[94:97], v[146:149], v[194:197], v[94:97]
	v_mfma_f32_16x16x32_bf16 v[86:89], v[154:157], v[194:197], v[86:89]
	v_mfma_f32_16x16x32_bf16 v[78:81], v[146:149], v[208:211], v[78:81]
	v_mfma_f32_16x16x32_bf16 v[70:73], v[154:157], v[208:211], v[70:73]
	v_mfma_f32_16x16x32_bf16 v[126:129], v[150:153], v[182:185], v[126:129]
	v_mfma_f32_16x16x32_bf16 v[118:121], v[158:161], v[182:185], v[118:121]
	v_mfma_f32_16x16x32_bf16 v[110:113], v[150:153], v[190:193], v[110:113]
	v_mfma_f32_16x16x32_bf16 v[102:105], v[158:161], v[190:193], v[102:105]
	v_mfma_f32_16x16x32_bf16 v[94:97], v[150:153], v[198:201], v[94:97]
	v_mfma_f32_16x16x32_bf16 v[86:89], v[158:161], v[198:201], v[86:89]
	v_mfma_f32_16x16x32_bf16 v[78:81], v[150:153], v[212:215], v[78:81]
	v_mfma_f32_16x16x32_bf16 v[70:73], v[158:161], v[212:215], v[70:73]
	v_mfma_f32_16x16x32_bf16 v[122:125], v[162:165], v[178:181], v[122:125]
	v_mfma_f32_16x16x32_bf16 v[114:117], v[170:173], v[178:181], v[114:117]
	v_mfma_f32_16x16x32_bf16 v[106:109], v[162:165], v[186:189], v[106:109]
	v_mfma_f32_16x16x32_bf16 v[98:101], v[170:173], v[186:189], v[98:101]
	v_mfma_f32_16x16x32_bf16 v[90:93], v[162:165], v[194:197], v[90:93]
	v_mfma_f32_16x16x32_bf16 v[82:85], v[170:173], v[194:197], v[82:85]
	v_mfma_f32_16x16x32_bf16 v[74:77], v[162:165], v[208:211], v[74:77]
	v_mfma_f32_16x16x32_bf16 v[66:69], v[170:173], v[208:211], v[66:69]
	v_mfma_f32_16x16x32_bf16 v[122:125], v[166:169], v[182:185], v[122:125]
	v_mfma_f32_16x16x32_bf16 v[114:117], v[174:177], v[182:185], v[114:117]
	v_mfma_f32_16x16x32_bf16 v[106:109], v[166:169], v[190:193], v[106:109]
	v_mfma_f32_16x16x32_bf16 v[98:101], v[174:177], v[190:193], v[98:101]
	v_mfma_f32_16x16x32_bf16 v[90:93], v[166:169], v[198:201], v[90:93]
	v_mfma_f32_16x16x32_bf16 v[82:85], v[174:177], v[198:201], v[82:85]
	v_mfma_f32_16x16x32_bf16 v[74:77], v[166:169], v[212:215], v[74:77]
	v_mfma_f32_16x16x32_bf16 v[66:69], v[174:177], v[212:215], v[66:69]
	s_barrier
	s_add_i32 s0, s33, s26
	s_add_u32 s100, s20, 0x80
	s_addc_u32 s101, s21, 0
	s_mov_b32 m0, s0
	ds_read_b128 v[178:181], v145 offset:49152
	ds_read_b128 v[182:185], v145 offset:50176
	ds_read_b128 v[186:189], v145 offset:51200
	ds_read_b128 v[190:193], v145 offset:52224
	ds_read_b128 v[194:197], v145 offset:53248
	ds_read_b128 v[198:201], v145 offset:54272
	ds_read_b128 v[208:211], v145 offset:55296
	ds_read_b128 v[212:215], v145 offset:56320
	global_load_lds_dwordx4 v202, s[100:101]
	s_add_i32 m0, s0, 0x2000
	s_add_u32 s100, s20, 0x80
	s_addc_u32 s101, s21, 0
	s_add_u32 s0, s20, 0x80080
	s_addc_u32 s1, s21, 0
	s_add_i32 s20, s55, s26
	global_load_lds_dwordx4 v130, s[100:101]
	s_mov_b32 m0, s20
	s_nop 0
	global_load_lds_dwordx4 v202, s[0:1]
	s_add_i32 m0, s20, 0x2000
	s_nop 0
	global_load_lds_dwordx4 v130, s[0:1]
	s_add_u32 s100, s22, 0x80
	s_addc_u32 s101, s23, 0
	s_mov_b32 m0, s31
	s_nop 0
	global_load_lds_dwordx4 v134, s[100:101]
	s_add_u32 s100, s22, 0x80
	s_addc_u32 s101, s23, 0
	s_mov_b32 m0, s34
	s_nop 0
	global_load_lds_dwordx4 v132, s[100:101]
	s_waitcnt vmcnt(8)
	s_waitcnt lgkmcnt(0)
	s_barrier
	v_mfma_f32_16x16x32_bf16 v[62:65], v[146:149], v[178:181], v[62:65]
	v_mfma_f32_16x16x32_bf16 v[54:57], v[154:157], v[178:181], v[54:57]
	v_mfma_f32_16x16x32_bf16 v[46:49], v[146:149], v[186:189], v[46:49]
	v_mfma_f32_16x16x32_bf16 v[38:41], v[154:157], v[186:189], v[38:41]
	v_mfma_f32_16x16x32_bf16 v[30:33], v[146:149], v[194:197], v[30:33]
	v_mfma_f32_16x16x32_bf16 v[22:25], v[154:157], v[194:197], v[22:25]
	v_mfma_f32_16x16x32_bf16 v[14:17], v[146:149], v[208:211], v[14:17]
	v_mfma_f32_16x16x32_bf16 v[6:9], v[154:157], v[208:211], v[6:9]
	v_mfma_f32_16x16x32_bf16 v[62:65], v[150:153], v[182:185], v[62:65]
	v_mfma_f32_16x16x32_bf16 v[54:57], v[158:161], v[182:185], v[54:57]
	v_mfma_f32_16x16x32_bf16 v[46:49], v[150:153], v[190:193], v[46:49]
	v_mfma_f32_16x16x32_bf16 v[38:41], v[158:161], v[190:193], v[38:41]
	v_mfma_f32_16x16x32_bf16 v[30:33], v[150:153], v[198:201], v[30:33]
	v_mfma_f32_16x16x32_bf16 v[22:25], v[158:161], v[198:201], v[22:25]
	v_mfma_f32_16x16x32_bf16 v[14:17], v[150:153], v[212:215], v[14:17]
	v_mfma_f32_16x16x32_bf16 v[6:9], v[158:161], v[212:215], v[6:9]
	v_mfma_f32_16x16x32_bf16 v[58:61], v[162:165], v[178:181], v[58:61]
	v_mfma_f32_16x16x32_bf16 v[50:53], v[170:173], v[178:181], v[50:53]
	v_mfma_f32_16x16x32_bf16 v[42:45], v[162:165], v[186:189], v[42:45]
	v_mfma_f32_16x16x32_bf16 v[34:37], v[170:173], v[186:189], v[34:37]
	v_mfma_f32_16x16x32_bf16 v[26:29], v[162:165], v[194:197], v[26:29]
	v_mfma_f32_16x16x32_bf16 v[18:21], v[170:173], v[194:197], v[18:21]
	v_mfma_f32_16x16x32_bf16 v[10:13], v[162:165], v[208:211], v[10:13]
	v_mfma_f32_16x16x32_bf16 v[2:5], v[170:173], v[208:211], v[2:5]
	v_mfma_f32_16x16x32_bf16 v[58:61], v[166:169], v[182:185], v[58:61]
	v_mfma_f32_16x16x32_bf16 v[50:53], v[174:177], v[182:185], v[50:53]
	v_mfma_f32_16x16x32_bf16 v[42:45], v[166:169], v[190:193], v[42:45]
	v_mfma_f32_16x16x32_bf16 v[34:37], v[174:177], v[190:193], v[34:37]
	v_mfma_f32_16x16x32_bf16 v[26:29], v[166:169], v[198:201], v[26:29]
	v_mfma_f32_16x16x32_bf16 v[18:21], v[174:177], v[198:201], v[18:21]
	v_mfma_f32_16x16x32_bf16 v[10:13], v[166:169], v[212:215], v[10:13]
	v_mfma_f32_16x16x32_bf16 v[2:5], v[174:177], v[212:215], v[2:5]
	s_barrier
	s_add_i32 s59, s59, 2
	s_add_u32 s18, s18, 0x100
	s_addc_u32 s19, s19, 0
	s_add_u32 s49, s49, 0x100
	s_addc_u32 s58, s58, 0
	s_cmp_gt_u32 s59, 29
	s_cbranch_scc0 .LBB0_837
	s_and_b64 vcc, exec, s[6:7]
	s_cbranch_vccz .LBB0_840
	s_barrier

.LBB0_970:
	s_add_u32 s16, s2, 0x100
	s_addc_u32 s17, s3, 0
	s_add_i32 s0, 0, 0x10000
	s_cmpk_eq_i32 s59, 0x54
	s_cselect_b32 s21, s7, s17
	s_cselect_b32 s20, s6, s16
	s_cselect_b32 s19, s15, s58
	s_cselect_b32 s18, s14, s49
	s_add_i32 s33, 0, 0x14000
	ds_read_b128 v[78:81], v205
	ds_read_b128 v[82:85], v205 offset:1024
	ds_read_b128 v[94:97], v205 offset:2048
	ds_read_b128 v[98:101], v205 offset:3072
	ds_read_b128 v[106:109], v205 offset:16384
	ds_read_b128 v[110:113], v205 offset:17408
	ds_read_b128 v[126:129], v205 offset:18432
	ds_read_b128 v[134:137], v205 offset:19456
	s_add_i32 m0, s25, 0xc000
	ds_read_b128 v[146:149], v239
	ds_read_b128 v[158:161], v239 offset:1024
	ds_read_b128 v[166:169], v239 offset:2048
	ds_read_b128 v[174:177], v239 offset:3072
	ds_read_b128 v[178:181], v239 offset:4096
	ds_read_b128 v[182:185], v239 offset:5120
	ds_read_b128 v[186:189], v239 offset:6144
	ds_read_b128 v[190:193], v239 offset:7168
	global_load_lds_dwordx4 v214, s[2:3]
	s_add_i32 m0, s25, 0xe000
	s_nop 0
	global_load_lds_dwordx4 v216, s[2:3]
	s_waitcnt vmcnt(8)
	s_waitcnt lgkmcnt(0)
	s_barrier
	v_mfma_f32_16x16x32_bf16 v[170:173], v[78:81], v[146:149], v[170:173]
	v_mfma_f32_16x16x32_bf16 v[162:165], v[94:97], v[146:149], v[162:165]
	v_mfma_f32_16x16x32_bf16 v[142:145], v[78:81], v[166:169], v[142:145]
	v_mfma_f32_16x16x32_bf16 v[138:141], v[94:97], v[166:169], v[138:141]
	v_mfma_f32_16x16x32_bf16 v[118:121], v[78:81], v[178:181], v[118:121]
	v_mfma_f32_16x16x32_bf16 v[114:117], v[94:97], v[178:181], v[114:117]
	v_mfma_f32_16x16x32_bf16 v[86:89], v[78:81], v[186:189], v[86:89]
	v_mfma_f32_16x16x32_bf16 v[74:77], v[94:97], v[186:189], v[74:77]
	v_mfma_f32_16x16x32_bf16 v[170:173], v[82:85], v[158:161], v[170:173]
	v_mfma_f32_16x16x32_bf16 v[162:165], v[98:101], v[158:161], v[162:165]
	v_mfma_f32_16x16x32_bf16 v[142:145], v[82:85], v[174:177], v[142:145]
	v_mfma_f32_16x16x32_bf16 v[138:141], v[98:101], v[174:177], v[138:141]
	v_mfma_f32_16x16x32_bf16 v[118:121], v[82:85], v[182:185], v[118:121]
	v_mfma_f32_16x16x32_bf16 v[114:117], v[98:101], v[182:185], v[114:117]
	v_mfma_f32_16x16x32_bf16 v[86:89], v[82:85], v[190:193], v[86:89]
	v_mfma_f32_16x16x32_bf16 v[74:77], v[98:101], v[190:193], v[74:77]
	v_mfma_f32_16x16x32_bf16 v[154:157], v[106:109], v[146:149], v[154:157]
	v_mfma_f32_16x16x32_bf16 v[130:133], v[106:109], v[166:169], v[130:133]
	v_mfma_f32_16x16x32_bf16 v[122:125], v[126:129], v[166:169], v[122:125]
	v_mfma_f32_16x16x32_bf16 v[102:105], v[106:109], v[178:181], v[102:105]
	v_mfma_f32_16x16x32_bf16 v[90:93], v[126:129], v[178:181], v[90:93]
	v_mfma_f32_16x16x32_bf16 v[70:73], v[106:109], v[186:189], v[70:73]
	v_mfma_f32_16x16x32_bf16 v[66:69], v[126:129], v[186:189], v[66:69]
	v_mfma_f32_16x16x32_bf16 v[154:157], v[110:113], v[158:161], v[154:157]
	v_mfma_f32_16x16x32_bf16 v[146:149], v[126:129], v[146:149], v[150:153]
	v_mfma_f32_16x16x32_bf16 v[130:133], v[110:113], v[174:177], v[130:133]
	v_mfma_f32_16x16x32_bf16 v[122:125], v[134:137], v[174:177], v[122:125]
	v_mfma_f32_16x16x32_bf16 v[102:105], v[110:113], v[182:185], v[102:105]
	v_mfma_f32_16x16x32_bf16 v[90:93], v[134:137], v[182:185], v[90:93]
	v_mfma_f32_16x16x32_bf16 v[70:73], v[110:113], v[190:193], v[70:73]
	v_mfma_f32_16x16x32_bf16 v[66:69], v[134:137], v[190:193], v[66:69]
	v_mfma_f32_16x16x32_bf16 v[146:149], v[134:137], v[158:161], v[146:149]
	s_barrier
	s_add_i32 s0, s0, s24
	s_mov_b32 m0, s0
	ds_read_b128 v[150:153], v239 offset:16384
	ds_read_b128 v[158:161], v239 offset:17408
	ds_read_b128 v[166:169], v239 offset:18432
	ds_read_b128 v[174:177], v239 offset:19456
	ds_read_b128 v[178:181], v239 offset:20480
	ds_read_b128 v[182:185], v239 offset:21504
	ds_read_b128 v[186:189], v239 offset:22528
	ds_read_b128 v[190:193], v239 offset:23552
	global_load_lds_dwordx4 v202, s[18:19]
	s_add_i32 m0, s0, 0x2000
	s_add_u32 s0, s18, 0x160000
	s_addc_u32 s1, s19, 0
	s_add_i32 s2, s33, s24
	global_load_lds_dwordx4 v208, s[18:19]
	s_mov_b32 m0, s2
	s_nop 0
	global_load_lds_dwordx4 v202, s[0:1]
	s_add_i32 m0, s2, 0x2000
	s_nop 0
	global_load_lds_dwordx4 v208, s[0:1]
	s_mov_b32 m0, s25
	s_nop 0
	global_load_lds_dwordx4 v212, s[20:21]
	s_mov_b32 m0, s26
	s_nop 0
	global_load_lds_dwordx4 v210, s[20:21]
	s_waitcnt vmcnt(8)
	s_waitcnt lgkmcnt(0)
	s_barrier
	v_mfma_f32_16x16x32_bf16 v[62:65], v[78:81], v[150:153], v[62:65]
	v_mfma_f32_16x16x32_bf16 v[58:61], v[94:97], v[150:153], v[58:61]
	v_mfma_f32_16x16x32_bf16 v[46:49], v[78:81], v[166:169], v[46:49]
	v_mfma_f32_16x16x32_bf16 v[42:45], v[94:97], v[166:169], v[42:45]
	v_mfma_f32_16x16x32_bf16 v[30:33], v[78:81], v[178:181], v[30:33]
	v_mfma_f32_16x16x32_bf16 v[26:29], v[94:97], v[178:181], v[26:29]
	v_mfma_f32_16x16x32_bf16 v[14:17], v[78:81], v[186:189], v[14:17]
	v_mfma_f32_16x16x32_bf16 v[10:13], v[94:97], v[186:189], v[10:13]
	v_mfma_f32_16x16x32_bf16 v[62:65], v[82:85], v[158:161], v[62:65]
	v_mfma_f32_16x16x32_bf16 v[58:61], v[98:101], v[158:161], v[58:61]
	v_mfma_f32_16x16x32_bf16 v[46:49], v[82:85], v[174:177], v[46:49]
	v_mfma_f32_16x16x32_bf16 v[42:45], v[98:101], v[174:177], v[42:45]
	v_mfma_f32_16x16x32_bf16 v[30:33], v[82:85], v[182:185], v[30:33]
	v_mfma_f32_16x16x32_bf16 v[26:29], v[98:101], v[182:185], v[26:29]
	v_mfma_f32_16x16x32_bf16 v[14:17], v[82:85], v[190:193], v[14:17]
	v_mfma_f32_16x16x32_bf16 v[10:13], v[98:101], v[190:193], v[10:13]
	v_mfma_f32_16x16x32_bf16 v[54:57], v[106:109], v[150:153], v[54:57]
	v_mfma_f32_16x16x32_bf16 v[50:53], v[126:129], v[150:153], v[50:53]
	v_mfma_f32_16x16x32_bf16 v[38:41], v[106:109], v[166:169], v[38:41]
	v_mfma_f32_16x16x32_bf16 v[34:37], v[126:129], v[166:169], v[34:37]
	v_mfma_f32_16x16x32_bf16 v[22:25], v[106:109], v[178:181], v[22:25]
	v_mfma_f32_16x16x32_bf16 v[18:21], v[126:129], v[178:181], v[18:21]
	v_mfma_f32_16x16x32_bf16 v[6:9], v[106:109], v[186:189], v[6:9]
	v_mfma_f32_16x16x32_bf16 v[2:5], v[126:129], v[186:189], v[2:5]
	v_mfma_f32_16x16x32_bf16 v[54:57], v[110:113], v[158:161], v[54:57]
	v_mfma_f32_16x16x32_bf16 v[50:53], v[134:137], v[158:161], v[50:53]
	v_mfma_f32_16x16x32_bf16 v[38:41], v[110:113], v[174:177], v[38:41]
	v_mfma_f32_16x16x32_bf16 v[34:37], v[134:137], v[174:177], v[34:37]
	v_mfma_f32_16x16x32_bf16 v[22:25], v[110:113], v[182:185], v[22:25]
	v_mfma_f32_16x16x32_bf16 v[18:21], v[134:137], v[182:185], v[18:21]
	v_mfma_f32_16x16x32_bf16 v[6:9], v[110:113], v[190:193], v[6:9]
	v_mfma_f32_16x16x32_bf16 v[2:5], v[134:137], v[190:193], v[2:5]
	s_barrier
	s_add_i32 s2, 0, 0x18000
	s_add_i32 s3, 0, 0x1c000
	ds_read_b128 v[78:81], v205 offset:32768
	ds_read_b128 v[82:85], v205 offset:33792
	ds_read_b128 v[94:97], v205 offset:34816
	ds_read_b128 v[98:101], v205 offset:35840
	ds_read_b128 v[106:109], v205 offset:49152
	ds_read_b128 v[110:113], v205 offset:50176
	ds_read_b128 v[126:129], v205 offset:51200
	ds_read_b128 v[134:137], v205 offset:52224
	s_add_u32 s0, s20, 0x160000
	s_addc_u32 s1, s21, 0
	s_mov_b32 m0, s27
	ds_read_b128 v[150:153], v239 offset:32768
	ds_read_b128 v[158:161], v239 offset:33792
	ds_read_b128 v[166:169], v239 offset:34816
	ds_read_b128 v[174:177], v239 offset:35840
	ds_read_b128 v[178:181], v239 offset:36864
	ds_read_b128 v[182:185], v239 offset:37888
	ds_read_b128 v[186:189], v239 offset:38912
	ds_read_b128 v[190:193], v239 offset:39936
	global_load_lds_dwordx4 v212, s[0:1]
	s_mov_b32 m0, s28
	s_nop 0
	global_load_lds_dwordx4 v210, s[0:1]
	s_waitcnt vmcnt(8)
	s_waitcnt lgkmcnt(0)
	s_barrier
	v_mfma_f32_16x16x32_bf16 v[170:173], v[78:81], v[150:153], v[170:173]
	v_mfma_f32_16x16x32_bf16 v[162:165], v[94:97], v[150:153], v[162:165]
	v_mfma_f32_16x16x32_bf16 v[142:145], v[78:81], v[166:169], v[142:145]
	v_mfma_f32_16x16x32_bf16 v[138:141], v[94:97], v[166:169], v[138:141]
	v_mfma_f32_16x16x32_bf16 v[118:121], v[78:81], v[178:181], v[118:121]
	v_mfma_f32_16x16x32_bf16 v[114:117], v[94:97], v[178:181], v[114:117]
	v_mfma_f32_16x16x32_bf16 v[86:89], v[78:81], v[186:189], v[86:89]
	v_mfma_f32_16x16x32_bf16 v[74:77], v[94:97], v[186:189], v[74:77]
	v_mfma_f32_16x16x32_bf16 v[170:173], v[82:85], v[158:161], v[170:173]
	v_mfma_f32_16x16x32_bf16 v[162:165], v[98:101], v[158:161], v[162:165]
	v_mfma_f32_16x16x32_bf16 v[142:145], v[82:85], v[174:177], v[142:145]
	v_mfma_f32_16x16x32_bf16 v[138:141], v[98:101], v[174:177], v[138:141]
	v_mfma_f32_16x16x32_bf16 v[118:121], v[82:85], v[182:185], v[118:121]
	v_mfma_f32_16x16x32_bf16 v[114:117], v[98:101], v[182:185], v[114:117]
	v_mfma_f32_16x16x32_bf16 v[86:89], v[82:85], v[190:193], v[86:89]
	v_mfma_f32_16x16x32_bf16 v[74:77], v[98:101], v[190:193], v[74:77]
	v_mfma_f32_16x16x32_bf16 v[154:157], v[106:109], v[150:153], v[154:157]
	v_mfma_f32_16x16x32_bf16 v[146:149], v[126:129], v[150:153], v[146:149]
	v_mfma_f32_16x16x32_bf16 v[130:133], v[106:109], v[166:169], v[130:133]
	v_mfma_f32_16x16x32_bf16 v[122:125], v[126:129], v[166:169], v[122:125]
	v_mfma_f32_16x16x32_bf16 v[102:105], v[106:109], v[178:181], v[102:105]
	v_mfma_f32_16x16x32_bf16 v[90:93], v[126:129], v[178:181], v[90:93]
	v_mfma_f32_16x16x32_bf16 v[70:73], v[106:109], v[186:189], v[70:73]
	v_mfma_f32_16x16x32_bf16 v[66:69], v[126:129], v[186:189], v[66:69]
	v_mfma_f32_16x16x32_bf16 v[154:157], v[110:113], v[158:161], v[154:157]
	v_mfma_f32_16x16x32_bf16 v[150:153], v[134:137], v[158:161], v[146:149]
	v_mfma_f32_16x16x32_bf16 v[130:133], v[110:113], v[174:177], v[130:133]
	v_mfma_f32_16x16x32_bf16 v[122:125], v[134:137], v[174:177], v[122:125]
	v_mfma_f32_16x16x32_bf16 v[102:105], v[110:113], v[182:185], v[102:105]
	v_mfma_f32_16x16x32_bf16 v[90:93], v[134:137], v[182:185], v[90:93]
	v_mfma_f32_16x16x32_bf16 v[70:73], v[110:113], v[190:193], v[70:73]
	v_mfma_f32_16x16x32_bf16 v[66:69], v[134:137], v[190:193], v[66:69]
	s_barrier
	s_add_i32 s0, s2, s24
	s_add_u32 s100, s18, 0x80
	s_addc_u32 s101, s19, 0
	s_mov_b32 m0, s0
	ds_read_b128 v[146:149], v239 offset:49152
	ds_read_b128 v[158:161], v239 offset:50176
	ds_read_b128 v[166:169], v239 offset:51200
	ds_read_b128 v[174:177], v239 offset:52224
	ds_read_b128 v[178:181], v239 offset:53248
	ds_read_b128 v[182:185], v239 offset:54272
	ds_read_b128 v[186:189], v239 offset:55296
	ds_read_b128 v[190:193], v239 offset:56320
	global_load_lds_dwordx4 v202, s[100:101]
	s_add_i32 m0, s0, 0x2000
	s_add_u32 s100, s18, 0x80
	s_addc_u32 s101, s19, 0
	s_add_u32 s0, s18, 0x160080
	s_addc_u32 s1, s19, 0
	s_add_i32 s2, s3, s24
	global_load_lds_dwordx4 v208, s[100:101]
	s_mov_b32 m0, s2
	s_nop 0
	global_load_lds_dwordx4 v202, s[0:1]
	s_add_i32 m0, s2, 0x2000
	s_nop 0
	global_load_lds_dwordx4 v208, s[0:1]
	s_add_u32 s100, s20, 0x80
	s_addc_u32 s101, s21, 0
	s_mov_b32 m0, s31
	s_nop 0
	global_load_lds_dwordx4 v212, s[100:101]
	s_add_u32 s100, s20, 0x80
	s_addc_u32 s101, s21, 0
	s_mov_b32 m0, s34
	s_nop 0
	global_load_lds_dwordx4 v210, s[100:101]
	s_waitcnt vmcnt(8)
	s_waitcnt lgkmcnt(0)
	s_barrier
	v_mfma_f32_16x16x32_bf16 v[62:65], v[78:81], v[146:149], v[62:65]
	v_mfma_f32_16x16x32_bf16 v[58:61], v[94:97], v[146:149], v[58:61]
	v_mfma_f32_16x16x32_bf16 v[46:49], v[78:81], v[166:169], v[46:49]
	v_mfma_f32_16x16x32_bf16 v[42:45], v[94:97], v[166:169], v[42:45]
	v_mfma_f32_16x16x32_bf16 v[30:33], v[78:81], v[178:181], v[30:33]
	v_mfma_f32_16x16x32_bf16 v[26:29], v[94:97], v[178:181], v[26:29]
	v_mfma_f32_16x16x32_bf16 v[14:17], v[78:81], v[186:189], v[14:17]
	v_mfma_f32_16x16x32_bf16 v[10:13], v[94:97], v[186:189], v[10:13]
	v_mfma_f32_16x16x32_bf16 v[62:65], v[82:85], v[158:161], v[62:65]
	v_mfma_f32_16x16x32_bf16 v[58:61], v[98:101], v[158:161], v[58:61]
	v_mfma_f32_16x16x32_bf16 v[46:49], v[82:85], v[174:177], v[46:49]
	v_mfma_f32_16x16x32_bf16 v[42:45], v[98:101], v[174:177], v[42:45]
	v_mfma_f32_16x16x32_bf16 v[30:33], v[82:85], v[182:185], v[30:33]
	v_mfma_f32_16x16x32_bf16 v[26:29], v[98:101], v[182:185], v[26:29]
	v_mfma_f32_16x16x32_bf16 v[14:17], v[82:85], v[190:193], v[14:17]
	v_mfma_f32_16x16x32_bf16 v[10:13], v[98:101], v[190:193], v[10:13]
	v_mfma_f32_16x16x32_bf16 v[54:57], v[106:109], v[146:149], v[54:57]
	v_mfma_f32_16x16x32_bf16 v[50:53], v[126:129], v[146:149], v[50:53]
	v_mfma_f32_16x16x32_bf16 v[38:41], v[106:109], v[166:169], v[38:41]
	v_mfma_f32_16x16x32_bf16 v[34:37], v[126:129], v[166:169], v[34:37]
	v_mfma_f32_16x16x32_bf16 v[22:25], v[106:109], v[178:181], v[22:25]
	v_mfma_f32_16x16x32_bf16 v[18:21], v[126:129], v[178:181], v[18:21]
	v_mfma_f32_16x16x32_bf16 v[6:9], v[106:109], v[186:189], v[6:9]
	v_mfma_f32_16x16x32_bf16 v[2:5], v[126:129], v[186:189], v[2:5]
	v_mfma_f32_16x16x32_bf16 v[54:57], v[110:113], v[158:161], v[54:57]
	v_mfma_f32_16x16x32_bf16 v[50:53], v[134:137], v[158:161], v[50:53]
	v_mfma_f32_16x16x32_bf16 v[38:41], v[110:113], v[174:177], v[38:41]
	v_mfma_f32_16x16x32_bf16 v[34:37], v[134:137], v[174:177], v[34:37]
	v_mfma_f32_16x16x32_bf16 v[22:25], v[110:113], v[182:185], v[22:25]
	v_mfma_f32_16x16x32_bf16 v[18:21], v[134:137], v[182:185], v[18:21]
	v_mfma_f32_16x16x32_bf16 v[6:9], v[110:113], v[190:193], v[6:9]
	v_mfma_f32_16x16x32_bf16 v[2:5], v[134:137], v[190:193], v[2:5]
	s_barrier
	s_add_i32 s59, s59, 2
	s_add_u32 s49, s49, 0x100
	s_addc_u32 s58, s58, 0
	s_cmpk_gt_u32 s59, 0x55
	s_mov_b64 s[2:3], s[16:17]
	s_cbranch_scc0 .LBB0_970
	s_and_b64 vcc, exec, s[10:11]
	s_cbranch_vccz .LBB0_973
	s_barrier

.LBB0_990:
	s_add_u32 s4, s2, 0x100
	s_addc_u32 s5, s3, 0
	s_add_i32 s0, 0, 0x10000
	s_cmp_eq_u32 s59, 4
	s_cselect_b32 s21, s15, s5
	s_cselect_b32 s20, s14, s4
	s_cselect_b32 s19, s17, s58
	s_cselect_b32 s18, s16, s49
	s_add_i32 s33, 0, 0x14000
	ds_read_b128 v[140:143], v136
	ds_read_b128 v[144:147], v136 offset:1024
	ds_read_b128 v[148:151], v136 offset:2048
	ds_read_b128 v[152:155], v136 offset:3072
	ds_read_b128 v[156:159], v136 offset:16384
	ds_read_b128 v[160:163], v136 offset:17408
	ds_read_b128 v[164:167], v136 offset:18432
	ds_read_b128 v[168:171], v136 offset:19456
	s_add_i32 m0, s25, 0xc000
	ds_read_b128 v[172:175], v139
	ds_read_b128 v[176:179], v139 offset:1024
	ds_read_b128 v[180:183], v139 offset:2048
	ds_read_b128 v[184:187], v139 offset:3072
	ds_read_b128 v[188:191], v139 offset:4096
	ds_read_b128 v[192:195], v139 offset:5120
	ds_read_b128 v[196:199], v139 offset:6144
	ds_read_b128 v[208:211], v139 offset:7168
	global_load_lds_dwordx4 v132, s[2:3]
	s_add_i32 m0, s25, 0xe000
	s_nop 0
	global_load_lds_dwordx4 v134, s[2:3]
	s_waitcnt vmcnt(8)
	s_waitcnt lgkmcnt(0)
	s_barrier
	v_mfma_f32_16x16x32_bf16 v[126:129], v[140:143], v[172:175], v[126:129]
	v_mfma_f32_16x16x32_bf16 v[122:125], v[148:151], v[172:175], v[122:125]
	v_mfma_f32_16x16x32_bf16 v[118:121], v[140:143], v[180:183], v[118:121]
	v_mfma_f32_16x16x32_bf16 v[114:117], v[148:151], v[180:183], v[114:117]
	v_mfma_f32_16x16x32_bf16 v[106:109], v[140:143], v[188:191], v[106:109]
	v_mfma_f32_16x16x32_bf16 v[98:101], v[148:151], v[188:191], v[98:101]
	v_mfma_f32_16x16x32_bf16 v[90:93], v[140:143], v[196:199], v[90:93]
	v_mfma_f32_16x16x32_bf16 v[82:85], v[148:151], v[196:199], v[82:85]
	v_mfma_f32_16x16x32_bf16 v[126:129], v[144:147], v[176:179], v[126:129]
	v_mfma_f32_16x16x32_bf16 v[122:125], v[152:155], v[176:179], v[122:125]
	v_mfma_f32_16x16x32_bf16 v[118:121], v[144:147], v[184:187], v[118:121]
	v_mfma_f32_16x16x32_bf16 v[114:117], v[152:155], v[184:187], v[114:117]
	v_mfma_f32_16x16x32_bf16 v[106:109], v[144:147], v[192:195], v[106:109]
	v_mfma_f32_16x16x32_bf16 v[98:101], v[152:155], v[192:195], v[98:101]
	v_mfma_f32_16x16x32_bf16 v[90:93], v[144:147], v[208:211], v[90:93]
	v_mfma_f32_16x16x32_bf16 v[82:85], v[152:155], v[208:211], v[82:85]
	v_mfma_f32_16x16x32_bf16 v[110:113], v[156:159], v[172:175], v[110:113]
	v_mfma_f32_16x16x32_bf16 v[102:105], v[164:167], v[172:175], v[102:105]
	v_mfma_f32_16x16x32_bf16 v[94:97], v[156:159], v[180:183], v[94:97]
	v_mfma_f32_16x16x32_bf16 v[86:89], v[164:167], v[180:183], v[86:89]
	v_mfma_f32_16x16x32_bf16 v[78:81], v[156:159], v[188:191], v[78:81]
	v_mfma_f32_16x16x32_bf16 v[74:77], v[164:167], v[188:191], v[74:77]
	v_mfma_f32_16x16x32_bf16 v[70:73], v[156:159], v[196:199], v[70:73]
	v_mfma_f32_16x16x32_bf16 v[66:69], v[164:167], v[196:199], v[66:69]
	v_mfma_f32_16x16x32_bf16 v[110:113], v[160:163], v[176:179], v[110:113]
	v_mfma_f32_16x16x32_bf16 v[102:105], v[168:171], v[176:179], v[102:105]
	v_mfma_f32_16x16x32_bf16 v[94:97], v[160:163], v[184:187], v[94:97]
	v_mfma_f32_16x16x32_bf16 v[86:89], v[168:171], v[184:187], v[86:89]
	v_mfma_f32_16x16x32_bf16 v[78:81], v[160:163], v[192:195], v[78:81]
	v_mfma_f32_16x16x32_bf16 v[74:77], v[168:171], v[192:195], v[74:77]
	v_mfma_f32_16x16x32_bf16 v[70:73], v[160:163], v[208:211], v[70:73]
	v_mfma_f32_16x16x32_bf16 v[66:69], v[168:171], v[208:211], v[66:69]
	s_barrier
	s_add_i32 s0, s0, s24
	s_mov_b32 m0, s0
	ds_read_b128 v[172:175], v139 offset:16384
	ds_read_b128 v[176:179], v139 offset:17408
	ds_read_b128 v[180:183], v139 offset:18432
	ds_read_b128 v[184:187], v139 offset:19456
	ds_read_b128 v[188:191], v139 offset:20480
	ds_read_b128 v[192:195], v139 offset:21504
	ds_read_b128 v[196:199], v139 offset:22528
	ds_read_b128 v[208:211], v139 offset:23552
	global_load_lds_dwordx4 v202, s[18:19]
	s_add_i32 m0, s0, 0x2000
	s_add_u32 s0, s18, 0x160000
	s_addc_u32 s1, s19, 0
	s_add_i32 s2, s33, s24
	global_load_lds_dwordx4 v130, s[18:19]
	s_mov_b32 m0, s2
	s_nop 0
	global_load_lds_dwordx4 v202, s[0:1]
	s_add_i32 m0, s2, 0x2000
	s_nop 0
	global_load_lds_dwordx4 v130, s[0:1]
	s_mov_b32 m0, s25
	s_nop 0
	global_load_lds_dwordx4 v202, s[20:21]
	s_mov_b32 m0, s26
	s_nop 0
	global_load_lds_dwordx4 v130, s[20:21]
	s_waitcnt vmcnt(8)
	s_waitcnt lgkmcnt(0)
	s_barrier
	v_mfma_f32_16x16x32_bf16 v[62:65], v[140:143], v[172:175], v[62:65]
	v_mfma_f32_16x16x32_bf16 v[58:61], v[148:151], v[172:175], v[58:61]
	v_mfma_f32_16x16x32_bf16 v[54:57], v[140:143], v[180:183], v[54:57]
	v_mfma_f32_16x16x32_bf16 v[50:53], v[148:151], v[180:183], v[50:53]
	v_mfma_f32_16x16x32_bf16 v[38:41], v[140:143], v[188:191], v[38:41]
	v_mfma_f32_16x16x32_bf16 v[34:37], v[148:151], v[188:191], v[34:37]
	v_mfma_f32_16x16x32_bf16 v[22:25], v[140:143], v[196:199], v[22:25]
	v_mfma_f32_16x16x32_bf16 v[18:21], v[148:151], v[196:199], v[18:21]
	v_mfma_f32_16x16x32_bf16 v[62:65], v[144:147], v[176:179], v[62:65]
	v_mfma_f32_16x16x32_bf16 v[58:61], v[152:155], v[176:179], v[58:61]
	v_mfma_f32_16x16x32_bf16 v[54:57], v[144:147], v[184:187], v[54:57]
	v_mfma_f32_16x16x32_bf16 v[50:53], v[152:155], v[184:187], v[50:53]
	v_mfma_f32_16x16x32_bf16 v[38:41], v[144:147], v[192:195], v[38:41]
	v_mfma_f32_16x16x32_bf16 v[34:37], v[152:155], v[192:195], v[34:37]
	v_mfma_f32_16x16x32_bf16 v[22:25], v[144:147], v[208:211], v[22:25]
	v_mfma_f32_16x16x32_bf16 v[18:21], v[152:155], v[208:211], v[18:21]
	v_mfma_f32_16x16x32_bf16 v[46:49], v[156:159], v[172:175], v[46:49]
	v_mfma_f32_16x16x32_bf16 v[42:45], v[164:167], v[172:175], v[42:45]
	v_mfma_f32_16x16x32_bf16 v[30:33], v[156:159], v[180:183], v[30:33]
	v_mfma_f32_16x16x32_bf16 v[26:29], v[164:167], v[180:183], v[26:29]
	v_mfma_f32_16x16x32_bf16 v[14:17], v[156:159], v[188:191], v[14:17]
	v_mfma_f32_16x16x32_bf16 v[10:13], v[164:167], v[188:191], v[10:13]
	v_mfma_f32_16x16x32_bf16 v[6:9], v[156:159], v[196:199], v[6:9]
	v_mfma_f32_16x16x32_bf16 v[2:5], v[164:167], v[196:199], v[2:5]
	v_mfma_f32_16x16x32_bf16 v[46:49], v[160:163], v[176:179], v[46:49]
	v_mfma_f32_16x16x32_bf16 v[42:45], v[168:171], v[176:179], v[42:45]
	v_mfma_f32_16x16x32_bf16 v[30:33], v[160:163], v[184:187], v[30:33]
	v_mfma_f32_16x16x32_bf16 v[26:29], v[168:171], v[184:187], v[26:29]
	v_mfma_f32_16x16x32_bf16 v[14:17], v[160:163], v[192:195], v[14:17]
	v_mfma_f32_16x16x32_bf16 v[10:13], v[168:171], v[192:195], v[10:13]
	v_mfma_f32_16x16x32_bf16 v[6:9], v[160:163], v[208:211], v[6:9]
	v_mfma_f32_16x16x32_bf16 v[2:5], v[168:171], v[208:211], v[2:5]
	s_barrier
	s_add_i32 s2, 0, 0x18000
	s_add_i32 s3, 0, 0x1c000
	ds_read_b128 v[140:143], v136 offset:32768
	ds_read_b128 v[144:147], v136 offset:33792
	ds_read_b128 v[148:151], v136 offset:34816
	ds_read_b128 v[152:155], v136 offset:35840
	ds_read_b128 v[156:159], v136 offset:49152
	ds_read_b128 v[160:163], v136 offset:50176
	ds_read_b128 v[164:167], v136 offset:51200
	ds_read_b128 v[168:171], v136 offset:52224
	s_add_u32 s0, s20, 0x160000
	s_addc_u32 s1, s21, 0
	s_mov_b32 m0, s27
	ds_read_b128 v[172:175], v139 offset:32768
	ds_read_b128 v[176:179], v139 offset:33792
	ds_read_b128 v[180:183], v139 offset:34816
	ds_read_b128 v[184:187], v139 offset:35840
	ds_read_b128 v[188:191], v139 offset:36864
	ds_read_b128 v[192:195], v139 offset:37888
	ds_read_b128 v[196:199], v139 offset:38912
	ds_read_b128 v[208:211], v139 offset:39936
	global_load_lds_dwordx4 v202, s[0:1]
	s_mov_b32 m0, s28
	s_nop 0
	global_load_lds_dwordx4 v130, s[0:1]
	s_waitcnt vmcnt(8)
	s_waitcnt lgkmcnt(0)
	s_barrier
	v_mfma_f32_16x16x32_bf16 v[126:129], v[140:143], v[172:175], v[126:129]
	v_mfma_f32_16x16x32_bf16 v[122:125], v[148:151], v[172:175], v[122:125]
	v_mfma_f32_16x16x32_bf16 v[118:121], v[140:143], v[180:183], v[118:121]
	v_mfma_f32_16x16x32_bf16 v[114:117], v[148:151], v[180:183], v[114:117]
	v_mfma_f32_16x16x32_bf16 v[106:109], v[140:143], v[188:191], v[106:109]
	v_mfma_f32_16x16x32_bf16 v[98:101], v[148:151], v[188:191], v[98:101]
	v_mfma_f32_16x16x32_bf16 v[90:93], v[140:143], v[196:199], v[90:93]
	v_mfma_f32_16x16x32_bf16 v[82:85], v[148:151], v[196:199], v[82:85]
	v_mfma_f32_16x16x32_bf16 v[126:129], v[144:147], v[176:179], v[126:129]
	v_mfma_f32_16x16x32_bf16 v[122:125], v[152:155], v[176:179], v[122:125]
	v_mfma_f32_16x16x32_bf16 v[118:121], v[144:147], v[184:187], v[118:121]
	v_mfma_f32_16x16x32_bf16 v[114:117], v[152:155], v[184:187], v[114:117]
	v_mfma_f32_16x16x32_bf16 v[106:109], v[144:147], v[192:195], v[106:109]
	v_mfma_f32_16x16x32_bf16 v[98:101], v[152:155], v[192:195], v[98:101]
	v_mfma_f32_16x16x32_bf16 v[90:93], v[144:147], v[208:211], v[90:93]
	v_mfma_f32_16x16x32_bf16 v[82:85], v[152:155], v[208:211], v[82:85]
	v_mfma_f32_16x16x32_bf16 v[110:113], v[156:159], v[172:175], v[110:113]
	v_mfma_f32_16x16x32_bf16 v[102:105], v[164:167], v[172:175], v[102:105]
	v_mfma_f32_16x16x32_bf16 v[94:97], v[156:159], v[180:183], v[94:97]
	v_mfma_f32_16x16x32_bf16 v[86:89], v[164:167], v[180:183], v[86:89]
	v_mfma_f32_16x16x32_bf16 v[78:81], v[156:159], v[188:191], v[78:81]
	v_mfma_f32_16x16x32_bf16 v[74:77], v[164:167], v[188:191], v[74:77]
	v_mfma_f32_16x16x32_bf16 v[70:73], v[156:159], v[196:199], v[70:73]
	v_mfma_f32_16x16x32_bf16 v[66:69], v[164:167], v[196:199], v[66:69]
	v_mfma_f32_16x16x32_bf16 v[110:113], v[160:163], v[176:179], v[110:113]
	v_mfma_f32_16x16x32_bf16 v[102:105], v[168:171], v[176:179], v[102:105]
	v_mfma_f32_16x16x32_bf16 v[94:97], v[160:163], v[184:187], v[94:97]
	v_mfma_f32_16x16x32_bf16 v[86:89], v[168:171], v[184:187], v[86:89]
	v_mfma_f32_16x16x32_bf16 v[78:81], v[160:163], v[192:195], v[78:81]
	v_mfma_f32_16x16x32_bf16 v[74:77], v[168:171], v[192:195], v[74:77]
	v_mfma_f32_16x16x32_bf16 v[70:73], v[160:163], v[208:211], v[70:73]
	v_mfma_f32_16x16x32_bf16 v[66:69], v[168:171], v[208:211], v[66:69]
	s_barrier
	s_add_i32 s0, s2, s24
	s_add_u32 s100, s18, 0x80
	s_addc_u32 s101, s19, 0
	s_mov_b32 m0, s0
	ds_read_b128 v[172:175], v139 offset:49152
	ds_read_b128 v[176:179], v139 offset:50176
	ds_read_b128 v[180:183], v139 offset:51200
	ds_read_b128 v[184:187], v139 offset:52224
	ds_read_b128 v[188:191], v139 offset:53248
	ds_read_b128 v[192:195], v139 offset:54272
	ds_read_b128 v[196:199], v139 offset:55296
	ds_read_b128 v[208:211], v139 offset:56320
	global_load_lds_dwordx4 v202, s[100:101]
	s_add_i32 m0, s0, 0x2000
	s_add_u32 s100, s18, 0x80
	s_addc_u32 s101, s19, 0
	s_add_u32 s0, s18, 0x160080
	s_addc_u32 s1, s19, 0
	s_add_i32 s2, s3, s24
	global_load_lds_dwordx4 v130, s[100:101]
	s_mov_b32 m0, s2
	s_nop 0
	global_load_lds_dwordx4 v202, s[0:1]
	s_add_i32 m0, s2, 0x2000
	s_nop 0
	global_load_lds_dwordx4 v130, s[0:1]
	s_add_u32 s100, s20, 0x80
	s_addc_u32 s101, s21, 0
	s_mov_b32 m0, s29
	s_nop 0
	global_load_lds_dwordx4 v202, s[100:101]
	s_add_u32 s100, s20, 0x80
	s_addc_u32 s101, s21, 0
	s_mov_b32 m0, s30
	s_nop 0
	global_load_lds_dwordx4 v130, s[100:101]
	s_waitcnt vmcnt(8)
	s_waitcnt lgkmcnt(0)
	s_barrier
	v_mfma_f32_16x16x32_bf16 v[62:65], v[140:143], v[172:175], v[62:65]
	v_mfma_f32_16x16x32_bf16 v[58:61], v[148:151], v[172:175], v[58:61]
	v_mfma_f32_16x16x32_bf16 v[54:57], v[140:143], v[180:183], v[54:57]
	v_mfma_f32_16x16x32_bf16 v[50:53], v[148:151], v[180:183], v[50:53]
	v_mfma_f32_16x16x32_bf16 v[38:41], v[140:143], v[188:191], v[38:41]
	v_mfma_f32_16x16x32_bf16 v[34:37], v[148:151], v[188:191], v[34:37]
	v_mfma_f32_16x16x32_bf16 v[22:25], v[140:143], v[196:199], v[22:25]
	v_mfma_f32_16x16x32_bf16 v[18:21], v[148:151], v[196:199], v[18:21]
	v_mfma_f32_16x16x32_bf16 v[62:65], v[144:147], v[176:179], v[62:65]
	v_mfma_f32_16x16x32_bf16 v[58:61], v[152:155], v[176:179], v[58:61]
	v_mfma_f32_16x16x32_bf16 v[54:57], v[144:147], v[184:187], v[54:57]
	v_mfma_f32_16x16x32_bf16 v[50:53], v[152:155], v[184:187], v[50:53]
	v_mfma_f32_16x16x32_bf16 v[38:41], v[144:147], v[192:195], v[38:41]
	v_mfma_f32_16x16x32_bf16 v[34:37], v[152:155], v[192:195], v[34:37]
	v_mfma_f32_16x16x32_bf16 v[22:25], v[144:147], v[208:211], v[22:25]
	v_mfma_f32_16x16x32_bf16 v[18:21], v[152:155], v[208:211], v[18:21]
	v_mfma_f32_16x16x32_bf16 v[46:49], v[156:159], v[172:175], v[46:49]
	v_mfma_f32_16x16x32_bf16 v[42:45], v[164:167], v[172:175], v[42:45]
	v_mfma_f32_16x16x32_bf16 v[30:33], v[156:159], v[180:183], v[30:33]
	v_mfma_f32_16x16x32_bf16 v[26:29], v[164:167], v[180:183], v[26:29]
	v_mfma_f32_16x16x32_bf16 v[14:17], v[156:159], v[188:191], v[14:17]
	v_mfma_f32_16x16x32_bf16 v[10:13], v[164:167], v[188:191], v[10:13]
	v_mfma_f32_16x16x32_bf16 v[6:9], v[156:159], v[196:199], v[6:9]
	v_mfma_f32_16x16x32_bf16 v[2:5], v[164:167], v[196:199], v[2:5]
	v_mfma_f32_16x16x32_bf16 v[46:49], v[160:163], v[176:179], v[46:49]
	v_mfma_f32_16x16x32_bf16 v[42:45], v[168:171], v[176:179], v[42:45]
	v_mfma_f32_16x16x32_bf16 v[30:33], v[160:163], v[184:187], v[30:33]
	v_mfma_f32_16x16x32_bf16 v[26:29], v[168:171], v[184:187], v[26:29]
	v_mfma_f32_16x16x32_bf16 v[14:17], v[160:163], v[192:195], v[14:17]
	v_mfma_f32_16x16x32_bf16 v[10:13], v[168:171], v[192:195], v[10:13]
	v_mfma_f32_16x16x32_bf16 v[6:9], v[160:163], v[208:211], v[6:9]
	v_mfma_f32_16x16x32_bf16 v[2:5], v[168:171], v[208:211], v[2:5]
	s_barrier
	s_add_i32 s59, s59, 2
	s_add_u32 s49, s49, 0x100
	s_addc_u32 s58, s58, 0
	s_cmp_gt_u32 s59, 5
	s_mov_b64 s[2:3], s[4:5]
	s_cbranch_scc0 .LBB0_990
	s_and_b64 vcc, exec, s[10:11]
	s_cbranch_vccz .LBB0_993
	s_barrier

.LBB0_1115:
	s_add_u32 s0, s22, 0xfff80080
	s_addc_u32 s1, s23, -1
	s_add_i32 s33, 0, 0x10000
	s_cmp_eq_u32 s58, 28
	s_cselect_b32 s5, s17, s1
	s_cselect_b32 s4, s39, s0
	s_cselect_b32 s3, s15, s49
	s_cselect_b32 s2, s40, s41
	s_add_i32 s55, 0, 0x14000
	ds_read_b128 v[148:151], v145
	ds_read_b128 v[152:155], v145 offset:1024
	ds_read_b128 v[156:159], v145 offset:2048
	ds_read_b128 v[160:163], v145 offset:3072
	ds_read_b128 v[164:167], v145 offset:16384
	ds_read_b128 v[168:171], v145 offset:17408
	ds_read_b128 v[172:175], v145 offset:18432
	ds_read_b128 v[176:179], v145 offset:19456
	s_add_i32 m0, s27, 0xc000
	ds_read_b128 v[180:183], v147
	ds_read_b128 v[184:187], v147 offset:1024
	ds_read_b128 v[188:191], v147 offset:2048
	ds_read_b128 v[192:195], v147 offset:3072
	ds_read_b128 v[196:199], v147 offset:4096
	ds_read_b128 v[208:211], v147 offset:5120
	ds_read_b128 v[212:215], v147 offset:6144
	ds_read_b128 v[216:219], v147 offset:7168
	global_load_lds_dwordx4 v138, s[22:23]
	s_add_i32 m0, s27, 0xe000
	s_nop 0
	global_load_lds_dwordx4 v140, s[22:23]
	s_waitcnt vmcnt(8)
	s_waitcnt lgkmcnt(0)
	s_barrier
	v_mfma_f32_16x16x32_bf16 v[126:129], v[148:151], v[180:183], v[126:129]
	v_mfma_f32_16x16x32_bf16 v[122:125], v[156:159], v[180:183], v[122:125]
	v_mfma_f32_16x16x32_bf16 v[110:113], v[148:151], v[188:191], v[110:113]
	v_mfma_f32_16x16x32_bf16 v[106:109], v[156:159], v[188:191], v[106:109]
	v_mfma_f32_16x16x32_bf16 v[94:97], v[148:151], v[196:199], v[94:97]
	v_mfma_f32_16x16x32_bf16 v[90:93], v[156:159], v[196:199], v[90:93]
	v_mfma_f32_16x16x32_bf16 v[78:81], v[148:151], v[212:215], v[78:81]
	v_mfma_f32_16x16x32_bf16 v[74:77], v[156:159], v[212:215], v[74:77]
	v_mfma_f32_16x16x32_bf16 v[126:129], v[152:155], v[184:187], v[126:129]
	v_mfma_f32_16x16x32_bf16 v[122:125], v[160:163], v[184:187], v[122:125]
	v_mfma_f32_16x16x32_bf16 v[110:113], v[152:155], v[192:195], v[110:113]
	v_mfma_f32_16x16x32_bf16 v[106:109], v[160:163], v[192:195], v[106:109]
	v_mfma_f32_16x16x32_bf16 v[94:97], v[152:155], v[208:211], v[94:97]
	v_mfma_f32_16x16x32_bf16 v[90:93], v[160:163], v[208:211], v[90:93]
	v_mfma_f32_16x16x32_bf16 v[78:81], v[152:155], v[216:219], v[78:81]
	v_mfma_f32_16x16x32_bf16 v[74:77], v[160:163], v[216:219], v[74:77]
	v_mfma_f32_16x16x32_bf16 v[118:121], v[164:167], v[180:183], v[118:121]
	v_mfma_f32_16x16x32_bf16 v[114:117], v[172:175], v[180:183], v[114:117]
	v_mfma_f32_16x16x32_bf16 v[102:105], v[164:167], v[188:191], v[102:105]
	v_mfma_f32_16x16x32_bf16 v[98:101], v[172:175], v[188:191], v[98:101]
	v_mfma_f32_16x16x32_bf16 v[86:89], v[164:167], v[196:199], v[86:89]
	v_mfma_f32_16x16x32_bf16 v[82:85], v[172:175], v[196:199], v[82:85]
	v_mfma_f32_16x16x32_bf16 v[70:73], v[164:167], v[212:215], v[70:73]
	v_mfma_f32_16x16x32_bf16 v[66:69], v[172:175], v[212:215], v[66:69]
	v_mfma_f32_16x16x32_bf16 v[118:121], v[168:171], v[184:187], v[118:121]
	v_mfma_f32_16x16x32_bf16 v[114:117], v[176:179], v[184:187], v[114:117]
	v_mfma_f32_16x16x32_bf16 v[102:105], v[168:171], v[192:195], v[102:105]
	v_mfma_f32_16x16x32_bf16 v[98:101], v[176:179], v[192:195], v[98:101]
	v_mfma_f32_16x16x32_bf16 v[86:89], v[168:171], v[208:211], v[86:89]
	v_mfma_f32_16x16x32_bf16 v[82:85], v[176:179], v[208:211], v[82:85]
	v_mfma_f32_16x16x32_bf16 v[70:73], v[168:171], v[216:219], v[70:73]
	v_mfma_f32_16x16x32_bf16 v[66:69], v[176:179], v[216:219], v[66:69]
	s_barrier
	s_add_i32 s0, s33, s26
	s_mov_b32 m0, s0
	ds_read_b128 v[180:183], v147 offset:16384
	ds_read_b128 v[184:187], v147 offset:17408
	ds_read_b128 v[188:191], v147 offset:18432
	ds_read_b128 v[192:195], v147 offset:19456
	ds_read_b128 v[196:199], v147 offset:20480
	ds_read_b128 v[208:211], v147 offset:21504
	ds_read_b128 v[212:215], v147 offset:22528
	ds_read_b128 v[216:219], v147 offset:23552
	global_load_lds_dwordx4 v134, s[2:3]
	s_add_i32 m0, s0, 0x2000
	s_add_u32 s0, s2, 0x80000
	s_addc_u32 s1, s3, 0
	s_add_i32 s33, s55, s26
	global_load_lds_dwordx4 v130, s[2:3]
	s_mov_b32 m0, s33
	s_nop 0
	global_load_lds_dwordx4 v134, s[0:1]
	s_add_i32 m0, s33, 0x2000
	s_nop 0
	global_load_lds_dwordx4 v130, s[0:1]
	s_mov_b32 m0, s27
	s_nop 0
	global_load_lds_dwordx4 v136, s[4:5]
	s_mov_b32 m0, s28
	s_nop 0
	global_load_lds_dwordx4 v132, s[4:5]
	s_waitcnt vmcnt(8)
	s_waitcnt lgkmcnt(0)
	s_barrier
	v_mfma_f32_16x16x32_bf16 v[62:65], v[148:151], v[180:183], v[62:65]
	v_mfma_f32_16x16x32_bf16 v[58:61], v[156:159], v[180:183], v[58:61]
	v_mfma_f32_16x16x32_bf16 v[46:49], v[148:151], v[188:191], v[46:49]
	v_mfma_f32_16x16x32_bf16 v[42:45], v[156:159], v[188:191], v[42:45]
	v_mfma_f32_16x16x32_bf16 v[30:33], v[148:151], v[196:199], v[30:33]
	v_mfma_f32_16x16x32_bf16 v[26:29], v[156:159], v[196:199], v[26:29]
	v_mfma_f32_16x16x32_bf16 v[14:17], v[148:151], v[212:215], v[14:17]
	v_mfma_f32_16x16x32_bf16 v[10:13], v[156:159], v[212:215], v[10:13]
	v_mfma_f32_16x16x32_bf16 v[62:65], v[152:155], v[184:187], v[62:65]
	v_mfma_f32_16x16x32_bf16 v[58:61], v[160:163], v[184:187], v[58:61]
	v_mfma_f32_16x16x32_bf16 v[46:49], v[152:155], v[192:195], v[46:49]
	v_mfma_f32_16x16x32_bf16 v[42:45], v[160:163], v[192:195], v[42:45]
	v_mfma_f32_16x16x32_bf16 v[30:33], v[152:155], v[208:211], v[30:33]
	v_mfma_f32_16x16x32_bf16 v[26:29], v[160:163], v[208:211], v[26:29]
	v_mfma_f32_16x16x32_bf16 v[14:17], v[152:155], v[216:219], v[14:17]
	v_mfma_f32_16x16x32_bf16 v[10:13], v[160:163], v[216:219], v[10:13]
	v_mfma_f32_16x16x32_bf16 v[54:57], v[164:167], v[180:183], v[54:57]
	v_mfma_f32_16x16x32_bf16 v[50:53], v[172:175], v[180:183], v[50:53]
	v_mfma_f32_16x16x32_bf16 v[38:41], v[164:167], v[188:191], v[38:41]
	v_mfma_f32_16x16x32_bf16 v[34:37], v[172:175], v[188:191], v[34:37]
	v_mfma_f32_16x16x32_bf16 v[22:25], v[164:167], v[196:199], v[22:25]
	v_mfma_f32_16x16x32_bf16 v[18:21], v[172:175], v[196:199], v[18:21]
	v_mfma_f32_16x16x32_bf16 v[6:9], v[164:167], v[212:215], v[6:9]
	v_mfma_f32_16x16x32_bf16 v[2:5], v[172:175], v[212:215], v[2:5]
	v_mfma_f32_16x16x32_bf16 v[54:57], v[168:171], v[184:187], v[54:57]
	v_mfma_f32_16x16x32_bf16 v[50:53], v[176:179], v[184:187], v[50:53]
	v_mfma_f32_16x16x32_bf16 v[38:41], v[168:171], v[192:195], v[38:41]
	v_mfma_f32_16x16x32_bf16 v[34:37], v[176:179], v[192:195], v[34:37]
	v_mfma_f32_16x16x32_bf16 v[22:25], v[168:171], v[208:211], v[22:25]
	v_mfma_f32_16x16x32_bf16 v[18:21], v[176:179], v[208:211], v[18:21]
	v_mfma_f32_16x16x32_bf16 v[6:9], v[168:171], v[216:219], v[6:9]
	v_mfma_f32_16x16x32_bf16 v[2:5], v[176:179], v[216:219], v[2:5]
	s_barrier
	s_add_i32 s33, 0, 0x18000
	s_add_i32 s55, 0, 0x1c000
	ds_read_b128 v[148:151], v145 offset:32768
	ds_read_b128 v[152:155], v145 offset:33792
	ds_read_b128 v[156:159], v145 offset:34816
	ds_read_b128 v[160:163], v145 offset:35840
	ds_read_b128 v[164:167], v145 offset:49152
	ds_read_b128 v[168:171], v145 offset:50176
	ds_read_b128 v[172:175], v145 offset:51200
	ds_read_b128 v[176:179], v145 offset:52224
	s_add_u32 s0, s4, 0x80000
	s_addc_u32 s1, s5, 0
	s_mov_b32 m0, s29
	ds_read_b128 v[180:183], v147 offset:32768
	ds_read_b128 v[184:187], v147 offset:33792
	ds_read_b128 v[188:191], v147 offset:34816
	ds_read_b128 v[192:195], v147 offset:35840
	ds_read_b128 v[196:199], v147 offset:36864
	ds_read_b128 v[208:211], v147 offset:37888
	ds_read_b128 v[212:215], v147 offset:38912
	ds_read_b128 v[216:219], v147 offset:39936
	global_load_lds_dwordx4 v136, s[0:1]
	s_mov_b32 m0, s30
	s_nop 0
	global_load_lds_dwordx4 v132, s[0:1]
	s_waitcnt vmcnt(8)
	s_waitcnt lgkmcnt(0)
	s_barrier
	v_mfma_f32_16x16x32_bf16 v[126:129], v[148:151], v[180:183], v[126:129]
	v_mfma_f32_16x16x32_bf16 v[122:125], v[156:159], v[180:183], v[122:125]
	v_mfma_f32_16x16x32_bf16 v[110:113], v[148:151], v[188:191], v[110:113]
	v_mfma_f32_16x16x32_bf16 v[106:109], v[156:159], v[188:191], v[106:109]
	v_mfma_f32_16x16x32_bf16 v[94:97], v[148:151], v[196:199], v[94:97]
	v_mfma_f32_16x16x32_bf16 v[90:93], v[156:159], v[196:199], v[90:93]
	v_mfma_f32_16x16x32_bf16 v[78:81], v[148:151], v[212:215], v[78:81]
	v_mfma_f32_16x16x32_bf16 v[74:77], v[156:159], v[212:215], v[74:77]
	v_mfma_f32_16x16x32_bf16 v[126:129], v[152:155], v[184:187], v[126:129]
	v_mfma_f32_16x16x32_bf16 v[122:125], v[160:163], v[184:187], v[122:125]
	v_mfma_f32_16x16x32_bf16 v[110:113], v[152:155], v[192:195], v[110:113]
	v_mfma_f32_16x16x32_bf16 v[106:109], v[160:163], v[192:195], v[106:109]
	v_mfma_f32_16x16x32_bf16 v[94:97], v[152:155], v[208:211], v[94:97]
	v_mfma_f32_16x16x32_bf16 v[90:93], v[160:163], v[208:211], v[90:93]
	v_mfma_f32_16x16x32_bf16 v[78:81], v[152:155], v[216:219], v[78:81]
	v_mfma_f32_16x16x32_bf16 v[74:77], v[160:163], v[216:219], v[74:77]
	v_mfma_f32_16x16x32_bf16 v[118:121], v[164:167], v[180:183], v[118:121]
	v_mfma_f32_16x16x32_bf16 v[114:117], v[172:175], v[180:183], v[114:117]
	v_mfma_f32_16x16x32_bf16 v[102:105], v[164:167], v[188:191], v[102:105]
	v_mfma_f32_16x16x32_bf16 v[98:101], v[172:175], v[188:191], v[98:101]
	v_mfma_f32_16x16x32_bf16 v[86:89], v[164:167], v[196:199], v[86:89]
	v_mfma_f32_16x16x32_bf16 v[82:85], v[172:175], v[196:199], v[82:85]
	v_mfma_f32_16x16x32_bf16 v[70:73], v[164:167], v[212:215], v[70:73]
	v_mfma_f32_16x16x32_bf16 v[66:69], v[172:175], v[212:215], v[66:69]
	v_mfma_f32_16x16x32_bf16 v[118:121], v[168:171], v[184:187], v[118:121]
	v_mfma_f32_16x16x32_bf16 v[114:117], v[176:179], v[184:187], v[114:117]
	v_mfma_f32_16x16x32_bf16 v[102:105], v[168:171], v[192:195], v[102:105]
	v_mfma_f32_16x16x32_bf16 v[98:101], v[176:179], v[192:195], v[98:101]
	v_mfma_f32_16x16x32_bf16 v[86:89], v[168:171], v[208:211], v[86:89]
	v_mfma_f32_16x16x32_bf16 v[82:85], v[176:179], v[208:211], v[82:85]
	v_mfma_f32_16x16x32_bf16 v[70:73], v[168:171], v[216:219], v[70:73]
	v_mfma_f32_16x16x32_bf16 v[66:69], v[176:179], v[216:219], v[66:69]
	s_barrier
	s_add_i32 s0, s33, s26
	s_add_u32 s100, s2, 0x80
	s_addc_u32 s101, s3, 0
	s_mov_b32 m0, s0
	ds_read_b128 v[180:183], v147 offset:49152
	ds_read_b128 v[184:187], v147 offset:50176
	ds_read_b128 v[188:191], v147 offset:51200
	ds_read_b128 v[192:195], v147 offset:52224
	ds_read_b128 v[196:199], v147 offset:53248
	ds_read_b128 v[208:211], v147 offset:54272
	ds_read_b128 v[212:215], v147 offset:55296
	ds_read_b128 v[216:219], v147 offset:56320
	global_load_lds_dwordx4 v134, s[100:101]
	s_add_i32 m0, s0, 0x2000
	s_add_u32 s100, s2, 0x80
	s_addc_u32 s101, s3, 0
	s_add_u32 s0, s2, 0x80080
	s_addc_u32 s1, s3, 0
	s_add_i32 s2, s55, s26
	global_load_lds_dwordx4 v130, s[100:101]
	s_mov_b32 m0, s2
	s_nop 0
	global_load_lds_dwordx4 v134, s[0:1]
	s_add_i32 m0, s2, 0x2000
	s_nop 0
	global_load_lds_dwordx4 v130, s[0:1]
	s_add_u32 s100, s4, 0x80
	s_addc_u32 s101, s5, 0
	s_mov_b32 m0, s34
	s_nop 0
	global_load_lds_dwordx4 v136, s[100:101]
	s_add_u32 s100, s4, 0x80
	s_addc_u32 s101, s5, 0
	s_mov_b32 m0, s35
	s_nop 0
	global_load_lds_dwordx4 v132, s[100:101]
	s_waitcnt vmcnt(8)
	s_waitcnt lgkmcnt(0)
	s_barrier
	v_mfma_f32_16x16x32_bf16 v[62:65], v[148:151], v[180:183], v[62:65]
	v_mfma_f32_16x16x32_bf16 v[58:61], v[156:159], v[180:183], v[58:61]
	v_mfma_f32_16x16x32_bf16 v[46:49], v[148:151], v[188:191], v[46:49]
	v_mfma_f32_16x16x32_bf16 v[42:45], v[156:159], v[188:191], v[42:45]
	v_mfma_f32_16x16x32_bf16 v[30:33], v[148:151], v[196:199], v[30:33]
	v_mfma_f32_16x16x32_bf16 v[26:29], v[156:159], v[196:199], v[26:29]
	v_mfma_f32_16x16x32_bf16 v[14:17], v[148:151], v[212:215], v[14:17]
	v_mfma_f32_16x16x32_bf16 v[10:13], v[156:159], v[212:215], v[10:13]
	v_mfma_f32_16x16x32_bf16 v[62:65], v[152:155], v[184:187], v[62:65]
	v_mfma_f32_16x16x32_bf16 v[58:61], v[160:163], v[184:187], v[58:61]
	v_mfma_f32_16x16x32_bf16 v[46:49], v[152:155], v[192:195], v[46:49]
	v_mfma_f32_16x16x32_bf16 v[42:45], v[160:163], v[192:195], v[42:45]
	v_mfma_f32_16x16x32_bf16 v[30:33], v[152:155], v[208:211], v[30:33]
	v_mfma_f32_16x16x32_bf16 v[26:29], v[160:163], v[208:211], v[26:29]
	v_mfma_f32_16x16x32_bf16 v[14:17], v[152:155], v[216:219], v[14:17]
	v_mfma_f32_16x16x32_bf16 v[10:13], v[160:163], v[216:219], v[10:13]
	v_mfma_f32_16x16x32_bf16 v[54:57], v[164:167], v[180:183], v[54:57]
	v_mfma_f32_16x16x32_bf16 v[50:53], v[172:175], v[180:183], v[50:53]
	v_mfma_f32_16x16x32_bf16 v[38:41], v[164:167], v[188:191], v[38:41]
	v_mfma_f32_16x16x32_bf16 v[34:37], v[172:175], v[188:191], v[34:37]
	v_mfma_f32_16x16x32_bf16 v[22:25], v[164:167], v[196:199], v[22:25]
	v_mfma_f32_16x16x32_bf16 v[18:21], v[172:175], v[196:199], v[18:21]
	v_mfma_f32_16x16x32_bf16 v[6:9], v[164:167], v[212:215], v[6:9]
	v_mfma_f32_16x16x32_bf16 v[2:5], v[172:175], v[212:215], v[2:5]
	v_mfma_f32_16x16x32_bf16 v[54:57], v[168:171], v[184:187], v[54:57]
	v_mfma_f32_16x16x32_bf16 v[50:53], v[176:179], v[184:187], v[50:53]
	v_mfma_f32_16x16x32_bf16 v[38:41], v[168:171], v[192:195], v[38:41]
	v_mfma_f32_16x16x32_bf16 v[34:37], v[176:179], v[192:195], v[34:37]
	v_mfma_f32_16x16x32_bf16 v[22:25], v[168:171], v[208:211], v[22:25]
	v_mfma_f32_16x16x32_bf16 v[18:21], v[176:179], v[208:211], v[18:21]
	v_mfma_f32_16x16x32_bf16 v[6:9], v[168:171], v[216:219], v[6:9]
	v_mfma_f32_16x16x32_bf16 v[2:5], v[176:179], v[216:219], v[2:5]
	s_barrier
	s_add_i32 s58, s58, 2
	s_add_u32 s22, s22, 0x100
	s_addc_u32 s23, s23, 0
	s_add_u32 s41, s41, 0x100
	s_addc_u32 s49, s49, 0
	s_cmp_gt_u32 s58, 29
	s_cbranch_scc0 .LBB0_1115
	s_and_b64 vcc, exec, s[10:11]
	s_cbranch_vccz .LBB0_1118
	s_barrier

.LBB0_1242:
	s_add_u32 s28, s18, s4
	s_addc_u32 s29, s19, s5
	s_add_u32 s24, s28, 0x100
	s_addc_u32 s25, s29, 0
	s_and_b64 s[0:1], s[2:3], exec
	s_cselect_b32 s25, s49, s25
	s_cselect_b32 s24, s58, s24
	s_add_u32 s0, s20, s4
	s_addc_u32 s1, s21, s5
	s_add_u32 s4, s0, 0x100
	s_addc_u32 s5, s1, 0
	s_add_i32 s55, 0, 0x10000
	s_and_b64 s[0:1], s[2:3], exec
	s_cselect_b32 s27, s59, s5
	s_cselect_b32 s26, s60, s4
	s_add_i32 s0, 0, 0x14000
	s_add_u32 s30, s28, 0x20080
	s_addc_u32 s31, s29, 0
	s_add_i32 s57, s55, s36
	s_add_i32 m0, s37, 0xc000
	s_add_i32 s1, s37, 0xe000
	s_add_i32 s63, s57, 0x2000
	v_add_u32_e32 v138, s55, v141
	s_add_u32 s28, s26, 0x10000
	ds_read_b128 v[144:147], v138
	ds_read_b128 v[148:151], v138 offset:1024
	ds_read_b128 v[152:155], v138 offset:2048
	ds_read_b128 v[156:159], v138 offset:3072
	v_add_u32_e32 v138, s0, v141
	s_addc_u32 s29, s27, 0
	s_add_i32 s33, s0, s36
	ds_read_b128 v[160:163], v138
	ds_read_b128 v[164:167], v138 offset:1024
	ds_read_b128 v[168:171], v138 offset:2048
	ds_read_b128 v[172:175], v138 offset:3072
	s_add_i32 s56, s33, 0x2000
	s_add_i32 vcc_lo, 0, 0x18000
	s_add_i32 vcc_hi, 0, 0x1c000
	s_add_u32 s4, s24, 0x20000
	s_addc_u32 s5, s25, 0
	s_add_i32 s61, vcc_lo, s36
	s_add_i32 s62, s61, 0x2000
	s_add_u32 s2, s26, 0x10080
	s_addc_u32 s3, s27, 0
	s_add_i32 s55, vcc_hi, s36
	s_add_i32 s0, s55, 0x2000
	ds_read_b128 v[176:179], v142
	ds_read_b128 v[180:183], v142 offset:1024
	ds_read_b128 v[184:187], v142 offset:2048
	ds_read_b128 v[188:191], v142 offset:3072
	ds_read_b128 v[192:195], v142 offset:4096
	ds_read_b128 v[196:199], v142 offset:5120
	ds_read_b128 v[208:211], v142 offset:6144
	ds_read_b128 v[212:215], v142 offset:7168
	global_load_lds_dwordx4 v134, s[30:31]
	s_mov_b32 m0, s1
	s_nop 0
	global_load_lds_dwordx4 v132, s[30:31]
	s_waitcnt vmcnt(8)
	s_waitcnt lgkmcnt(0)
	s_barrier
	v_mfma_f32_16x16x32_bf16 v[126:129], v[144:147], v[176:179], v[126:129]
	v_mfma_f32_16x16x32_bf16 v[122:125], v[152:155], v[176:179], v[122:125]
	v_mfma_f32_16x16x32_bf16 v[118:121], v[144:147], v[184:187], v[118:121]
	v_mfma_f32_16x16x32_bf16 v[110:113], v[152:155], v[184:187], v[110:113]
	v_mfma_f32_16x16x32_bf16 v[102:105], v[144:147], v[192:195], v[102:105]
	v_mfma_f32_16x16x32_bf16 v[94:97], v[152:155], v[192:195], v[94:97]
	v_mfma_f32_16x16x32_bf16 v[86:89], v[144:147], v[208:211], v[86:89]
	v_mfma_f32_16x16x32_bf16 v[78:81], v[152:155], v[208:211], v[78:81]
	v_mfma_f32_16x16x32_bf16 v[126:129], v[148:151], v[180:183], v[126:129]
	v_mfma_f32_16x16x32_bf16 v[122:125], v[156:159], v[180:183], v[122:125]
	v_mfma_f32_16x16x32_bf16 v[118:121], v[148:151], v[188:191], v[118:121]
	v_mfma_f32_16x16x32_bf16 v[110:113], v[156:159], v[188:191], v[110:113]
	v_mfma_f32_16x16x32_bf16 v[102:105], v[148:151], v[196:199], v[102:105]
	v_mfma_f32_16x16x32_bf16 v[94:97], v[156:159], v[196:199], v[94:97]
	v_mfma_f32_16x16x32_bf16 v[86:89], v[148:151], v[212:215], v[86:89]
	v_mfma_f32_16x16x32_bf16 v[78:81], v[156:159], v[212:215], v[78:81]
	v_mfma_f32_16x16x32_bf16 v[114:117], v[160:163], v[176:179], v[114:117]
	v_mfma_f32_16x16x32_bf16 v[106:109], v[168:171], v[176:179], v[106:109]
	v_mfma_f32_16x16x32_bf16 v[98:101], v[160:163], v[184:187], v[98:101]
	v_mfma_f32_16x16x32_bf16 v[90:93], v[168:171], v[184:187], v[90:93]
	v_mfma_f32_16x16x32_bf16 v[82:85], v[160:163], v[192:195], v[82:85]
	v_mfma_f32_16x16x32_bf16 v[74:77], v[168:171], v[192:195], v[74:77]
	v_mfma_f32_16x16x32_bf16 v[70:73], v[160:163], v[208:211], v[70:73]
	v_mfma_f32_16x16x32_bf16 v[66:69], v[168:171], v[208:211], v[66:69]
	v_mfma_f32_16x16x32_bf16 v[114:117], v[164:167], v[180:183], v[114:117]
	v_mfma_f32_16x16x32_bf16 v[106:109], v[172:175], v[180:183], v[106:109]
	v_mfma_f32_16x16x32_bf16 v[98:101], v[164:167], v[188:191], v[98:101]
	v_mfma_f32_16x16x32_bf16 v[90:93], v[172:175], v[188:191], v[90:93]
	v_mfma_f32_16x16x32_bf16 v[82:85], v[164:167], v[196:199], v[82:85]
	v_mfma_f32_16x16x32_bf16 v[74:77], v[172:175], v[196:199], v[74:77]
	v_mfma_f32_16x16x32_bf16 v[70:73], v[164:167], v[212:215], v[70:73]
	v_mfma_f32_16x16x32_bf16 v[66:69], v[172:175], v[212:215], v[66:69]
	s_barrier
	s_mov_b32 m0, s57
	ds_read_b128 v[176:179], v142 offset:16384
	ds_read_b128 v[180:183], v142 offset:17408
	ds_read_b128 v[184:187], v142 offset:18432
	ds_read_b128 v[188:191], v142 offset:19456
	ds_read_b128 v[192:195], v142 offset:20480
	ds_read_b128 v[196:199], v142 offset:21504
	ds_read_b128 v[208:211], v142 offset:22528
	ds_read_b128 v[212:215], v142 offset:23552
	global_load_lds_dwordx4 v202, s[26:27]
	s_mov_b32 m0, s63
	s_nop 0
	global_load_lds_dwordx4 v130, s[26:27]
	s_mov_b32 m0, s33
	s_nop 0
	global_load_lds_dwordx4 v202, s[28:29]
	s_mov_b32 m0, s56
	s_nop 0
	global_load_lds_dwordx4 v130, s[28:29]
	s_mov_b32 m0, s37
	s_nop 0
	global_load_lds_dwordx4 v134, s[24:25]
	s_mov_b32 m0, s38
	s_nop 0
	global_load_lds_dwordx4 v132, s[24:25]
	s_waitcnt vmcnt(8)
	s_waitcnt lgkmcnt(0)
	s_barrier
	v_mfma_f32_16x16x32_bf16 v[62:65], v[144:147], v[176:179], v[62:65]
	v_mfma_f32_16x16x32_bf16 v[58:61], v[152:155], v[176:179], v[58:61]
	v_mfma_f32_16x16x32_bf16 v[54:57], v[144:147], v[184:187], v[54:57]
	v_mfma_f32_16x16x32_bf16 v[46:49], v[152:155], v[184:187], v[46:49]
	v_mfma_f32_16x16x32_bf16 v[38:41], v[144:147], v[192:195], v[38:41]
	v_mfma_f32_16x16x32_bf16 v[30:33], v[152:155], v[192:195], v[30:33]
	v_mfma_f32_16x16x32_bf16 v[22:25], v[144:147], v[208:211], v[22:25]
	v_mfma_f32_16x16x32_bf16 v[14:17], v[152:155], v[208:211], v[14:17]
	v_mfma_f32_16x16x32_bf16 v[62:65], v[148:151], v[180:183], v[62:65]
	v_mfma_f32_16x16x32_bf16 v[58:61], v[156:159], v[180:183], v[58:61]
	v_mfma_f32_16x16x32_bf16 v[54:57], v[148:151], v[188:191], v[54:57]
	v_mfma_f32_16x16x32_bf16 v[46:49], v[156:159], v[188:191], v[46:49]
	v_mfma_f32_16x16x32_bf16 v[38:41], v[148:151], v[196:199], v[38:41]
	v_mfma_f32_16x16x32_bf16 v[30:33], v[156:159], v[196:199], v[30:33]
	v_mfma_f32_16x16x32_bf16 v[22:25], v[148:151], v[212:215], v[22:25]
	v_mfma_f32_16x16x32_bf16 v[14:17], v[156:159], v[212:215], v[14:17]
	v_mfma_f32_16x16x32_bf16 v[50:53], v[160:163], v[176:179], v[50:53]
	v_mfma_f32_16x16x32_bf16 v[42:45], v[168:171], v[176:179], v[42:45]
	v_mfma_f32_16x16x32_bf16 v[34:37], v[160:163], v[184:187], v[34:37]
	v_mfma_f32_16x16x32_bf16 v[26:29], v[168:171], v[184:187], v[26:29]
	v_mfma_f32_16x16x32_bf16 v[18:21], v[160:163], v[192:195], v[18:21]
	v_mfma_f32_16x16x32_bf16 v[10:13], v[168:171], v[192:195], v[10:13]
	v_mfma_f32_16x16x32_bf16 v[6:9], v[160:163], v[208:211], v[6:9]
	v_mfma_f32_16x16x32_bf16 v[2:5], v[168:171], v[208:211], v[2:5]
	v_mfma_f32_16x16x32_bf16 v[50:53], v[164:167], v[180:183], v[50:53]
	v_mfma_f32_16x16x32_bf16 v[42:45], v[172:175], v[180:183], v[42:45]
	v_mfma_f32_16x16x32_bf16 v[34:37], v[164:167], v[188:191], v[34:37]
	v_mfma_f32_16x16x32_bf16 v[26:29], v[172:175], v[188:191], v[26:29]
	v_mfma_f32_16x16x32_bf16 v[18:21], v[164:167], v[196:199], v[18:21]
	v_mfma_f32_16x16x32_bf16 v[10:13], v[172:175], v[196:199], v[10:13]
	v_mfma_f32_16x16x32_bf16 v[6:9], v[164:167], v[212:215], v[6:9]
	v_mfma_f32_16x16x32_bf16 v[2:5], v[172:175], v[212:215], v[2:5]
	s_barrier
	v_add_u32_e32 v143, vcc_lo, v141
	ds_read_b128 v[144:147], v143
	ds_read_b128 v[148:151], v143 offset:1024
	ds_read_b128 v[152:155], v143 offset:2048
	ds_read_b128 v[156:159], v143 offset:3072
	v_add_u32_e32 v143, vcc_hi, v141
	ds_read_b128 v[160:163], v143
	ds_read_b128 v[164:167], v143 offset:1024
	ds_read_b128 v[168:171], v143 offset:2048
	ds_read_b128 v[172:175], v143 offset:3072
	s_mov_b32 m0, s39
	ds_read_b128 v[176:179], v142 offset:32768
	ds_read_b128 v[180:183], v142 offset:33792
	ds_read_b128 v[184:187], v142 offset:34816
	ds_read_b128 v[188:191], v142 offset:35840
	ds_read_b128 v[192:195], v142 offset:36864
	ds_read_b128 v[196:199], v142 offset:37888
	ds_read_b128 v[208:211], v142 offset:38912
	ds_read_b128 v[212:215], v142 offset:39936
	global_load_lds_dwordx4 v134, s[4:5]
	s_mov_b32 m0, s40
	s_nop 0
	global_load_lds_dwordx4 v132, s[4:5]
	s_waitcnt vmcnt(8)
	s_waitcnt lgkmcnt(0)
	s_barrier
	v_mfma_f32_16x16x32_bf16 v[126:129], v[144:147], v[176:179], v[126:129]
	v_mfma_f32_16x16x32_bf16 v[122:125], v[152:155], v[176:179], v[122:125]
	v_mfma_f32_16x16x32_bf16 v[118:121], v[144:147], v[184:187], v[118:121]
	v_mfma_f32_16x16x32_bf16 v[110:113], v[152:155], v[184:187], v[110:113]
	v_mfma_f32_16x16x32_bf16 v[102:105], v[144:147], v[192:195], v[102:105]
	v_mfma_f32_16x16x32_bf16 v[94:97], v[152:155], v[192:195], v[94:97]
	v_mfma_f32_16x16x32_bf16 v[86:89], v[144:147], v[208:211], v[86:89]
	v_mfma_f32_16x16x32_bf16 v[78:81], v[152:155], v[208:211], v[78:81]
	v_mfma_f32_16x16x32_bf16 v[126:129], v[148:151], v[180:183], v[126:129]
	v_mfma_f32_16x16x32_bf16 v[122:125], v[156:159], v[180:183], v[122:125]
	v_mfma_f32_16x16x32_bf16 v[118:121], v[148:151], v[188:191], v[118:121]
	v_mfma_f32_16x16x32_bf16 v[110:113], v[156:159], v[188:191], v[110:113]
	v_mfma_f32_16x16x32_bf16 v[102:105], v[148:151], v[196:199], v[102:105]
	v_mfma_f32_16x16x32_bf16 v[94:97], v[156:159], v[196:199], v[94:97]
	v_mfma_f32_16x16x32_bf16 v[86:89], v[148:151], v[212:215], v[86:89]
	v_mfma_f32_16x16x32_bf16 v[78:81], v[156:159], v[212:215], v[78:81]
	v_mfma_f32_16x16x32_bf16 v[114:117], v[160:163], v[176:179], v[114:117]
	v_mfma_f32_16x16x32_bf16 v[106:109], v[168:171], v[176:179], v[106:109]
	v_mfma_f32_16x16x32_bf16 v[98:101], v[160:163], v[184:187], v[98:101]
	v_mfma_f32_16x16x32_bf16 v[90:93], v[168:171], v[184:187], v[90:93]
	v_mfma_f32_16x16x32_bf16 v[82:85], v[160:163], v[192:195], v[82:85]
	v_mfma_f32_16x16x32_bf16 v[74:77], v[168:171], v[192:195], v[74:77]
	v_mfma_f32_16x16x32_bf16 v[70:73], v[160:163], v[208:211], v[70:73]
	v_mfma_f32_16x16x32_bf16 v[66:69], v[168:171], v[208:211], v[66:69]
	v_mfma_f32_16x16x32_bf16 v[114:117], v[164:167], v[180:183], v[114:117]
	v_mfma_f32_16x16x32_bf16 v[106:109], v[172:175], v[180:183], v[106:109]
	v_mfma_f32_16x16x32_bf16 v[98:101], v[164:167], v[188:191], v[98:101]
	v_mfma_f32_16x16x32_bf16 v[90:93], v[172:175], v[188:191], v[90:93]
	v_mfma_f32_16x16x32_bf16 v[82:85], v[164:167], v[196:199], v[82:85]
	v_mfma_f32_16x16x32_bf16 v[74:77], v[172:175], v[196:199], v[74:77]
	v_mfma_f32_16x16x32_bf16 v[70:73], v[164:167], v[212:215], v[70:73]
	v_mfma_f32_16x16x32_bf16 v[66:69], v[172:175], v[212:215], v[66:69]
	s_barrier
	s_mov_b32 m0, s61
	s_add_u32 s100, s26, 0x80
	s_addc_u32 s101, s27, 0
	ds_read_b128 v[176:179], v142 offset:49152
	ds_read_b128 v[180:183], v142 offset:50176
	ds_read_b128 v[184:187], v142 offset:51200
	ds_read_b128 v[188:191], v142 offset:52224
	ds_read_b128 v[192:195], v142 offset:53248
	ds_read_b128 v[196:199], v142 offset:54272
	ds_read_b128 v[208:211], v142 offset:55296
	ds_read_b128 v[212:215], v142 offset:56320
	global_load_lds_dwordx4 v202, s[100:101]
	s_add_u32 s100, s26, 0x80
	s_addc_u32 s101, s27, 0
	s_mov_b32 m0, s62
	s_nop 0
	global_load_lds_dwordx4 v130, s[100:101]
	s_mov_b32 m0, s55
	s_nop 0
	global_load_lds_dwordx4 v202, s[2:3]
	s_mov_b32 m0, s0
	s_nop 0
	global_load_lds_dwordx4 v130, s[2:3]
	s_add_u32 s100, s24, 0x80
	s_addc_u32 s101, s25, 0
	s_mov_b32 m0, s41
	s_nop 0
	global_load_lds_dwordx4 v134, s[100:101]
	s_add_u32 s100, s24, 0x80
	s_addc_u32 s101, s25, 0
	s_mov_b32 m0, s86
	s_nop 0
	global_load_lds_dwordx4 v132, s[100:101]
	s_waitcnt vmcnt(8)
	s_waitcnt lgkmcnt(0)
	s_barrier
	v_mfma_f32_16x16x32_bf16 v[62:65], v[144:147], v[176:179], v[62:65]
	v_mfma_f32_16x16x32_bf16 v[58:61], v[152:155], v[176:179], v[58:61]
	v_mfma_f32_16x16x32_bf16 v[54:57], v[144:147], v[184:187], v[54:57]
	v_mfma_f32_16x16x32_bf16 v[46:49], v[152:155], v[184:187], v[46:49]
	v_mfma_f32_16x16x32_bf16 v[38:41], v[144:147], v[192:195], v[38:41]
	v_mfma_f32_16x16x32_bf16 v[30:33], v[152:155], v[192:195], v[30:33]
	v_mfma_f32_16x16x32_bf16 v[22:25], v[144:147], v[208:211], v[22:25]
	v_mfma_f32_16x16x32_bf16 v[14:17], v[152:155], v[208:211], v[14:17]
	v_mfma_f32_16x16x32_bf16 v[62:65], v[148:151], v[180:183], v[62:65]
	v_mfma_f32_16x16x32_bf16 v[58:61], v[156:159], v[180:183], v[58:61]
	v_mfma_f32_16x16x32_bf16 v[54:57], v[148:151], v[188:191], v[54:57]
	v_mfma_f32_16x16x32_bf16 v[46:49], v[156:159], v[188:191], v[46:49]
	v_mfma_f32_16x16x32_bf16 v[38:41], v[148:151], v[196:199], v[38:41]
	v_mfma_f32_16x16x32_bf16 v[30:33], v[156:159], v[196:199], v[30:33]
	v_mfma_f32_16x16x32_bf16 v[22:25], v[148:151], v[212:215], v[22:25]
	v_mfma_f32_16x16x32_bf16 v[14:17], v[156:159], v[212:215], v[14:17]
	v_mfma_f32_16x16x32_bf16 v[50:53], v[160:163], v[176:179], v[50:53]
	v_mfma_f32_16x16x32_bf16 v[42:45], v[168:171], v[176:179], v[42:45]
	v_mfma_f32_16x16x32_bf16 v[34:37], v[160:163], v[184:187], v[34:37]
	v_mfma_f32_16x16x32_bf16 v[26:29], v[168:171], v[184:187], v[26:29]
	v_mfma_f32_16x16x32_bf16 v[18:21], v[160:163], v[192:195], v[18:21]
	v_mfma_f32_16x16x32_bf16 v[10:13], v[168:171], v[192:195], v[10:13]
	v_mfma_f32_16x16x32_bf16 v[6:9], v[160:163], v[208:211], v[6:9]
	v_mfma_f32_16x16x32_bf16 v[2:5], v[168:171], v[208:211], v[2:5]
	v_mfma_f32_16x16x32_bf16 v[50:53], v[164:167], v[180:183], v[50:53]
	v_mfma_f32_16x16x32_bf16 v[42:45], v[172:175], v[180:183], v[42:45]
	v_mfma_f32_16x16x32_bf16 v[34:37], v[164:167], v[188:191], v[34:37]
	v_mfma_f32_16x16x32_bf16 v[26:29], v[172:175], v[188:191], v[26:29]
	v_mfma_f32_16x16x32_bf16 v[18:21], v[164:167], v[196:199], v[18:21]
	v_mfma_f32_16x16x32_bf16 v[10:13], v[172:175], v[196:199], v[10:13]
	v_mfma_f32_16x16x32_bf16 v[6:9], v[164:167], v[212:215], v[6:9]
	v_mfma_f32_16x16x32_bf16 v[2:5], v[172:175], v[212:215], v[2:5]
	s_barrier
	s_andn2_b64 vcc, exec, s[22:23]
	s_mov_b64 s[2:3], -1
	s_mov_b64 s[22:23], 0
	s_mov_b64 s[4:5], 0x100
	s_cbranch_vccz .LBB0_1242
	s_and_b64 vcc, exec, s[10:11]
	s_cbranch_vccz .LBB0_1245
	s_barrier

.LBB0_1363:
	s_add_u32 s0, s20, 0xfffe0080
	s_addc_u32 s1, s21, -1
	s_add_i32 s33, 0, 0x10000
	s_cmp_eq_u32 s59, 4
	s_cselect_b32 s5, s38, s1
	s_cselect_b32 s4, s39, s0
	s_cselect_b32 s3, s40, s58
	s_cselect_b32 s2, s41, s49
	s_add_i32 s55, 0, 0x14000
	ds_read_b128 v[148:151], v143
	ds_read_b128 v[152:155], v143 offset:1024
	ds_read_b128 v[156:159], v143 offset:2048
	ds_read_b128 v[160:163], v143 offset:3072
	ds_read_b128 v[164:167], v143 offset:16384
	ds_read_b128 v[168:171], v143 offset:17408
	ds_read_b128 v[172:175], v143 offset:18432
	ds_read_b128 v[176:179], v143 offset:19456
	s_add_i32 m0, s25, 0xc000
	ds_read_b128 v[180:183], v146
	ds_read_b128 v[184:187], v146 offset:1024
	ds_read_b128 v[188:191], v146 offset:2048
	ds_read_b128 v[192:195], v146 offset:3072
	ds_read_b128 v[196:199], v146 offset:4096
	ds_read_b128 v[208:211], v146 offset:5120
	ds_read_b128 v[212:215], v146 offset:6144
	ds_read_b128 v[216:219], v146 offset:7168
	global_load_lds_dwordx4 v138, s[20:21]
	s_add_i32 m0, s25, 0xe000
	s_nop 0
	global_load_lds_dwordx4 v140, s[20:21]
	s_waitcnt vmcnt(8)
	s_waitcnt lgkmcnt(0)
	s_barrier
	v_mfma_f32_16x16x32_bf16 v[126:129], v[148:151], v[180:183], v[126:129]
	v_mfma_f32_16x16x32_bf16 v[122:125], v[156:159], v[180:183], v[122:125]
	v_mfma_f32_16x16x32_bf16 v[110:113], v[148:151], v[188:191], v[110:113]
	v_mfma_f32_16x16x32_bf16 v[106:109], v[156:159], v[188:191], v[106:109]
	v_mfma_f32_16x16x32_bf16 v[94:97], v[148:151], v[196:199], v[94:97]
	v_mfma_f32_16x16x32_bf16 v[90:93], v[156:159], v[196:199], v[90:93]
	v_mfma_f32_16x16x32_bf16 v[78:81], v[148:151], v[212:215], v[78:81]
	v_mfma_f32_16x16x32_bf16 v[74:77], v[156:159], v[212:215], v[74:77]
	v_mfma_f32_16x16x32_bf16 v[126:129], v[152:155], v[184:187], v[126:129]
	v_mfma_f32_16x16x32_bf16 v[122:125], v[160:163], v[184:187], v[122:125]
	v_mfma_f32_16x16x32_bf16 v[110:113], v[152:155], v[192:195], v[110:113]
	v_mfma_f32_16x16x32_bf16 v[106:109], v[160:163], v[192:195], v[106:109]
	v_mfma_f32_16x16x32_bf16 v[94:97], v[152:155], v[208:211], v[94:97]
	v_mfma_f32_16x16x32_bf16 v[90:93], v[160:163], v[208:211], v[90:93]
	v_mfma_f32_16x16x32_bf16 v[78:81], v[152:155], v[216:219], v[78:81]
	v_mfma_f32_16x16x32_bf16 v[74:77], v[160:163], v[216:219], v[74:77]
	v_mfma_f32_16x16x32_bf16 v[118:121], v[164:167], v[180:183], v[118:121]
	v_mfma_f32_16x16x32_bf16 v[114:117], v[172:175], v[180:183], v[114:117]
	v_mfma_f32_16x16x32_bf16 v[102:105], v[164:167], v[188:191], v[102:105]
	v_mfma_f32_16x16x32_bf16 v[98:101], v[172:175], v[188:191], v[98:101]
	v_mfma_f32_16x16x32_bf16 v[86:89], v[164:167], v[196:199], v[86:89]
	v_mfma_f32_16x16x32_bf16 v[82:85], v[172:175], v[196:199], v[82:85]
	v_mfma_f32_16x16x32_bf16 v[70:73], v[164:167], v[212:215], v[70:73]
	v_mfma_f32_16x16x32_bf16 v[66:69], v[172:175], v[212:215], v[66:69]
	v_mfma_f32_16x16x32_bf16 v[118:121], v[168:171], v[184:187], v[118:121]
	v_mfma_f32_16x16x32_bf16 v[114:117], v[176:179], v[184:187], v[114:117]
	v_mfma_f32_16x16x32_bf16 v[102:105], v[168:171], v[192:195], v[102:105]
	v_mfma_f32_16x16x32_bf16 v[98:101], v[176:179], v[192:195], v[98:101]
	v_mfma_f32_16x16x32_bf16 v[86:89], v[168:171], v[208:211], v[86:89]
	v_mfma_f32_16x16x32_bf16 v[82:85], v[176:179], v[208:211], v[82:85]
	v_mfma_f32_16x16x32_bf16 v[70:73], v[168:171], v[216:219], v[70:73]
	v_mfma_f32_16x16x32_bf16 v[66:69], v[176:179], v[216:219], v[66:69]
	s_barrier
	s_add_i32 s0, s33, s24
	s_mov_b32 m0, s0
	ds_read_b128 v[180:183], v146 offset:16384
	ds_read_b128 v[184:187], v146 offset:17408
	ds_read_b128 v[188:191], v146 offset:18432
	ds_read_b128 v[192:195], v146 offset:19456
	ds_read_b128 v[196:199], v146 offset:20480
	ds_read_b128 v[208:211], v146 offset:21504
	ds_read_b128 v[212:215], v146 offset:22528
	ds_read_b128 v[216:219], v146 offset:23552
	global_load_lds_dwordx4 v134, s[2:3]
	s_add_i32 m0, s0, 0x2000
	s_add_u32 s0, s2, 0x20000
	s_addc_u32 s1, s3, 0
	s_add_i32 s33, s55, s24
	global_load_lds_dwordx4 v130, s[2:3]
	s_mov_b32 m0, s33
	s_nop 0
	global_load_lds_dwordx4 v134, s[0:1]
	s_add_i32 m0, s33, 0x2000
	s_nop 0
	global_load_lds_dwordx4 v130, s[0:1]
	s_mov_b32 m0, s25
	s_nop 0
	global_load_lds_dwordx4 v136, s[4:5]
	s_mov_b32 m0, s26
	s_nop 0
	global_load_lds_dwordx4 v132, s[4:5]
	s_waitcnt vmcnt(8)
	s_waitcnt lgkmcnt(0)
	s_barrier
	v_mfma_f32_16x16x32_bf16 v[62:65], v[148:151], v[180:183], v[62:65]
	v_mfma_f32_16x16x32_bf16 v[58:61], v[156:159], v[180:183], v[58:61]
	v_mfma_f32_16x16x32_bf16 v[46:49], v[148:151], v[188:191], v[46:49]
	v_mfma_f32_16x16x32_bf16 v[42:45], v[156:159], v[188:191], v[42:45]
	v_mfma_f32_16x16x32_bf16 v[30:33], v[148:151], v[196:199], v[30:33]
	v_mfma_f32_16x16x32_bf16 v[26:29], v[156:159], v[196:199], v[26:29]
	v_mfma_f32_16x16x32_bf16 v[14:17], v[148:151], v[212:215], v[14:17]
	v_mfma_f32_16x16x32_bf16 v[10:13], v[156:159], v[212:215], v[10:13]
	v_mfma_f32_16x16x32_bf16 v[62:65], v[152:155], v[184:187], v[62:65]
	v_mfma_f32_16x16x32_bf16 v[58:61], v[160:163], v[184:187], v[58:61]
	v_mfma_f32_16x16x32_bf16 v[46:49], v[152:155], v[192:195], v[46:49]
	v_mfma_f32_16x16x32_bf16 v[42:45], v[160:163], v[192:195], v[42:45]
	v_mfma_f32_16x16x32_bf16 v[30:33], v[152:155], v[208:211], v[30:33]
	v_mfma_f32_16x16x32_bf16 v[26:29], v[160:163], v[208:211], v[26:29]
	v_mfma_f32_16x16x32_bf16 v[14:17], v[152:155], v[216:219], v[14:17]
	v_mfma_f32_16x16x32_bf16 v[10:13], v[160:163], v[216:219], v[10:13]
	v_mfma_f32_16x16x32_bf16 v[54:57], v[164:167], v[180:183], v[54:57]
	v_mfma_f32_16x16x32_bf16 v[50:53], v[172:175], v[180:183], v[50:53]
	v_mfma_f32_16x16x32_bf16 v[38:41], v[164:167], v[188:191], v[38:41]
	v_mfma_f32_16x16x32_bf16 v[34:37], v[172:175], v[188:191], v[34:37]
	v_mfma_f32_16x16x32_bf16 v[22:25], v[164:167], v[196:199], v[22:25]
	v_mfma_f32_16x16x32_bf16 v[18:21], v[172:175], v[196:199], v[18:21]
	v_mfma_f32_16x16x32_bf16 v[6:9], v[164:167], v[212:215], v[6:9]
	v_mfma_f32_16x16x32_bf16 v[2:5], v[172:175], v[212:215], v[2:5]
	v_mfma_f32_16x16x32_bf16 v[54:57], v[168:171], v[184:187], v[54:57]
	v_mfma_f32_16x16x32_bf16 v[50:53], v[176:179], v[184:187], v[50:53]
	v_mfma_f32_16x16x32_bf16 v[38:41], v[168:171], v[192:195], v[38:41]
	v_mfma_f32_16x16x32_bf16 v[34:37], v[176:179], v[192:195], v[34:37]
	v_mfma_f32_16x16x32_bf16 v[22:25], v[168:171], v[208:211], v[22:25]
	v_mfma_f32_16x16x32_bf16 v[18:21], v[176:179], v[208:211], v[18:21]
	v_mfma_f32_16x16x32_bf16 v[6:9], v[168:171], v[216:219], v[6:9]
	v_mfma_f32_16x16x32_bf16 v[2:5], v[176:179], v[216:219], v[2:5]
	s_barrier
	s_add_i32 s33, 0, 0x18000
	s_add_i32 s55, 0, 0x1c000
	ds_read_b128 v[148:151], v143 offset:32768
	ds_read_b128 v[152:155], v143 offset:33792
	ds_read_b128 v[156:159], v143 offset:34816
	ds_read_b128 v[160:163], v143 offset:35840
	ds_read_b128 v[164:167], v143 offset:49152
	ds_read_b128 v[168:171], v143 offset:50176
	ds_read_b128 v[172:175], v143 offset:51200
	ds_read_b128 v[176:179], v143 offset:52224
	s_add_u32 s0, s4, 0x20000
	s_addc_u32 s1, s5, 0
	s_mov_b32 m0, s27
	ds_read_b128 v[180:183], v146 offset:32768
	ds_read_b128 v[184:187], v146 offset:33792
	ds_read_b128 v[188:191], v146 offset:34816
	ds_read_b128 v[192:195], v146 offset:35840
	ds_read_b128 v[196:199], v146 offset:36864
	ds_read_b128 v[208:211], v146 offset:37888
	ds_read_b128 v[212:215], v146 offset:38912
	ds_read_b128 v[216:219], v146 offset:39936
	global_load_lds_dwordx4 v136, s[0:1]
	s_mov_b32 m0, s28
	s_nop 0
	global_load_lds_dwordx4 v132, s[0:1]
	s_waitcnt vmcnt(8)
	s_waitcnt lgkmcnt(0)
	s_barrier
	v_mfma_f32_16x16x32_bf16 v[126:129], v[148:151], v[180:183], v[126:129]
	v_mfma_f32_16x16x32_bf16 v[122:125], v[156:159], v[180:183], v[122:125]
	v_mfma_f32_16x16x32_bf16 v[110:113], v[148:151], v[188:191], v[110:113]
	v_mfma_f32_16x16x32_bf16 v[106:109], v[156:159], v[188:191], v[106:109]
	v_mfma_f32_16x16x32_bf16 v[94:97], v[148:151], v[196:199], v[94:97]
	v_mfma_f32_16x16x32_bf16 v[90:93], v[156:159], v[196:199], v[90:93]
	v_mfma_f32_16x16x32_bf16 v[78:81], v[148:151], v[212:215], v[78:81]
	v_mfma_f32_16x16x32_bf16 v[74:77], v[156:159], v[212:215], v[74:77]
	v_mfma_f32_16x16x32_bf16 v[126:129], v[152:155], v[184:187], v[126:129]
	v_mfma_f32_16x16x32_bf16 v[122:125], v[160:163], v[184:187], v[122:125]
	v_mfma_f32_16x16x32_bf16 v[110:113], v[152:155], v[192:195], v[110:113]
	v_mfma_f32_16x16x32_bf16 v[106:109], v[160:163], v[192:195], v[106:109]
	v_mfma_f32_16x16x32_bf16 v[94:97], v[152:155], v[208:211], v[94:97]
	v_mfma_f32_16x16x32_bf16 v[90:93], v[160:163], v[208:211], v[90:93]
	v_mfma_f32_16x16x32_bf16 v[78:81], v[152:155], v[216:219], v[78:81]
	v_mfma_f32_16x16x32_bf16 v[74:77], v[160:163], v[216:219], v[74:77]
	v_mfma_f32_16x16x32_bf16 v[118:121], v[164:167], v[180:183], v[118:121]
	v_mfma_f32_16x16x32_bf16 v[114:117], v[172:175], v[180:183], v[114:117]
	v_mfma_f32_16x16x32_bf16 v[102:105], v[164:167], v[188:191], v[102:105]
	v_mfma_f32_16x16x32_bf16 v[98:101], v[172:175], v[188:191], v[98:101]
	v_mfma_f32_16x16x32_bf16 v[86:89], v[164:167], v[196:199], v[86:89]
	v_mfma_f32_16x16x32_bf16 v[82:85], v[172:175], v[196:199], v[82:85]
	v_mfma_f32_16x16x32_bf16 v[70:73], v[164:167], v[212:215], v[70:73]
	v_mfma_f32_16x16x32_bf16 v[66:69], v[172:175], v[212:215], v[66:69]
	v_mfma_f32_16x16x32_bf16 v[118:121], v[168:171], v[184:187], v[118:121]
	v_mfma_f32_16x16x32_bf16 v[114:117], v[176:179], v[184:187], v[114:117]
	v_mfma_f32_16x16x32_bf16 v[102:105], v[168:171], v[192:195], v[102:105]
	v_mfma_f32_16x16x32_bf16 v[98:101], v[176:179], v[192:195], v[98:101]
	v_mfma_f32_16x16x32_bf16 v[86:89], v[168:171], v[208:211], v[86:89]
	v_mfma_f32_16x16x32_bf16 v[82:85], v[176:179], v[208:211], v[82:85]
	v_mfma_f32_16x16x32_bf16 v[70:73], v[168:171], v[216:219], v[70:73]
	v_mfma_f32_16x16x32_bf16 v[66:69], v[176:179], v[216:219], v[66:69]
	s_barrier
	s_add_i32 s0, s33, s24
	s_add_u32 s100, s2, 0x80
	s_addc_u32 s101, s3, 0
	s_mov_b32 m0, s0
	ds_read_b128 v[180:183], v146 offset:49152
	ds_read_b128 v[184:187], v146 offset:50176
	ds_read_b128 v[188:191], v146 offset:51200
	ds_read_b128 v[192:195], v146 offset:52224
	ds_read_b128 v[196:199], v146 offset:53248
	ds_read_b128 v[208:211], v146 offset:54272
	ds_read_b128 v[212:215], v146 offset:55296
	ds_read_b128 v[216:219], v146 offset:56320
	global_load_lds_dwordx4 v134, s[100:101]
	s_add_i32 m0, s0, 0x2000
	s_add_u32 s100, s2, 0x80
	s_addc_u32 s101, s3, 0
	s_add_u32 s0, s2, 0x20080
	s_addc_u32 s1, s3, 0
	s_add_i32 s2, s55, s24
	global_load_lds_dwordx4 v130, s[100:101]
	s_mov_b32 m0, s2
	s_nop 0
	global_load_lds_dwordx4 v134, s[0:1]
	s_add_i32 m0, s2, 0x2000
	s_nop 0
	global_load_lds_dwordx4 v130, s[0:1]
	s_add_u32 s100, s4, 0x80
	s_addc_u32 s101, s5, 0
	s_mov_b32 m0, s29
	s_nop 0
	global_load_lds_dwordx4 v136, s[100:101]
	s_add_u32 s100, s4, 0x80
	s_addc_u32 s101, s5, 0
	s_mov_b32 m0, s30
	s_nop 0
	global_load_lds_dwordx4 v132, s[100:101]
	s_waitcnt vmcnt(8)
	s_waitcnt lgkmcnt(0)
	s_barrier
	v_mfma_f32_16x16x32_bf16 v[62:65], v[148:151], v[180:183], v[62:65]
	v_mfma_f32_16x16x32_bf16 v[58:61], v[156:159], v[180:183], v[58:61]
	v_mfma_f32_16x16x32_bf16 v[46:49], v[148:151], v[188:191], v[46:49]
	v_mfma_f32_16x16x32_bf16 v[42:45], v[156:159], v[188:191], v[42:45]
	v_mfma_f32_16x16x32_bf16 v[30:33], v[148:151], v[196:199], v[30:33]
	v_mfma_f32_16x16x32_bf16 v[26:29], v[156:159], v[196:199], v[26:29]
	v_mfma_f32_16x16x32_bf16 v[14:17], v[148:151], v[212:215], v[14:17]
	v_mfma_f32_16x16x32_bf16 v[10:13], v[156:159], v[212:215], v[10:13]
	v_mfma_f32_16x16x32_bf16 v[62:65], v[152:155], v[184:187], v[62:65]
	v_mfma_f32_16x16x32_bf16 v[58:61], v[160:163], v[184:187], v[58:61]
	v_mfma_f32_16x16x32_bf16 v[46:49], v[152:155], v[192:195], v[46:49]
	v_mfma_f32_16x16x32_bf16 v[42:45], v[160:163], v[192:195], v[42:45]
	v_mfma_f32_16x16x32_bf16 v[30:33], v[152:155], v[208:211], v[30:33]
	v_mfma_f32_16x16x32_bf16 v[26:29], v[160:163], v[208:211], v[26:29]
	v_mfma_f32_16x16x32_bf16 v[14:17], v[152:155], v[216:219], v[14:17]
	v_mfma_f32_16x16x32_bf16 v[10:13], v[160:163], v[216:219], v[10:13]
	v_mfma_f32_16x16x32_bf16 v[54:57], v[164:167], v[180:183], v[54:57]
	v_mfma_f32_16x16x32_bf16 v[50:53], v[172:175], v[180:183], v[50:53]
	v_mfma_f32_16x16x32_bf16 v[38:41], v[164:167], v[188:191], v[38:41]
	v_mfma_f32_16x16x32_bf16 v[34:37], v[172:175], v[188:191], v[34:37]
	v_mfma_f32_16x16x32_bf16 v[22:25], v[164:167], v[196:199], v[22:25]
	v_mfma_f32_16x16x32_bf16 v[18:21], v[172:175], v[196:199], v[18:21]
	v_mfma_f32_16x16x32_bf16 v[6:9], v[164:167], v[212:215], v[6:9]
	v_mfma_f32_16x16x32_bf16 v[2:5], v[172:175], v[212:215], v[2:5]
	v_mfma_f32_16x16x32_bf16 v[54:57], v[168:171], v[184:187], v[54:57]
	v_mfma_f32_16x16x32_bf16 v[50:53], v[176:179], v[184:187], v[50:53]
	v_mfma_f32_16x16x32_bf16 v[38:41], v[168:171], v[192:195], v[38:41]
	v_mfma_f32_16x16x32_bf16 v[34:37], v[176:179], v[192:195], v[34:37]
	v_mfma_f32_16x16x32_bf16 v[22:25], v[168:171], v[208:211], v[22:25]
	v_mfma_f32_16x16x32_bf16 v[18:21], v[176:179], v[208:211], v[18:21]
	v_mfma_f32_16x16x32_bf16 v[6:9], v[168:171], v[216:219], v[6:9]
	v_mfma_f32_16x16x32_bf16 v[2:5], v[176:179], v[216:219], v[2:5]
	s_barrier
	s_add_i32 s59, s59, 2
	s_add_u32 s20, s20, 0x100
	s_addc_u32 s21, s21, 0
	s_add_u32 s49, s49, 0x100
	s_addc_u32 s58, s58, 0
	s_cmp_gt_u32 s59, 5
	s_cbranch_scc0 .LBB0_1363
	s_and_b64 vcc, exec, s[14:15]
	s_cbranch_vccz .LBB0_1366
	s_barrier

.LBB0_1428:
	s_add_u32 s0, s26, 0xfff80080
	s_addc_u32 s1, s27, -1
	s_add_i32 s33, 0, 0x10000
	s_cmp_eq_u32 s61, 28
	s_cselect_b32 s5, s17, s1
	s_cselect_b32 s4, s49, s0
	s_cselect_b32 s3, s15, s60
	s_cselect_b32 s2, s58, s59
	s_add_i32 s55, 0, 0x14000
	ds_read_b128 v[126:129], v187
	ds_read_b128 v[134:137], v187 offset:1024
	ds_read_b128 v[138:141], v187 offset:2048
	ds_read_b128 v[142:145], v187 offset:3072
	ds_read_b128 v[146:149], v187 offset:16384
	ds_read_b128 v[150:153], v187 offset:17408
	ds_read_b128 v[154:157], v187 offset:18432
	ds_read_b128 v[158:161], v187 offset:19456
	s_add_i32 m0, s23, 0xc000
	ds_read_b128 v[172:175], v189
	ds_read_b128 v[176:179], v189 offset:1024
	ds_read_b128 v[180:183], v189 offset:2048
	ds_read_b128 v[190:193], v189 offset:3072
	ds_read_b128 v[194:197], v189 offset:4096
	ds_read_b128 v[198:201], v189 offset:5120
	ds_read_b128 v[208:211], v189 offset:6144
	ds_read_b128 v[212:215], v189 offset:7168
	global_load_lds_dwordx4 v168, s[26:27]
	s_add_i32 m0, s23, 0xe000
	s_nop 0
	global_load_lds_dwordx4 v170, s[26:27]
	s_waitcnt vmcnt(8)
	s_waitcnt lgkmcnt(0)
	s_barrier
	v_mfma_f32_16x16x32_bf16 v[130:133], v[126:129], v[172:175], v[130:133]
	v_mfma_f32_16x16x32_bf16 v[118:121], v[138:141], v[172:175], v[118:121]
	v_mfma_f32_16x16x32_bf16 v[110:113], v[126:129], v[180:183], v[110:113]
	v_mfma_f32_16x16x32_bf16 v[102:105], v[138:141], v[180:183], v[102:105]
	v_mfma_f32_16x16x32_bf16 v[94:97], v[126:129], v[194:197], v[94:97]
	v_mfma_f32_16x16x32_bf16 v[86:89], v[138:141], v[194:197], v[86:89]
	v_mfma_f32_16x16x32_bf16 v[78:81], v[126:129], v[208:211], v[78:81]
	v_mfma_f32_16x16x32_bf16 v[70:73], v[138:141], v[208:211], v[70:73]
	v_mfma_f32_16x16x32_bf16 v[130:133], v[134:137], v[176:179], v[130:133]
	v_mfma_f32_16x16x32_bf16 v[118:121], v[142:145], v[176:179], v[118:121]
	v_mfma_f32_16x16x32_bf16 v[110:113], v[134:137], v[190:193], v[110:113]
	v_mfma_f32_16x16x32_bf16 v[102:105], v[142:145], v[190:193], v[102:105]
	v_mfma_f32_16x16x32_bf16 v[94:97], v[134:137], v[198:201], v[94:97]
	v_mfma_f32_16x16x32_bf16 v[86:89], v[142:145], v[198:201], v[86:89]
	v_mfma_f32_16x16x32_bf16 v[78:81], v[134:137], v[212:215], v[78:81]
	v_mfma_f32_16x16x32_bf16 v[70:73], v[142:145], v[212:215], v[70:73]
	v_mfma_f32_16x16x32_bf16 v[122:125], v[146:149], v[172:175], v[122:125]
	v_mfma_f32_16x16x32_bf16 v[114:117], v[154:157], v[172:175], v[114:117]
	v_mfma_f32_16x16x32_bf16 v[106:109], v[146:149], v[180:183], v[106:109]
	v_mfma_f32_16x16x32_bf16 v[98:101], v[154:157], v[180:183], v[98:101]
	v_mfma_f32_16x16x32_bf16 v[90:93], v[146:149], v[194:197], v[90:93]
	v_mfma_f32_16x16x32_bf16 v[82:85], v[154:157], v[194:197], v[82:85]
	v_mfma_f32_16x16x32_bf16 v[74:77], v[146:149], v[208:211], v[74:77]
	v_mfma_f32_16x16x32_bf16 v[66:69], v[154:157], v[208:211], v[66:69]
	v_mfma_f32_16x16x32_bf16 v[122:125], v[150:153], v[176:179], v[122:125]
	v_mfma_f32_16x16x32_bf16 v[114:117], v[158:161], v[176:179], v[114:117]
	v_mfma_f32_16x16x32_bf16 v[106:109], v[150:153], v[190:193], v[106:109]
	v_mfma_f32_16x16x32_bf16 v[98:101], v[158:161], v[190:193], v[98:101]
	v_mfma_f32_16x16x32_bf16 v[90:93], v[150:153], v[198:201], v[90:93]
	v_mfma_f32_16x16x32_bf16 v[82:85], v[158:161], v[198:201], v[82:85]
	v_mfma_f32_16x16x32_bf16 v[74:77], v[150:153], v[212:215], v[74:77]
	v_mfma_f32_16x16x32_bf16 v[66:69], v[158:161], v[212:215], v[66:69]
	s_barrier
	s_add_i32 s0, s33, s34
	s_mov_b32 m0, s0
	ds_read_b128 v[172:175], v189 offset:16384
	ds_read_b128 v[176:179], v189 offset:17408
	ds_read_b128 v[180:183], v189 offset:18432
	ds_read_b128 v[190:193], v189 offset:19456
	ds_read_b128 v[194:197], v189 offset:20480
	ds_read_b128 v[198:201], v189 offset:21504
	ds_read_b128 v[208:211], v189 offset:22528
	ds_read_b128 v[212:215], v189 offset:23552
	global_load_lds_dwordx4 v202, s[2:3]
	s_add_i32 m0, s0, 0x2000
	s_add_u32 s0, s2, 0x80000
	s_addc_u32 s1, s3, 0
	s_add_i32 s33, s55, s34
	global_load_lds_dwordx4 v162, s[2:3]
	s_mov_b32 m0, s33
	s_nop 0
	global_load_lds_dwordx4 v202, s[0:1]
	s_add_i32 m0, s33, 0x2000
	s_nop 0
	global_load_lds_dwordx4 v162, s[0:1]
	s_mov_b32 m0, s23
	s_nop 0
	global_load_lds_dwordx4 v166, s[4:5]
	s_mov_b32 m0, s25
	s_nop 0
	global_load_lds_dwordx4 v164, s[4:5]
	s_waitcnt vmcnt(8)
	s_waitcnt lgkmcnt(0)
	s_barrier
	v_mfma_f32_16x16x32_bf16 v[62:65], v[126:129], v[172:175], v[62:65]
	v_mfma_f32_16x16x32_bf16 v[54:57], v[138:141], v[172:175], v[54:57]
	v_mfma_f32_16x16x32_bf16 v[46:49], v[126:129], v[180:183], v[46:49]
	v_mfma_f32_16x16x32_bf16 v[38:41], v[138:141], v[180:183], v[38:41]
	v_mfma_f32_16x16x32_bf16 v[30:33], v[126:129], v[194:197], v[30:33]
	v_mfma_f32_16x16x32_bf16 v[22:25], v[138:141], v[194:197], v[22:25]
	v_mfma_f32_16x16x32_bf16 v[14:17], v[126:129], v[208:211], v[14:17]
	v_mfma_f32_16x16x32_bf16 v[6:9], v[138:141], v[208:211], v[6:9]
	v_mfma_f32_16x16x32_bf16 v[62:65], v[134:137], v[176:179], v[62:65]
	v_mfma_f32_16x16x32_bf16 v[54:57], v[142:145], v[176:179], v[54:57]
	v_mfma_f32_16x16x32_bf16 v[46:49], v[134:137], v[190:193], v[46:49]
	v_mfma_f32_16x16x32_bf16 v[38:41], v[142:145], v[190:193], v[38:41]
	v_mfma_f32_16x16x32_bf16 v[30:33], v[134:137], v[198:201], v[30:33]
	v_mfma_f32_16x16x32_bf16 v[22:25], v[142:145], v[198:201], v[22:25]
	v_mfma_f32_16x16x32_bf16 v[14:17], v[134:137], v[212:215], v[14:17]
	v_mfma_f32_16x16x32_bf16 v[6:9], v[142:145], v[212:215], v[6:9]
	v_mfma_f32_16x16x32_bf16 v[58:61], v[146:149], v[172:175], v[58:61]
	v_mfma_f32_16x16x32_bf16 v[50:53], v[154:157], v[172:175], v[50:53]
	v_mfma_f32_16x16x32_bf16 v[42:45], v[146:149], v[180:183], v[42:45]
	v_mfma_f32_16x16x32_bf16 v[34:37], v[154:157], v[180:183], v[34:37]
	v_mfma_f32_16x16x32_bf16 v[26:29], v[146:149], v[194:197], v[26:29]
	v_mfma_f32_16x16x32_bf16 v[18:21], v[154:157], v[194:197], v[18:21]
	v_mfma_f32_16x16x32_bf16 v[10:13], v[146:149], v[208:211], v[10:13]
	v_mfma_f32_16x16x32_bf16 v[2:5], v[154:157], v[208:211], v[2:5]
	v_mfma_f32_16x16x32_bf16 v[58:61], v[150:153], v[176:179], v[58:61]
	v_mfma_f32_16x16x32_bf16 v[50:53], v[158:161], v[176:179], v[50:53]
	v_mfma_f32_16x16x32_bf16 v[42:45], v[150:153], v[190:193], v[42:45]
	v_mfma_f32_16x16x32_bf16 v[34:37], v[158:161], v[190:193], v[34:37]
	v_mfma_f32_16x16x32_bf16 v[26:29], v[150:153], v[198:201], v[26:29]
	v_mfma_f32_16x16x32_bf16 v[18:21], v[158:161], v[198:201], v[18:21]
	v_mfma_f32_16x16x32_bf16 v[10:13], v[150:153], v[212:215], v[10:13]
	v_mfma_f32_16x16x32_bf16 v[2:5], v[158:161], v[212:215], v[2:5]
	s_barrier
	s_add_i32 s33, 0, 0x18000
	s_add_i32 s55, 0, 0x1c000
	ds_read_b128 v[126:129], v187 offset:32768
	ds_read_b128 v[134:137], v187 offset:33792
	ds_read_b128 v[138:141], v187 offset:34816
	ds_read_b128 v[142:145], v187 offset:35840
	ds_read_b128 v[146:149], v187 offset:49152
	ds_read_b128 v[150:153], v187 offset:50176
	ds_read_b128 v[154:157], v187 offset:51200
	ds_read_b128 v[158:161], v187 offset:52224
	s_add_u32 s0, s4, 0x80000
	s_addc_u32 s1, s5, 0
	s_mov_b32 m0, s35
	ds_read_b128 v[172:175], v189 offset:32768
	ds_read_b128 v[176:179], v189 offset:33792
	ds_read_b128 v[180:183], v189 offset:34816
	ds_read_b128 v[190:193], v189 offset:35840
	ds_read_b128 v[194:197], v189 offset:36864
	ds_read_b128 v[198:201], v189 offset:37888
	ds_read_b128 v[208:211], v189 offset:38912
	ds_read_b128 v[212:215], v189 offset:39936
	global_load_lds_dwordx4 v166, s[0:1]
	s_mov_b32 m0, s36
	s_nop 0
	global_load_lds_dwordx4 v164, s[0:1]
	s_waitcnt vmcnt(8)
	s_waitcnt lgkmcnt(0)
	s_barrier
	v_mfma_f32_16x16x32_bf16 v[130:133], v[126:129], v[172:175], v[130:133]
	v_mfma_f32_16x16x32_bf16 v[118:121], v[138:141], v[172:175], v[118:121]
	v_mfma_f32_16x16x32_bf16 v[110:113], v[126:129], v[180:183], v[110:113]
	v_mfma_f32_16x16x32_bf16 v[102:105], v[138:141], v[180:183], v[102:105]
	v_mfma_f32_16x16x32_bf16 v[94:97], v[126:129], v[194:197], v[94:97]
	v_mfma_f32_16x16x32_bf16 v[86:89], v[138:141], v[194:197], v[86:89]
	v_mfma_f32_16x16x32_bf16 v[78:81], v[126:129], v[208:211], v[78:81]
	v_mfma_f32_16x16x32_bf16 v[70:73], v[138:141], v[208:211], v[70:73]
	v_mfma_f32_16x16x32_bf16 v[130:133], v[134:137], v[176:179], v[130:133]
	v_mfma_f32_16x16x32_bf16 v[118:121], v[142:145], v[176:179], v[118:121]
	v_mfma_f32_16x16x32_bf16 v[110:113], v[134:137], v[190:193], v[110:113]
	v_mfma_f32_16x16x32_bf16 v[102:105], v[142:145], v[190:193], v[102:105]
	v_mfma_f32_16x16x32_bf16 v[94:97], v[134:137], v[198:201], v[94:97]
	v_mfma_f32_16x16x32_bf16 v[86:89], v[142:145], v[198:201], v[86:89]
	v_mfma_f32_16x16x32_bf16 v[78:81], v[134:137], v[212:215], v[78:81]
	v_mfma_f32_16x16x32_bf16 v[70:73], v[142:145], v[212:215], v[70:73]
	v_mfma_f32_16x16x32_bf16 v[122:125], v[146:149], v[172:175], v[122:125]
	v_mfma_f32_16x16x32_bf16 v[114:117], v[154:157], v[172:175], v[114:117]
	v_mfma_f32_16x16x32_bf16 v[106:109], v[146:149], v[180:183], v[106:109]
	v_mfma_f32_16x16x32_bf16 v[98:101], v[154:157], v[180:183], v[98:101]
	v_mfma_f32_16x16x32_bf16 v[90:93], v[146:149], v[194:197], v[90:93]
	v_mfma_f32_16x16x32_bf16 v[82:85], v[154:157], v[194:197], v[82:85]
	v_mfma_f32_16x16x32_bf16 v[74:77], v[146:149], v[208:211], v[74:77]
	v_mfma_f32_16x16x32_bf16 v[66:69], v[154:157], v[208:211], v[66:69]
	v_mfma_f32_16x16x32_bf16 v[122:125], v[150:153], v[176:179], v[122:125]
	v_mfma_f32_16x16x32_bf16 v[114:117], v[158:161], v[176:179], v[114:117]
	v_mfma_f32_16x16x32_bf16 v[106:109], v[150:153], v[190:193], v[106:109]
	v_mfma_f32_16x16x32_bf16 v[98:101], v[158:161], v[190:193], v[98:101]
	v_mfma_f32_16x16x32_bf16 v[90:93], v[150:153], v[198:201], v[90:93]
	v_mfma_f32_16x16x32_bf16 v[82:85], v[158:161], v[198:201], v[82:85]
	v_mfma_f32_16x16x32_bf16 v[74:77], v[150:153], v[212:215], v[74:77]
	v_mfma_f32_16x16x32_bf16 v[66:69], v[158:161], v[212:215], v[66:69]
	s_barrier
	s_add_i32 s0, s33, s34
	s_add_u32 s100, s2, 0x80
	s_addc_u32 s101, s3, 0
	s_mov_b32 m0, s0
	ds_read_b128 v[172:175], v189 offset:49152
	ds_read_b128 v[176:179], v189 offset:50176
	ds_read_b128 v[180:183], v189 offset:51200
	ds_read_b128 v[190:193], v189 offset:52224
	ds_read_b128 v[194:197], v189 offset:53248
	ds_read_b128 v[198:201], v189 offset:54272
	ds_read_b128 v[208:211], v189 offset:55296
	ds_read_b128 v[212:215], v189 offset:56320
	global_load_lds_dwordx4 v202, s[100:101]
	s_add_i32 m0, s0, 0x2000
	s_add_u32 s100, s2, 0x80
	s_addc_u32 s101, s3, 0
	s_add_u32 s0, s2, 0x80080
	s_addc_u32 s1, s3, 0
	s_add_i32 s2, s55, s34
	global_load_lds_dwordx4 v162, s[100:101]
	s_mov_b32 m0, s2
	s_nop 0
	global_load_lds_dwordx4 v202, s[0:1]
	s_add_i32 m0, s2, 0x2000
	s_nop 0
	global_load_lds_dwordx4 v162, s[0:1]
	s_add_u32 s100, s4, 0x80
	s_addc_u32 s101, s5, 0
	s_mov_b32 m0, s39
	s_nop 0
	global_load_lds_dwordx4 v166, s[100:101]
	s_add_u32 s100, s4, 0x80
	s_addc_u32 s101, s5, 0
	s_mov_b32 m0, s40
	s_nop 0
	global_load_lds_dwordx4 v164, s[100:101]
	s_waitcnt vmcnt(8)
	s_waitcnt lgkmcnt(0)
	s_barrier
	v_mfma_f32_16x16x32_bf16 v[62:65], v[126:129], v[172:175], v[62:65]
	v_mfma_f32_16x16x32_bf16 v[54:57], v[138:141], v[172:175], v[54:57]
	v_mfma_f32_16x16x32_bf16 v[46:49], v[126:129], v[180:183], v[46:49]
	v_mfma_f32_16x16x32_bf16 v[38:41], v[138:141], v[180:183], v[38:41]
	v_mfma_f32_16x16x32_bf16 v[30:33], v[126:129], v[194:197], v[30:33]
	v_mfma_f32_16x16x32_bf16 v[22:25], v[138:141], v[194:197], v[22:25]
	v_mfma_f32_16x16x32_bf16 v[14:17], v[126:129], v[208:211], v[14:17]
	v_mfma_f32_16x16x32_bf16 v[6:9], v[138:141], v[208:211], v[6:9]
	v_mfma_f32_16x16x32_bf16 v[62:65], v[134:137], v[176:179], v[62:65]
	v_mfma_f32_16x16x32_bf16 v[54:57], v[142:145], v[176:179], v[54:57]
	v_mfma_f32_16x16x32_bf16 v[46:49], v[134:137], v[190:193], v[46:49]
	v_mfma_f32_16x16x32_bf16 v[38:41], v[142:145], v[190:193], v[38:41]
	v_mfma_f32_16x16x32_bf16 v[30:33], v[134:137], v[198:201], v[30:33]
	v_mfma_f32_16x16x32_bf16 v[22:25], v[142:145], v[198:201], v[22:25]
	v_mfma_f32_16x16x32_bf16 v[14:17], v[134:137], v[212:215], v[14:17]
	v_mfma_f32_16x16x32_bf16 v[6:9], v[142:145], v[212:215], v[6:9]
	v_mfma_f32_16x16x32_bf16 v[58:61], v[146:149], v[172:175], v[58:61]
	v_mfma_f32_16x16x32_bf16 v[50:53], v[154:157], v[172:175], v[50:53]
	v_mfma_f32_16x16x32_bf16 v[42:45], v[146:149], v[180:183], v[42:45]
	v_mfma_f32_16x16x32_bf16 v[34:37], v[154:157], v[180:183], v[34:37]
	v_mfma_f32_16x16x32_bf16 v[26:29], v[146:149], v[194:197], v[26:29]
	v_mfma_f32_16x16x32_bf16 v[18:21], v[154:157], v[194:197], v[18:21]
	v_mfma_f32_16x16x32_bf16 v[10:13], v[146:149], v[208:211], v[10:13]
	v_mfma_f32_16x16x32_bf16 v[2:5], v[154:157], v[208:211], v[2:5]
	v_mfma_f32_16x16x32_bf16 v[58:61], v[150:153], v[176:179], v[58:61]
	v_mfma_f32_16x16x32_bf16 v[50:53], v[158:161], v[176:179], v[50:53]
	v_mfma_f32_16x16x32_bf16 v[42:45], v[150:153], v[190:193], v[42:45]
	v_mfma_f32_16x16x32_bf16 v[34:37], v[158:161], v[190:193], v[34:37]
	v_mfma_f32_16x16x32_bf16 v[26:29], v[150:153], v[198:201], v[26:29]
	v_mfma_f32_16x16x32_bf16 v[18:21], v[158:161], v[198:201], v[18:21]
	v_mfma_f32_16x16x32_bf16 v[10:13], v[150:153], v[212:215], v[10:13]
	v_mfma_f32_16x16x32_bf16 v[2:5], v[158:161], v[212:215], v[2:5]
	s_barrier
	s_add_i32 s61, s61, 2
	s_add_u32 s26, s26, 0x100
	s_addc_u32 s27, s27, 0
	s_add_u32 s59, s59, 0x100
	s_addc_u32 s60, s60, 0
	s_cmp_gt_u32 s61, 29
	s_cbranch_scc0 .LBB0_1428
	s_and_b64 vcc, exec, s[10:11]
	s_cbranch_vccz .LBB0_1431
	s_barrier

.LBB0_1594:
	s_add_u32 s0, s28, 0xfff80080
	s_addc_u32 s1, s29, -1
	s_add_i32 s33, 0, 0x10000
	s_cmp_eq_u32 s61, 28
	s_cselect_b32 s5, s19, s1
	s_cselect_b32 s4, s49, s0
	s_cselect_b32 s3, s17, s60
	s_cselect_b32 s2, s58, s59
	s_add_i32 s55, 0, 0x14000
	ds_read_b128 v[146:149], v143
	ds_read_b128 v[150:153], v143 offset:1024
	ds_read_b128 v[154:157], v143 offset:2048
	ds_read_b128 v[158:161], v143 offset:3072
	ds_read_b128 v[162:165], v143 offset:16384
	ds_read_b128 v[166:169], v143 offset:17408
	ds_read_b128 v[170:173], v143 offset:18432
	ds_read_b128 v[174:177], v143 offset:19456
	s_add_i32 m0, s25, 0xc000
	ds_read_b128 v[178:181], v145
	ds_read_b128 v[182:185], v145 offset:1024
	ds_read_b128 v[186:189], v145 offset:2048
	ds_read_b128 v[190:193], v145 offset:3072
	ds_read_b128 v[194:197], v145 offset:4096
	ds_read_b128 v[198:201], v145 offset:5120
	ds_read_b128 v[208:211], v145 offset:6144
	ds_read_b128 v[212:215], v145 offset:7168
	global_load_lds_dwordx4 v136, s[28:29]
	s_add_i32 m0, s25, 0xe000
	s_nop 0
	global_load_lds_dwordx4 v138, s[28:29]
	s_waitcnt vmcnt(8)
	s_waitcnt lgkmcnt(0)
	s_barrier
	v_mfma_f32_16x16x32_bf16 v[126:129], v[146:149], v[178:181], v[126:129]
	v_mfma_f32_16x16x32_bf16 v[118:121], v[154:157], v[178:181], v[118:121]
	v_mfma_f32_16x16x32_bf16 v[110:113], v[146:149], v[186:189], v[110:113]
	v_mfma_f32_16x16x32_bf16 v[102:105], v[154:157], v[186:189], v[102:105]
	v_mfma_f32_16x16x32_bf16 v[94:97], v[146:149], v[194:197], v[94:97]
	v_mfma_f32_16x16x32_bf16 v[86:89], v[154:157], v[194:197], v[86:89]
	v_mfma_f32_16x16x32_bf16 v[78:81], v[146:149], v[208:211], v[78:81]
	v_mfma_f32_16x16x32_bf16 v[70:73], v[154:157], v[208:211], v[70:73]
	v_mfma_f32_16x16x32_bf16 v[126:129], v[150:153], v[182:185], v[126:129]
	v_mfma_f32_16x16x32_bf16 v[118:121], v[158:161], v[182:185], v[118:121]
	v_mfma_f32_16x16x32_bf16 v[110:113], v[150:153], v[190:193], v[110:113]
	v_mfma_f32_16x16x32_bf16 v[102:105], v[158:161], v[190:193], v[102:105]
	v_mfma_f32_16x16x32_bf16 v[94:97], v[150:153], v[198:201], v[94:97]
	v_mfma_f32_16x16x32_bf16 v[86:89], v[158:161], v[198:201], v[86:89]
	v_mfma_f32_16x16x32_bf16 v[78:81], v[150:153], v[212:215], v[78:81]
	v_mfma_f32_16x16x32_bf16 v[70:73], v[158:161], v[212:215], v[70:73]
	v_mfma_f32_16x16x32_bf16 v[122:125], v[162:165], v[178:181], v[122:125]
	v_mfma_f32_16x16x32_bf16 v[114:117], v[170:173], v[178:181], v[114:117]
	v_mfma_f32_16x16x32_bf16 v[106:109], v[162:165], v[186:189], v[106:109]
	v_mfma_f32_16x16x32_bf16 v[98:101], v[170:173], v[186:189], v[98:101]
	v_mfma_f32_16x16x32_bf16 v[90:93], v[162:165], v[194:197], v[90:93]
	v_mfma_f32_16x16x32_bf16 v[82:85], v[170:173], v[194:197], v[82:85]
	v_mfma_f32_16x16x32_bf16 v[74:77], v[162:165], v[208:211], v[74:77]
	v_mfma_f32_16x16x32_bf16 v[66:69], v[170:173], v[208:211], v[66:69]
	v_mfma_f32_16x16x32_bf16 v[122:125], v[166:169], v[182:185], v[122:125]
	v_mfma_f32_16x16x32_bf16 v[114:117], v[174:177], v[182:185], v[114:117]
	v_mfma_f32_16x16x32_bf16 v[106:109], v[166:169], v[190:193], v[106:109]
	v_mfma_f32_16x16x32_bf16 v[98:101], v[174:177], v[190:193], v[98:101]
	v_mfma_f32_16x16x32_bf16 v[90:93], v[166:169], v[198:201], v[90:93]
	v_mfma_f32_16x16x32_bf16 v[82:85], v[174:177], v[198:201], v[82:85]
	v_mfma_f32_16x16x32_bf16 v[74:77], v[166:169], v[212:215], v[74:77]
	v_mfma_f32_16x16x32_bf16 v[66:69], v[174:177], v[212:215], v[66:69]
	s_barrier
	s_add_i32 s0, s33, s36
	s_mov_b32 m0, s0
	ds_read_b128 v[178:181], v145 offset:16384
	ds_read_b128 v[182:185], v145 offset:17408
	ds_read_b128 v[186:189], v145 offset:18432
	ds_read_b128 v[190:193], v145 offset:19456
	ds_read_b128 v[194:197], v145 offset:20480
	ds_read_b128 v[198:201], v145 offset:21504
	ds_read_b128 v[208:211], v145 offset:22528
	ds_read_b128 v[212:215], v145 offset:23552
	global_load_lds_dwordx4 v202, s[2:3]
	s_add_i32 m0, s0, 0x2000
	s_add_u32 s0, s2, 0x80000
	s_addc_u32 s1, s3, 0
	s_add_i32 s33, s55, s36
	global_load_lds_dwordx4 v130, s[2:3]
	s_mov_b32 m0, s33
	s_nop 0
	global_load_lds_dwordx4 v202, s[0:1]
	s_add_i32 m0, s33, 0x2000
	s_nop 0
	global_load_lds_dwordx4 v130, s[0:1]
	s_mov_b32 m0, s25
	s_nop 0
	global_load_lds_dwordx4 v134, s[4:5]
	s_mov_b32 m0, s27
	s_nop 0
	global_load_lds_dwordx4 v132, s[4:5]
	s_waitcnt vmcnt(8)
	s_waitcnt lgkmcnt(0)
	s_barrier
	v_mfma_f32_16x16x32_bf16 v[62:65], v[146:149], v[178:181], v[62:65]
	v_mfma_f32_16x16x32_bf16 v[54:57], v[154:157], v[178:181], v[54:57]
	v_mfma_f32_16x16x32_bf16 v[46:49], v[146:149], v[186:189], v[46:49]
	v_mfma_f32_16x16x32_bf16 v[38:41], v[154:157], v[186:189], v[38:41]
	v_mfma_f32_16x16x32_bf16 v[30:33], v[146:149], v[194:197], v[30:33]
	v_mfma_f32_16x16x32_bf16 v[22:25], v[154:157], v[194:197], v[22:25]
	v_mfma_f32_16x16x32_bf16 v[14:17], v[146:149], v[208:211], v[14:17]
	v_mfma_f32_16x16x32_bf16 v[6:9], v[154:157], v[208:211], v[6:9]
	v_mfma_f32_16x16x32_bf16 v[62:65], v[150:153], v[182:185], v[62:65]
	v_mfma_f32_16x16x32_bf16 v[54:57], v[158:161], v[182:185], v[54:57]
	v_mfma_f32_16x16x32_bf16 v[46:49], v[150:153], v[190:193], v[46:49]
	v_mfma_f32_16x16x32_bf16 v[38:41], v[158:161], v[190:193], v[38:41]
	v_mfma_f32_16x16x32_bf16 v[30:33], v[150:153], v[198:201], v[30:33]
	v_mfma_f32_16x16x32_bf16 v[22:25], v[158:161], v[198:201], v[22:25]
	v_mfma_f32_16x16x32_bf16 v[14:17], v[150:153], v[212:215], v[14:17]
	v_mfma_f32_16x16x32_bf16 v[6:9], v[158:161], v[212:215], v[6:9]
	v_mfma_f32_16x16x32_bf16 v[58:61], v[162:165], v[178:181], v[58:61]
	v_mfma_f32_16x16x32_bf16 v[50:53], v[170:173], v[178:181], v[50:53]
	v_mfma_f32_16x16x32_bf16 v[42:45], v[162:165], v[186:189], v[42:45]
	v_mfma_f32_16x16x32_bf16 v[34:37], v[170:173], v[186:189], v[34:37]
	v_mfma_f32_16x16x32_bf16 v[26:29], v[162:165], v[194:197], v[26:29]
	v_mfma_f32_16x16x32_bf16 v[18:21], v[170:173], v[194:197], v[18:21]
	v_mfma_f32_16x16x32_bf16 v[10:13], v[162:165], v[208:211], v[10:13]
	v_mfma_f32_16x16x32_bf16 v[2:5], v[170:173], v[208:211], v[2:5]
	v_mfma_f32_16x16x32_bf16 v[58:61], v[166:169], v[182:185], v[58:61]
	v_mfma_f32_16x16x32_bf16 v[50:53], v[174:177], v[182:185], v[50:53]
	v_mfma_f32_16x16x32_bf16 v[42:45], v[166:169], v[190:193], v[42:45]
	v_mfma_f32_16x16x32_bf16 v[34:37], v[174:177], v[190:193], v[34:37]
	v_mfma_f32_16x16x32_bf16 v[26:29], v[166:169], v[198:201], v[26:29]
	v_mfma_f32_16x16x32_bf16 v[18:21], v[174:177], v[198:201], v[18:21]
	v_mfma_f32_16x16x32_bf16 v[10:13], v[166:169], v[212:215], v[10:13]
	v_mfma_f32_16x16x32_bf16 v[2:5], v[174:177], v[212:215], v[2:5]
	s_barrier
	s_add_i32 s33, 0, 0x18000
	s_add_i32 s55, 0, 0x1c000
	ds_read_b128 v[146:149], v143 offset:32768
	ds_read_b128 v[150:153], v143 offset:33792
	ds_read_b128 v[154:157], v143 offset:34816
	ds_read_b128 v[158:161], v143 offset:35840
	ds_read_b128 v[162:165], v143 offset:49152
	ds_read_b128 v[166:169], v143 offset:50176
	ds_read_b128 v[170:173], v143 offset:51200
	ds_read_b128 v[174:177], v143 offset:52224
	s_add_u32 s0, s4, 0x80000
	s_addc_u32 s1, s5, 0
	s_mov_b32 m0, s37
	ds_read_b128 v[178:181], v145 offset:32768
	ds_read_b128 v[182:185], v145 offset:33792
	ds_read_b128 v[186:189], v145 offset:34816
	ds_read_b128 v[190:193], v145 offset:35840
	ds_read_b128 v[194:197], v145 offset:36864
	ds_read_b128 v[198:201], v145 offset:37888
	ds_read_b128 v[208:211], v145 offset:38912
	ds_read_b128 v[212:215], v145 offset:39936
	global_load_lds_dwordx4 v134, s[0:1]
	s_mov_b32 m0, s38
	s_nop 0
	global_load_lds_dwordx4 v132, s[0:1]
	s_waitcnt vmcnt(8)
	s_waitcnt lgkmcnt(0)
	s_barrier
	v_mfma_f32_16x16x32_bf16 v[126:129], v[146:149], v[178:181], v[126:129]
	v_mfma_f32_16x16x32_bf16 v[118:121], v[154:157], v[178:181], v[118:121]
	v_mfma_f32_16x16x32_bf16 v[110:113], v[146:149], v[186:189], v[110:113]
	v_mfma_f32_16x16x32_bf16 v[102:105], v[154:157], v[186:189], v[102:105]
	v_mfma_f32_16x16x32_bf16 v[94:97], v[146:149], v[194:197], v[94:97]
	v_mfma_f32_16x16x32_bf16 v[86:89], v[154:157], v[194:197], v[86:89]
	v_mfma_f32_16x16x32_bf16 v[78:81], v[146:149], v[208:211], v[78:81]
	v_mfma_f32_16x16x32_bf16 v[70:73], v[154:157], v[208:211], v[70:73]
	v_mfma_f32_16x16x32_bf16 v[126:129], v[150:153], v[182:185], v[126:129]
	v_mfma_f32_16x16x32_bf16 v[118:121], v[158:161], v[182:185], v[118:121]
	v_mfma_f32_16x16x32_bf16 v[110:113], v[150:153], v[190:193], v[110:113]
	v_mfma_f32_16x16x32_bf16 v[102:105], v[158:161], v[190:193], v[102:105]
	v_mfma_f32_16x16x32_bf16 v[94:97], v[150:153], v[198:201], v[94:97]
	v_mfma_f32_16x16x32_bf16 v[86:89], v[158:161], v[198:201], v[86:89]
	v_mfma_f32_16x16x32_bf16 v[78:81], v[150:153], v[212:215], v[78:81]
	v_mfma_f32_16x16x32_bf16 v[70:73], v[158:161], v[212:215], v[70:73]
	v_mfma_f32_16x16x32_bf16 v[122:125], v[162:165], v[178:181], v[122:125]
	v_mfma_f32_16x16x32_bf16 v[114:117], v[170:173], v[178:181], v[114:117]
	v_mfma_f32_16x16x32_bf16 v[106:109], v[162:165], v[186:189], v[106:109]
	v_mfma_f32_16x16x32_bf16 v[98:101], v[170:173], v[186:189], v[98:101]
	v_mfma_f32_16x16x32_bf16 v[90:93], v[162:165], v[194:197], v[90:93]
	v_mfma_f32_16x16x32_bf16 v[82:85], v[170:173], v[194:197], v[82:85]
	v_mfma_f32_16x16x32_bf16 v[74:77], v[162:165], v[208:211], v[74:77]
	v_mfma_f32_16x16x32_bf16 v[66:69], v[170:173], v[208:211], v[66:69]
	v_mfma_f32_16x16x32_bf16 v[122:125], v[166:169], v[182:185], v[122:125]
	v_mfma_f32_16x16x32_bf16 v[114:117], v[174:177], v[182:185], v[114:117]
	v_mfma_f32_16x16x32_bf16 v[106:109], v[166:169], v[190:193], v[106:109]
	v_mfma_f32_16x16x32_bf16 v[98:101], v[174:177], v[190:193], v[98:101]
	v_mfma_f32_16x16x32_bf16 v[90:93], v[166:169], v[198:201], v[90:93]
	v_mfma_f32_16x16x32_bf16 v[82:85], v[174:177], v[198:201], v[82:85]
	v_mfma_f32_16x16x32_bf16 v[74:77], v[166:169], v[212:215], v[74:77]
	v_mfma_f32_16x16x32_bf16 v[66:69], v[174:177], v[212:215], v[66:69]
	s_barrier
	s_add_i32 s0, s33, s36
	s_add_u32 s100, s2, 0x80
	s_addc_u32 s101, s3, 0
	s_mov_b32 m0, s0
	ds_read_b128 v[178:181], v145 offset:49152
	ds_read_b128 v[182:185], v145 offset:50176
	ds_read_b128 v[186:189], v145 offset:51200
	ds_read_b128 v[190:193], v145 offset:52224
	ds_read_b128 v[194:197], v145 offset:53248
	ds_read_b128 v[198:201], v145 offset:54272
	ds_read_b128 v[208:211], v145 offset:55296
	ds_read_b128 v[212:215], v145 offset:56320
	global_load_lds_dwordx4 v202, s[100:101]
	s_add_i32 m0, s0, 0x2000
	s_add_u32 s100, s2, 0x80
	s_addc_u32 s101, s3, 0
	s_add_u32 s0, s2, 0x80080
	s_addc_u32 s1, s3, 0
	s_add_i32 s2, s55, s36
	global_load_lds_dwordx4 v130, s[100:101]
	s_mov_b32 m0, s2
	s_nop 0
	global_load_lds_dwordx4 v202, s[0:1]
	s_add_i32 m0, s2, 0x2000
	s_nop 0
	global_load_lds_dwordx4 v130, s[0:1]
	s_add_u32 s100, s4, 0x80
	s_addc_u32 s101, s5, 0
	s_mov_b32 m0, s39
	s_nop 0
	global_load_lds_dwordx4 v134, s[100:101]
	s_add_u32 s100, s4, 0x80
	s_addc_u32 s101, s5, 0
	s_mov_b32 m0, s40
	s_nop 0
	global_load_lds_dwordx4 v132, s[100:101]
	s_waitcnt vmcnt(8)
	s_waitcnt lgkmcnt(0)
	s_barrier
	v_mfma_f32_16x16x32_bf16 v[62:65], v[146:149], v[178:181], v[62:65]
	v_mfma_f32_16x16x32_bf16 v[54:57], v[154:157], v[178:181], v[54:57]
	v_mfma_f32_16x16x32_bf16 v[46:49], v[146:149], v[186:189], v[46:49]
	v_mfma_f32_16x16x32_bf16 v[38:41], v[154:157], v[186:189], v[38:41]
	v_mfma_f32_16x16x32_bf16 v[30:33], v[146:149], v[194:197], v[30:33]
	v_mfma_f32_16x16x32_bf16 v[22:25], v[154:157], v[194:197], v[22:25]
	v_mfma_f32_16x16x32_bf16 v[14:17], v[146:149], v[208:211], v[14:17]
	v_mfma_f32_16x16x32_bf16 v[6:9], v[154:157], v[208:211], v[6:9]
	v_mfma_f32_16x16x32_bf16 v[62:65], v[150:153], v[182:185], v[62:65]
	v_mfma_f32_16x16x32_bf16 v[54:57], v[158:161], v[182:185], v[54:57]
	v_mfma_f32_16x16x32_bf16 v[46:49], v[150:153], v[190:193], v[46:49]
	v_mfma_f32_16x16x32_bf16 v[38:41], v[158:161], v[190:193], v[38:41]
	v_mfma_f32_16x16x32_bf16 v[30:33], v[150:153], v[198:201], v[30:33]
	v_mfma_f32_16x16x32_bf16 v[22:25], v[158:161], v[198:201], v[22:25]
	v_mfma_f32_16x16x32_bf16 v[14:17], v[150:153], v[212:215], v[14:17]
	v_mfma_f32_16x16x32_bf16 v[6:9], v[158:161], v[212:215], v[6:9]
	v_mfma_f32_16x16x32_bf16 v[58:61], v[162:165], v[178:181], v[58:61]
	v_mfma_f32_16x16x32_bf16 v[50:53], v[170:173], v[178:181], v[50:53]
	v_mfma_f32_16x16x32_bf16 v[42:45], v[162:165], v[186:189], v[42:45]
	v_mfma_f32_16x16x32_bf16 v[34:37], v[170:173], v[186:189], v[34:37]
	v_mfma_f32_16x16x32_bf16 v[26:29], v[162:165], v[194:197], v[26:29]
	v_mfma_f32_16x16x32_bf16 v[18:21], v[170:173], v[194:197], v[18:21]
	v_mfma_f32_16x16x32_bf16 v[10:13], v[162:165], v[208:211], v[10:13]
	v_mfma_f32_16x16x32_bf16 v[2:5], v[170:173], v[208:211], v[2:5]
	v_mfma_f32_16x16x32_bf16 v[58:61], v[166:169], v[182:185], v[58:61]
	v_mfma_f32_16x16x32_bf16 v[50:53], v[174:177], v[182:185], v[50:53]
	v_mfma_f32_16x16x32_bf16 v[42:45], v[166:169], v[190:193], v[42:45]
	v_mfma_f32_16x16x32_bf16 v[34:37], v[174:177], v[190:193], v[34:37]
	v_mfma_f32_16x16x32_bf16 v[26:29], v[166:169], v[198:201], v[26:29]
	v_mfma_f32_16x16x32_bf16 v[18:21], v[174:177], v[198:201], v[18:21]
	v_mfma_f32_16x16x32_bf16 v[10:13], v[166:169], v[212:215], v[10:13]
	v_mfma_f32_16x16x32_bf16 v[2:5], v[174:177], v[212:215], v[2:5]
	s_barrier
	s_add_i32 s61, s61, 2
	s_add_u32 s28, s28, 0x100
	s_addc_u32 s29, s29, 0
	s_add_u32 s59, s59, 0x100
	s_addc_u32 s60, s60, 0
	s_cmp_gt_u32 s61, 29
	s_cbranch_scc0 .LBB0_1594
	s_and_b64 vcc, exec, s[14:15]
	s_cbranch_vccz .LBB0_1597
	s_barrier

.LBB0_1718:
	s_add_u32 s18, s4, 0x100
	s_addc_u32 s19, s5, 0
	s_add_i32 s0, 0, 0x10000
	s_cmpk_eq_i32 s59, 0x54
	s_cselect_b32 s23, s9, s19
	s_cselect_b32 s22, s8, s18
	s_cselect_b32 s21, s17, s58
	s_cselect_b32 s20, s16, s49
	s_add_i32 s33, 0, 0x14000
	ds_read_b128 v[78:81], v205
	ds_read_b128 v[82:85], v205 offset:1024
	ds_read_b128 v[94:97], v205 offset:2048
	ds_read_b128 v[98:101], v205 offset:3072
	ds_read_b128 v[106:109], v205 offset:16384
	ds_read_b128 v[110:113], v205 offset:17408
	ds_read_b128 v[126:129], v205 offset:18432
	ds_read_b128 v[134:137], v205 offset:19456
	s_add_i32 m0, s27, 0xc000
	ds_read_b128 v[146:149], v239
	ds_read_b128 v[158:161], v239 offset:1024
	ds_read_b128 v[166:169], v239 offset:2048
	ds_read_b128 v[174:177], v239 offset:3072
	ds_read_b128 v[178:181], v239 offset:4096
	ds_read_b128 v[182:185], v239 offset:5120
	ds_read_b128 v[186:189], v239 offset:6144
	ds_read_b128 v[190:193], v239 offset:7168
	global_load_lds_dwordx4 v214, s[4:5]
	s_add_i32 m0, s27, 0xe000
	s_nop 0
	global_load_lds_dwordx4 v216, s[4:5]
	s_waitcnt vmcnt(8)
	s_waitcnt lgkmcnt(0)
	s_barrier
	v_mfma_f32_16x16x32_bf16 v[170:173], v[78:81], v[146:149], v[170:173]
	v_mfma_f32_16x16x32_bf16 v[162:165], v[94:97], v[146:149], v[162:165]
	v_mfma_f32_16x16x32_bf16 v[142:145], v[78:81], v[166:169], v[142:145]
	v_mfma_f32_16x16x32_bf16 v[138:141], v[94:97], v[166:169], v[138:141]
	v_mfma_f32_16x16x32_bf16 v[118:121], v[78:81], v[178:181], v[118:121]
	v_mfma_f32_16x16x32_bf16 v[114:117], v[94:97], v[178:181], v[114:117]
	v_mfma_f32_16x16x32_bf16 v[86:89], v[78:81], v[186:189], v[86:89]
	v_mfma_f32_16x16x32_bf16 v[74:77], v[94:97], v[186:189], v[74:77]
	v_mfma_f32_16x16x32_bf16 v[170:173], v[82:85], v[158:161], v[170:173]
	v_mfma_f32_16x16x32_bf16 v[162:165], v[98:101], v[158:161], v[162:165]
	v_mfma_f32_16x16x32_bf16 v[142:145], v[82:85], v[174:177], v[142:145]
	v_mfma_f32_16x16x32_bf16 v[138:141], v[98:101], v[174:177], v[138:141]
	v_mfma_f32_16x16x32_bf16 v[118:121], v[82:85], v[182:185], v[118:121]
	v_mfma_f32_16x16x32_bf16 v[114:117], v[98:101], v[182:185], v[114:117]
	v_mfma_f32_16x16x32_bf16 v[86:89], v[82:85], v[190:193], v[86:89]
	v_mfma_f32_16x16x32_bf16 v[74:77], v[98:101], v[190:193], v[74:77]
	v_mfma_f32_16x16x32_bf16 v[154:157], v[106:109], v[146:149], v[154:157]
	v_mfma_f32_16x16x32_bf16 v[130:133], v[106:109], v[166:169], v[130:133]
	v_mfma_f32_16x16x32_bf16 v[122:125], v[126:129], v[166:169], v[122:125]
	v_mfma_f32_16x16x32_bf16 v[102:105], v[106:109], v[178:181], v[102:105]
	v_mfma_f32_16x16x32_bf16 v[90:93], v[126:129], v[178:181], v[90:93]
	v_mfma_f32_16x16x32_bf16 v[70:73], v[106:109], v[186:189], v[70:73]
	v_mfma_f32_16x16x32_bf16 v[66:69], v[126:129], v[186:189], v[66:69]
	v_mfma_f32_16x16x32_bf16 v[154:157], v[110:113], v[158:161], v[154:157]
	v_mfma_f32_16x16x32_bf16 v[146:149], v[126:129], v[146:149], v[150:153]
	v_mfma_f32_16x16x32_bf16 v[130:133], v[110:113], v[174:177], v[130:133]
	v_mfma_f32_16x16x32_bf16 v[122:125], v[134:137], v[174:177], v[122:125]
	v_mfma_f32_16x16x32_bf16 v[102:105], v[110:113], v[182:185], v[102:105]
	v_mfma_f32_16x16x32_bf16 v[90:93], v[134:137], v[182:185], v[90:93]
	v_mfma_f32_16x16x32_bf16 v[70:73], v[110:113], v[190:193], v[70:73]
	v_mfma_f32_16x16x32_bf16 v[66:69], v[134:137], v[190:193], v[66:69]
	v_mfma_f32_16x16x32_bf16 v[146:149], v[134:137], v[158:161], v[146:149]
	s_barrier
	s_add_i32 s0, s0, s26
	s_mov_b32 m0, s0
	ds_read_b128 v[150:153], v239 offset:16384
	ds_read_b128 v[158:161], v239 offset:17408
	ds_read_b128 v[166:169], v239 offset:18432
	ds_read_b128 v[174:177], v239 offset:19456
	ds_read_b128 v[178:181], v239 offset:20480
	ds_read_b128 v[182:185], v239 offset:21504
	ds_read_b128 v[186:189], v239 offset:22528
	ds_read_b128 v[190:193], v239 offset:23552
	global_load_lds_dwordx4 v202, s[20:21]
	s_add_i32 m0, s0, 0x2000
	s_add_u32 s0, s20, 0x160000
	s_addc_u32 s1, s21, 0
	s_add_i32 s4, s33, s26
	global_load_lds_dwordx4 v208, s[20:21]
	s_mov_b32 m0, s4
	s_nop 0
	global_load_lds_dwordx4 v202, s[0:1]
	s_add_i32 m0, s4, 0x2000
	s_nop 0
	global_load_lds_dwordx4 v208, s[0:1]
	s_mov_b32 m0, s27
	s_nop 0
	global_load_lds_dwordx4 v212, s[22:23]
	s_mov_b32 m0, s28
	s_nop 0
	global_load_lds_dwordx4 v210, s[22:23]
	s_waitcnt vmcnt(8)
	s_waitcnt lgkmcnt(0)
	s_barrier
	v_mfma_f32_16x16x32_bf16 v[62:65], v[78:81], v[150:153], v[62:65]
	v_mfma_f32_16x16x32_bf16 v[58:61], v[94:97], v[150:153], v[58:61]
	v_mfma_f32_16x16x32_bf16 v[46:49], v[78:81], v[166:169], v[46:49]
	v_mfma_f32_16x16x32_bf16 v[42:45], v[94:97], v[166:169], v[42:45]
	v_mfma_f32_16x16x32_bf16 v[30:33], v[78:81], v[178:181], v[30:33]
	v_mfma_f32_16x16x32_bf16 v[26:29], v[94:97], v[178:181], v[26:29]
	v_mfma_f32_16x16x32_bf16 v[14:17], v[78:81], v[186:189], v[14:17]
	v_mfma_f32_16x16x32_bf16 v[10:13], v[94:97], v[186:189], v[10:13]
	v_mfma_f32_16x16x32_bf16 v[62:65], v[82:85], v[158:161], v[62:65]
	v_mfma_f32_16x16x32_bf16 v[58:61], v[98:101], v[158:161], v[58:61]
	v_mfma_f32_16x16x32_bf16 v[46:49], v[82:85], v[174:177], v[46:49]
	v_mfma_f32_16x16x32_bf16 v[42:45], v[98:101], v[174:177], v[42:45]
	v_mfma_f32_16x16x32_bf16 v[30:33], v[82:85], v[182:185], v[30:33]
	v_mfma_f32_16x16x32_bf16 v[26:29], v[98:101], v[182:185], v[26:29]
	v_mfma_f32_16x16x32_bf16 v[14:17], v[82:85], v[190:193], v[14:17]
	v_mfma_f32_16x16x32_bf16 v[10:13], v[98:101], v[190:193], v[10:13]
	v_mfma_f32_16x16x32_bf16 v[54:57], v[106:109], v[150:153], v[54:57]
	v_mfma_f32_16x16x32_bf16 v[50:53], v[126:129], v[150:153], v[50:53]
	v_mfma_f32_16x16x32_bf16 v[38:41], v[106:109], v[166:169], v[38:41]
	v_mfma_f32_16x16x32_bf16 v[34:37], v[126:129], v[166:169], v[34:37]
	v_mfma_f32_16x16x32_bf16 v[22:25], v[106:109], v[178:181], v[22:25]
	v_mfma_f32_16x16x32_bf16 v[18:21], v[126:129], v[178:181], v[18:21]
	v_mfma_f32_16x16x32_bf16 v[6:9], v[106:109], v[186:189], v[6:9]
	v_mfma_f32_16x16x32_bf16 v[2:5], v[126:129], v[186:189], v[2:5]
	v_mfma_f32_16x16x32_bf16 v[54:57], v[110:113], v[158:161], v[54:57]
	v_mfma_f32_16x16x32_bf16 v[50:53], v[134:137], v[158:161], v[50:53]
	v_mfma_f32_16x16x32_bf16 v[38:41], v[110:113], v[174:177], v[38:41]
	v_mfma_f32_16x16x32_bf16 v[34:37], v[134:137], v[174:177], v[34:37]
	v_mfma_f32_16x16x32_bf16 v[22:25], v[110:113], v[182:185], v[22:25]
	v_mfma_f32_16x16x32_bf16 v[18:21], v[134:137], v[182:185], v[18:21]
	v_mfma_f32_16x16x32_bf16 v[6:9], v[110:113], v[190:193], v[6:9]
	v_mfma_f32_16x16x32_bf16 v[2:5], v[134:137], v[190:193], v[2:5]
	s_barrier
	s_add_i32 s4, 0, 0x18000
	s_add_i32 s5, 0, 0x1c000
	ds_read_b128 v[78:81], v205 offset:32768
	ds_read_b128 v[82:85], v205 offset:33792
	ds_read_b128 v[94:97], v205 offset:34816
	ds_read_b128 v[98:101], v205 offset:35840
	ds_read_b128 v[106:109], v205 offset:49152
	ds_read_b128 v[110:113], v205 offset:50176
	ds_read_b128 v[126:129], v205 offset:51200
	ds_read_b128 v[134:137], v205 offset:52224
	s_add_u32 s0, s22, 0x160000
	s_addc_u32 s1, s23, 0
	s_mov_b32 m0, s29
	ds_read_b128 v[150:153], v239 offset:32768
	ds_read_b128 v[158:161], v239 offset:33792
	ds_read_b128 v[166:169], v239 offset:34816
	ds_read_b128 v[174:177], v239 offset:35840
	ds_read_b128 v[178:181], v239 offset:36864
	ds_read_b128 v[182:185], v239 offset:37888
	ds_read_b128 v[186:189], v239 offset:38912
	ds_read_b128 v[190:193], v239 offset:39936
	global_load_lds_dwordx4 v212, s[0:1]
	s_mov_b32 m0, s30
	s_nop 0
	global_load_lds_dwordx4 v210, s[0:1]
	s_waitcnt vmcnt(8)
	s_waitcnt lgkmcnt(0)
	s_barrier
	v_mfma_f32_16x16x32_bf16 v[170:173], v[78:81], v[150:153], v[170:173]
	v_mfma_f32_16x16x32_bf16 v[162:165], v[94:97], v[150:153], v[162:165]
	v_mfma_f32_16x16x32_bf16 v[142:145], v[78:81], v[166:169], v[142:145]
	v_mfma_f32_16x16x32_bf16 v[138:141], v[94:97], v[166:169], v[138:141]
	v_mfma_f32_16x16x32_bf16 v[118:121], v[78:81], v[178:181], v[118:121]
	v_mfma_f32_16x16x32_bf16 v[114:117], v[94:97], v[178:181], v[114:117]
	v_mfma_f32_16x16x32_bf16 v[86:89], v[78:81], v[186:189], v[86:89]
	v_mfma_f32_16x16x32_bf16 v[74:77], v[94:97], v[186:189], v[74:77]
	v_mfma_f32_16x16x32_bf16 v[170:173], v[82:85], v[158:161], v[170:173]
	v_mfma_f32_16x16x32_bf16 v[162:165], v[98:101], v[158:161], v[162:165]
	v_mfma_f32_16x16x32_bf16 v[142:145], v[82:85], v[174:177], v[142:145]
	v_mfma_f32_16x16x32_bf16 v[138:141], v[98:101], v[174:177], v[138:141]
	v_mfma_f32_16x16x32_bf16 v[118:121], v[82:85], v[182:185], v[118:121]
	v_mfma_f32_16x16x32_bf16 v[114:117], v[98:101], v[182:185], v[114:117]
	v_mfma_f32_16x16x32_bf16 v[86:89], v[82:85], v[190:193], v[86:89]
	v_mfma_f32_16x16x32_bf16 v[74:77], v[98:101], v[190:193], v[74:77]
	v_mfma_f32_16x16x32_bf16 v[154:157], v[106:109], v[150:153], v[154:157]
	v_mfma_f32_16x16x32_bf16 v[146:149], v[126:129], v[150:153], v[146:149]
	v_mfma_f32_16x16x32_bf16 v[130:133], v[106:109], v[166:169], v[130:133]
	v_mfma_f32_16x16x32_bf16 v[122:125], v[126:129], v[166:169], v[122:125]
	v_mfma_f32_16x16x32_bf16 v[102:105], v[106:109], v[178:181], v[102:105]
	v_mfma_f32_16x16x32_bf16 v[90:93], v[126:129], v[178:181], v[90:93]
	v_mfma_f32_16x16x32_bf16 v[70:73], v[106:109], v[186:189], v[70:73]
	v_mfma_f32_16x16x32_bf16 v[66:69], v[126:129], v[186:189], v[66:69]
	v_mfma_f32_16x16x32_bf16 v[154:157], v[110:113], v[158:161], v[154:157]
	v_mfma_f32_16x16x32_bf16 v[150:153], v[134:137], v[158:161], v[146:149]
	v_mfma_f32_16x16x32_bf16 v[130:133], v[110:113], v[174:177], v[130:133]
	v_mfma_f32_16x16x32_bf16 v[122:125], v[134:137], v[174:177], v[122:125]
	v_mfma_f32_16x16x32_bf16 v[102:105], v[110:113], v[182:185], v[102:105]
	v_mfma_f32_16x16x32_bf16 v[90:93], v[134:137], v[182:185], v[90:93]
	v_mfma_f32_16x16x32_bf16 v[70:73], v[110:113], v[190:193], v[70:73]
	v_mfma_f32_16x16x32_bf16 v[66:69], v[134:137], v[190:193], v[66:69]
	s_barrier
	s_add_i32 s0, s4, s26
	s_add_u32 s100, s20, 0x80
	s_addc_u32 s101, s21, 0
	s_mov_b32 m0, s0
	ds_read_b128 v[146:149], v239 offset:49152
	ds_read_b128 v[158:161], v239 offset:50176
	ds_read_b128 v[166:169], v239 offset:51200
	ds_read_b128 v[174:177], v239 offset:52224
	ds_read_b128 v[178:181], v239 offset:53248
	ds_read_b128 v[182:185], v239 offset:54272
	ds_read_b128 v[186:189], v239 offset:55296
	ds_read_b128 v[190:193], v239 offset:56320
	global_load_lds_dwordx4 v202, s[100:101]
	s_add_i32 m0, s0, 0x2000
	s_add_u32 s100, s20, 0x80
	s_addc_u32 s101, s21, 0
	s_add_u32 s0, s20, 0x160080
	s_addc_u32 s1, s21, 0
	s_add_i32 s4, s5, s26
	global_load_lds_dwordx4 v208, s[100:101]
	s_mov_b32 m0, s4
	s_nop 0
	global_load_lds_dwordx4 v202, s[0:1]
	s_add_i32 m0, s4, 0x2000
	s_nop 0
	global_load_lds_dwordx4 v208, s[0:1]
	s_add_u32 s100, s22, 0x80
	s_addc_u32 s101, s23, 0
	s_mov_b32 m0, s35
	s_nop 0
	global_load_lds_dwordx4 v212, s[100:101]
	s_add_u32 s100, s22, 0x80
	s_addc_u32 s101, s23, 0
	s_mov_b32 m0, s36
	s_nop 0
	global_load_lds_dwordx4 v210, s[100:101]
	s_waitcnt vmcnt(8)
	s_waitcnt lgkmcnt(0)
	s_barrier
	v_mfma_f32_16x16x32_bf16 v[62:65], v[78:81], v[146:149], v[62:65]
	v_mfma_f32_16x16x32_bf16 v[58:61], v[94:97], v[146:149], v[58:61]
	v_mfma_f32_16x16x32_bf16 v[46:49], v[78:81], v[166:169], v[46:49]
	v_mfma_f32_16x16x32_bf16 v[42:45], v[94:97], v[166:169], v[42:45]
	v_mfma_f32_16x16x32_bf16 v[30:33], v[78:81], v[178:181], v[30:33]
	v_mfma_f32_16x16x32_bf16 v[26:29], v[94:97], v[178:181], v[26:29]
	v_mfma_f32_16x16x32_bf16 v[14:17], v[78:81], v[186:189], v[14:17]
	v_mfma_f32_16x16x32_bf16 v[10:13], v[94:97], v[186:189], v[10:13]
	v_mfma_f32_16x16x32_bf16 v[62:65], v[82:85], v[158:161], v[62:65]
	v_mfma_f32_16x16x32_bf16 v[58:61], v[98:101], v[158:161], v[58:61]
	v_mfma_f32_16x16x32_bf16 v[46:49], v[82:85], v[174:177], v[46:49]
	v_mfma_f32_16x16x32_bf16 v[42:45], v[98:101], v[174:177], v[42:45]
	v_mfma_f32_16x16x32_bf16 v[30:33], v[82:85], v[182:185], v[30:33]
	v_mfma_f32_16x16x32_bf16 v[26:29], v[98:101], v[182:185], v[26:29]
	v_mfma_f32_16x16x32_bf16 v[14:17], v[82:85], v[190:193], v[14:17]
	v_mfma_f32_16x16x32_bf16 v[10:13], v[98:101], v[190:193], v[10:13]
	v_mfma_f32_16x16x32_bf16 v[54:57], v[106:109], v[146:149], v[54:57]
	v_mfma_f32_16x16x32_bf16 v[50:53], v[126:129], v[146:149], v[50:53]
	v_mfma_f32_16x16x32_bf16 v[38:41], v[106:109], v[166:169], v[38:41]
	v_mfma_f32_16x16x32_bf16 v[34:37], v[126:129], v[166:169], v[34:37]
	v_mfma_f32_16x16x32_bf16 v[22:25], v[106:109], v[178:181], v[22:25]
	v_mfma_f32_16x16x32_bf16 v[18:21], v[126:129], v[178:181], v[18:21]
	v_mfma_f32_16x16x32_bf16 v[6:9], v[106:109], v[186:189], v[6:9]
	v_mfma_f32_16x16x32_bf16 v[2:5], v[126:129], v[186:189], v[2:5]
	v_mfma_f32_16x16x32_bf16 v[54:57], v[110:113], v[158:161], v[54:57]
	v_mfma_f32_16x16x32_bf16 v[50:53], v[134:137], v[158:161], v[50:53]
	v_mfma_f32_16x16x32_bf16 v[38:41], v[110:113], v[174:177], v[38:41]
	v_mfma_f32_16x16x32_bf16 v[34:37], v[134:137], v[174:177], v[34:37]
	v_mfma_f32_16x16x32_bf16 v[22:25], v[110:113], v[182:185], v[22:25]
	v_mfma_f32_16x16x32_bf16 v[18:21], v[134:137], v[182:185], v[18:21]
	v_mfma_f32_16x16x32_bf16 v[6:9], v[110:113], v[190:193], v[6:9]
	v_mfma_f32_16x16x32_bf16 v[2:5], v[134:137], v[190:193], v[2:5]
	s_barrier
	s_add_i32 s59, s59, 2
	s_add_u32 s49, s49, 0x100
	s_addc_u32 s58, s58, 0
	s_cmpk_gt_u32 s59, 0x55
	s_mov_b64 s[4:5], s[18:19]
	s_cbranch_scc0 .LBB0_1718
	s_and_b64 vcc, exec, s[14:15]
	s_cbranch_vccz .LBB0_1721
	s_barrier

.LBB0_1739:
	s_add_u32 s16, s14, 0x100
	s_addc_u32 s17, s15, 0
	s_add_i32 s0, 0, 0x10000
	s_cmp_eq_u32 s49, 4
	s_cselect_b32 s21, s9, s17
	s_cselect_b32 s20, s8, s16
	s_cselect_b32 s19, s11, s41
	s_cselect_b32 s18, s10, s40
	s_add_i32 s33, 0, 0x14000
	ds_read_b128 v[140:143], v136
	ds_read_b128 v[144:147], v136 offset:1024
	ds_read_b128 v[148:151], v136 offset:2048
	ds_read_b128 v[152:155], v136 offset:3072
	ds_read_b128 v[156:159], v136 offset:16384
	ds_read_b128 v[160:163], v136 offset:17408
	ds_read_b128 v[164:167], v136 offset:18432
	ds_read_b128 v[168:171], v136 offset:19456
	s_add_i32 m0, s23, 0xc000
	ds_read_b128 v[172:175], v139
	ds_read_b128 v[176:179], v139 offset:1024
	ds_read_b128 v[180:183], v139 offset:2048
	ds_read_b128 v[184:187], v139 offset:3072
	ds_read_b128 v[188:191], v139 offset:4096
	ds_read_b128 v[192:195], v139 offset:5120
	ds_read_b128 v[196:199], v139 offset:6144
	ds_read_b128 v[208:211], v139 offset:7168
	global_load_lds_dwordx4 v132, s[14:15]
	s_add_i32 m0, s23, 0xe000
	s_nop 0
	global_load_lds_dwordx4 v134, s[14:15]
	s_waitcnt vmcnt(8)
	s_waitcnt lgkmcnt(0)
	s_barrier
	v_mfma_f32_16x16x32_bf16 v[126:129], v[140:143], v[172:175], v[126:129]
	v_mfma_f32_16x16x32_bf16 v[122:125], v[148:151], v[172:175], v[122:125]
	v_mfma_f32_16x16x32_bf16 v[118:121], v[140:143], v[180:183], v[118:121]
	v_mfma_f32_16x16x32_bf16 v[114:117], v[148:151], v[180:183], v[114:117]
	v_mfma_f32_16x16x32_bf16 v[106:109], v[140:143], v[188:191], v[106:109]
	v_mfma_f32_16x16x32_bf16 v[98:101], v[148:151], v[188:191], v[98:101]
	v_mfma_f32_16x16x32_bf16 v[90:93], v[140:143], v[196:199], v[90:93]
	v_mfma_f32_16x16x32_bf16 v[82:85], v[148:151], v[196:199], v[82:85]
	v_mfma_f32_16x16x32_bf16 v[126:129], v[144:147], v[176:179], v[126:129]
	v_mfma_f32_16x16x32_bf16 v[122:125], v[152:155], v[176:179], v[122:125]
	v_mfma_f32_16x16x32_bf16 v[118:121], v[144:147], v[184:187], v[118:121]
	v_mfma_f32_16x16x32_bf16 v[114:117], v[152:155], v[184:187], v[114:117]
	v_mfma_f32_16x16x32_bf16 v[106:109], v[144:147], v[192:195], v[106:109]
	v_mfma_f32_16x16x32_bf16 v[98:101], v[152:155], v[192:195], v[98:101]
	v_mfma_f32_16x16x32_bf16 v[90:93], v[144:147], v[208:211], v[90:93]
	v_mfma_f32_16x16x32_bf16 v[82:85], v[152:155], v[208:211], v[82:85]
	v_mfma_f32_16x16x32_bf16 v[110:113], v[156:159], v[172:175], v[110:113]
	v_mfma_f32_16x16x32_bf16 v[102:105], v[164:167], v[172:175], v[102:105]
	v_mfma_f32_16x16x32_bf16 v[94:97], v[156:159], v[180:183], v[94:97]
	v_mfma_f32_16x16x32_bf16 v[86:89], v[164:167], v[180:183], v[86:89]
	v_mfma_f32_16x16x32_bf16 v[78:81], v[156:159], v[188:191], v[78:81]
	v_mfma_f32_16x16x32_bf16 v[74:77], v[164:167], v[188:191], v[74:77]
	v_mfma_f32_16x16x32_bf16 v[70:73], v[156:159], v[196:199], v[70:73]
	v_mfma_f32_16x16x32_bf16 v[66:69], v[164:167], v[196:199], v[66:69]
	v_mfma_f32_16x16x32_bf16 v[110:113], v[160:163], v[176:179], v[110:113]
	v_mfma_f32_16x16x32_bf16 v[102:105], v[168:171], v[176:179], v[102:105]
	v_mfma_f32_16x16x32_bf16 v[94:97], v[160:163], v[184:187], v[94:97]
	v_mfma_f32_16x16x32_bf16 v[86:89], v[168:171], v[184:187], v[86:89]
	v_mfma_f32_16x16x32_bf16 v[78:81], v[160:163], v[192:195], v[78:81]
	v_mfma_f32_16x16x32_bf16 v[74:77], v[168:171], v[192:195], v[74:77]
	v_mfma_f32_16x16x32_bf16 v[70:73], v[160:163], v[208:211], v[70:73]
	v_mfma_f32_16x16x32_bf16 v[66:69], v[168:171], v[208:211], v[66:69]
	s_barrier
	s_add_i32 s0, s0, s22
	s_mov_b32 m0, s0
	ds_read_b128 v[172:175], v139 offset:16384
	ds_read_b128 v[176:179], v139 offset:17408
	ds_read_b128 v[180:183], v139 offset:18432
	ds_read_b128 v[184:187], v139 offset:19456
	ds_read_b128 v[188:191], v139 offset:20480
	ds_read_b128 v[192:195], v139 offset:21504
	ds_read_b128 v[196:199], v139 offset:22528
	ds_read_b128 v[208:211], v139 offset:23552
	global_load_lds_dwordx4 v202, s[18:19]
	s_add_i32 m0, s0, 0x2000
	s_add_u32 s0, s18, 0x160000
	s_addc_u32 s1, s19, 0
	s_add_i32 s14, s33, s22
	global_load_lds_dwordx4 v130, s[18:19]
	s_mov_b32 m0, s14
	s_nop 0
	global_load_lds_dwordx4 v202, s[0:1]
	s_add_i32 m0, s14, 0x2000
	s_nop 0
	global_load_lds_dwordx4 v130, s[0:1]
	s_mov_b32 m0, s23
	s_nop 0
	global_load_lds_dwordx4 v202, s[20:21]
	s_mov_b32 m0, s26
	s_nop 0
	global_load_lds_dwordx4 v130, s[20:21]
	s_waitcnt vmcnt(8)
	s_waitcnt lgkmcnt(0)
	s_barrier
	v_mfma_f32_16x16x32_bf16 v[62:65], v[140:143], v[172:175], v[62:65]
	v_mfma_f32_16x16x32_bf16 v[58:61], v[148:151], v[172:175], v[58:61]
	v_mfma_f32_16x16x32_bf16 v[54:57], v[140:143], v[180:183], v[54:57]
	v_mfma_f32_16x16x32_bf16 v[50:53], v[148:151], v[180:183], v[50:53]
	v_mfma_f32_16x16x32_bf16 v[38:41], v[140:143], v[188:191], v[38:41]
	v_mfma_f32_16x16x32_bf16 v[34:37], v[148:151], v[188:191], v[34:37]
	v_mfma_f32_16x16x32_bf16 v[22:25], v[140:143], v[196:199], v[22:25]
	v_mfma_f32_16x16x32_bf16 v[18:21], v[148:151], v[196:199], v[18:21]
	v_mfma_f32_16x16x32_bf16 v[62:65], v[144:147], v[176:179], v[62:65]
	v_mfma_f32_16x16x32_bf16 v[58:61], v[152:155], v[176:179], v[58:61]
	v_mfma_f32_16x16x32_bf16 v[54:57], v[144:147], v[184:187], v[54:57]
	v_mfma_f32_16x16x32_bf16 v[50:53], v[152:155], v[184:187], v[50:53]
	v_mfma_f32_16x16x32_bf16 v[38:41], v[144:147], v[192:195], v[38:41]
	v_mfma_f32_16x16x32_bf16 v[34:37], v[152:155], v[192:195], v[34:37]
	v_mfma_f32_16x16x32_bf16 v[22:25], v[144:147], v[208:211], v[22:25]
	v_mfma_f32_16x16x32_bf16 v[18:21], v[152:155], v[208:211], v[18:21]
	v_mfma_f32_16x16x32_bf16 v[46:49], v[156:159], v[172:175], v[46:49]
	v_mfma_f32_16x16x32_bf16 v[42:45], v[164:167], v[172:175], v[42:45]
	v_mfma_f32_16x16x32_bf16 v[30:33], v[156:159], v[180:183], v[30:33]
	v_mfma_f32_16x16x32_bf16 v[26:29], v[164:167], v[180:183], v[26:29]
	v_mfma_f32_16x16x32_bf16 v[14:17], v[156:159], v[188:191], v[14:17]
	v_mfma_f32_16x16x32_bf16 v[10:13], v[164:167], v[188:191], v[10:13]
	v_mfma_f32_16x16x32_bf16 v[6:9], v[156:159], v[196:199], v[6:9]
	v_mfma_f32_16x16x32_bf16 v[2:5], v[164:167], v[196:199], v[2:5]
	v_mfma_f32_16x16x32_bf16 v[46:49], v[160:163], v[176:179], v[46:49]
	v_mfma_f32_16x16x32_bf16 v[42:45], v[168:171], v[176:179], v[42:45]
	v_mfma_f32_16x16x32_bf16 v[30:33], v[160:163], v[184:187], v[30:33]
	v_mfma_f32_16x16x32_bf16 v[26:29], v[168:171], v[184:187], v[26:29]
	v_mfma_f32_16x16x32_bf16 v[14:17], v[160:163], v[192:195], v[14:17]
	v_mfma_f32_16x16x32_bf16 v[10:13], v[168:171], v[192:195], v[10:13]
	v_mfma_f32_16x16x32_bf16 v[6:9], v[160:163], v[208:211], v[6:9]
	v_mfma_f32_16x16x32_bf16 v[2:5], v[168:171], v[208:211], v[2:5]
	s_barrier
	s_add_i32 s14, 0, 0x18000
	s_add_i32 s15, 0, 0x1c000
	ds_read_b128 v[140:143], v136 offset:32768
	ds_read_b128 v[144:147], v136 offset:33792
	ds_read_b128 v[148:151], v136 offset:34816
	ds_read_b128 v[152:155], v136 offset:35840
	ds_read_b128 v[156:159], v136 offset:49152
	ds_read_b128 v[160:163], v136 offset:50176
	ds_read_b128 v[164:167], v136 offset:51200
	ds_read_b128 v[168:171], v136 offset:52224
	s_add_u32 s0, s20, 0x160000
	s_addc_u32 s1, s21, 0
	s_mov_b32 m0, s27
	ds_read_b128 v[172:175], v139 offset:32768
	ds_read_b128 v[176:179], v139 offset:33792
	ds_read_b128 v[180:183], v139 offset:34816
	ds_read_b128 v[184:187], v139 offset:35840
	ds_read_b128 v[188:191], v139 offset:36864
	ds_read_b128 v[192:195], v139 offset:37888
	ds_read_b128 v[196:199], v139 offset:38912
	ds_read_b128 v[208:211], v139 offset:39936
	global_load_lds_dwordx4 v202, s[0:1]
	s_mov_b32 m0, s28
	s_nop 0
	global_load_lds_dwordx4 v130, s[0:1]
	s_waitcnt vmcnt(8)
	s_waitcnt lgkmcnt(0)
	s_barrier
	v_mfma_f32_16x16x32_bf16 v[126:129], v[140:143], v[172:175], v[126:129]
	v_mfma_f32_16x16x32_bf16 v[122:125], v[148:151], v[172:175], v[122:125]
	v_mfma_f32_16x16x32_bf16 v[118:121], v[140:143], v[180:183], v[118:121]
	v_mfma_f32_16x16x32_bf16 v[114:117], v[148:151], v[180:183], v[114:117]
	v_mfma_f32_16x16x32_bf16 v[106:109], v[140:143], v[188:191], v[106:109]
	v_mfma_f32_16x16x32_bf16 v[98:101], v[148:151], v[188:191], v[98:101]
	v_mfma_f32_16x16x32_bf16 v[90:93], v[140:143], v[196:199], v[90:93]
	v_mfma_f32_16x16x32_bf16 v[82:85], v[148:151], v[196:199], v[82:85]
	v_mfma_f32_16x16x32_bf16 v[126:129], v[144:147], v[176:179], v[126:129]
	v_mfma_f32_16x16x32_bf16 v[122:125], v[152:155], v[176:179], v[122:125]
	v_mfma_f32_16x16x32_bf16 v[118:121], v[144:147], v[184:187], v[118:121]
	v_mfma_f32_16x16x32_bf16 v[114:117], v[152:155], v[184:187], v[114:117]
	v_mfma_f32_16x16x32_bf16 v[106:109], v[144:147], v[192:195], v[106:109]
	v_mfma_f32_16x16x32_bf16 v[98:101], v[152:155], v[192:195], v[98:101]
	v_mfma_f32_16x16x32_bf16 v[90:93], v[144:147], v[208:211], v[90:93]
	v_mfma_f32_16x16x32_bf16 v[82:85], v[152:155], v[208:211], v[82:85]
	v_mfma_f32_16x16x32_bf16 v[110:113], v[156:159], v[172:175], v[110:113]
	v_mfma_f32_16x16x32_bf16 v[102:105], v[164:167], v[172:175], v[102:105]
	v_mfma_f32_16x16x32_bf16 v[94:97], v[156:159], v[180:183], v[94:97]
	v_mfma_f32_16x16x32_bf16 v[86:89], v[164:167], v[180:183], v[86:89]
	v_mfma_f32_16x16x32_bf16 v[78:81], v[156:159], v[188:191], v[78:81]
	v_mfma_f32_16x16x32_bf16 v[74:77], v[164:167], v[188:191], v[74:77]
	v_mfma_f32_16x16x32_bf16 v[70:73], v[156:159], v[196:199], v[70:73]
	v_mfma_f32_16x16x32_bf16 v[66:69], v[164:167], v[196:199], v[66:69]
	v_mfma_f32_16x16x32_bf16 v[110:113], v[160:163], v[176:179], v[110:113]
	v_mfma_f32_16x16x32_bf16 v[102:105], v[168:171], v[176:179], v[102:105]
	v_mfma_f32_16x16x32_bf16 v[94:97], v[160:163], v[184:187], v[94:97]
	v_mfma_f32_16x16x32_bf16 v[86:89], v[168:171], v[184:187], v[86:89]
	v_mfma_f32_16x16x32_bf16 v[78:81], v[160:163], v[192:195], v[78:81]
	v_mfma_f32_16x16x32_bf16 v[74:77], v[168:171], v[192:195], v[74:77]
	v_mfma_f32_16x16x32_bf16 v[70:73], v[160:163], v[208:211], v[70:73]
	v_mfma_f32_16x16x32_bf16 v[66:69], v[168:171], v[208:211], v[66:69]
	s_barrier
	s_add_i32 s0, s14, s22
	s_add_u32 s100, s18, 0x80
	s_addc_u32 s101, s19, 0
	s_mov_b32 m0, s0
	ds_read_b128 v[172:175], v139 offset:49152
	ds_read_b128 v[176:179], v139 offset:50176
	ds_read_b128 v[180:183], v139 offset:51200
	ds_read_b128 v[184:187], v139 offset:52224
	ds_read_b128 v[188:191], v139 offset:53248
	ds_read_b128 v[192:195], v139 offset:54272
	ds_read_b128 v[196:199], v139 offset:55296
	ds_read_b128 v[208:211], v139 offset:56320
	global_load_lds_dwordx4 v202, s[100:101]
	s_add_i32 m0, s0, 0x2000
	s_add_u32 s100, s18, 0x80
	s_addc_u32 s101, s19, 0
	s_add_u32 s0, s18, 0x160080
	s_addc_u32 s1, s19, 0
	s_add_i32 s14, s15, s22
	global_load_lds_dwordx4 v130, s[100:101]
	s_mov_b32 m0, s14
	s_nop 0
	global_load_lds_dwordx4 v202, s[0:1]
	s_add_i32 m0, s14, 0x2000
	s_nop 0
	global_load_lds_dwordx4 v130, s[0:1]
	s_add_u32 s100, s20, 0x80
	s_addc_u32 s101, s21, 0
	s_mov_b32 m0, s29
	s_nop 0
	global_load_lds_dwordx4 v202, s[100:101]
	s_add_u32 s100, s20, 0x80
	s_addc_u32 s101, s21, 0
	s_mov_b32 m0, s30
	s_nop 0
	global_load_lds_dwordx4 v130, s[100:101]
	s_waitcnt vmcnt(8)
	s_waitcnt lgkmcnt(0)
	s_barrier
	v_mfma_f32_16x16x32_bf16 v[62:65], v[140:143], v[172:175], v[62:65]
	v_mfma_f32_16x16x32_bf16 v[58:61], v[148:151], v[172:175], v[58:61]
	v_mfma_f32_16x16x32_bf16 v[54:57], v[140:143], v[180:183], v[54:57]
	v_mfma_f32_16x16x32_bf16 v[50:53], v[148:151], v[180:183], v[50:53]
	v_mfma_f32_16x16x32_bf16 v[38:41], v[140:143], v[188:191], v[38:41]
	v_mfma_f32_16x16x32_bf16 v[34:37], v[148:151], v[188:191], v[34:37]
	v_mfma_f32_16x16x32_bf16 v[22:25], v[140:143], v[196:199], v[22:25]
	v_mfma_f32_16x16x32_bf16 v[18:21], v[148:151], v[196:199], v[18:21]
	v_mfma_f32_16x16x32_bf16 v[62:65], v[144:147], v[176:179], v[62:65]
	v_mfma_f32_16x16x32_bf16 v[58:61], v[152:155], v[176:179], v[58:61]
	v_mfma_f32_16x16x32_bf16 v[54:57], v[144:147], v[184:187], v[54:57]
	v_mfma_f32_16x16x32_bf16 v[50:53], v[152:155], v[184:187], v[50:53]
	v_mfma_f32_16x16x32_bf16 v[38:41], v[144:147], v[192:195], v[38:41]
	v_mfma_f32_16x16x32_bf16 v[34:37], v[152:155], v[192:195], v[34:37]
	v_mfma_f32_16x16x32_bf16 v[22:25], v[144:147], v[208:211], v[22:25]
	v_mfma_f32_16x16x32_bf16 v[18:21], v[152:155], v[208:211], v[18:21]
	v_mfma_f32_16x16x32_bf16 v[46:49], v[156:159], v[172:175], v[46:49]
	v_mfma_f32_16x16x32_bf16 v[42:45], v[164:167], v[172:175], v[42:45]
	v_mfma_f32_16x16x32_bf16 v[30:33], v[156:159], v[180:183], v[30:33]
	v_mfma_f32_16x16x32_bf16 v[26:29], v[164:167], v[180:183], v[26:29]
	v_mfma_f32_16x16x32_bf16 v[14:17], v[156:159], v[188:191], v[14:17]
	v_mfma_f32_16x16x32_bf16 v[10:13], v[164:167], v[188:191], v[10:13]
	v_mfma_f32_16x16x32_bf16 v[6:9], v[156:159], v[196:199], v[6:9]
	v_mfma_f32_16x16x32_bf16 v[2:5], v[164:167], v[196:199], v[2:5]
	v_mfma_f32_16x16x32_bf16 v[46:49], v[160:163], v[176:179], v[46:49]
	v_mfma_f32_16x16x32_bf16 v[42:45], v[168:171], v[176:179], v[42:45]
	v_mfma_f32_16x16x32_bf16 v[30:33], v[160:163], v[184:187], v[30:33]
	v_mfma_f32_16x16x32_bf16 v[26:29], v[168:171], v[184:187], v[26:29]
	v_mfma_f32_16x16x32_bf16 v[14:17], v[160:163], v[192:195], v[14:17]
	v_mfma_f32_16x16x32_bf16 v[10:13], v[168:171], v[192:195], v[10:13]
	v_mfma_f32_16x16x32_bf16 v[6:9], v[160:163], v[208:211], v[6:9]
	v_mfma_f32_16x16x32_bf16 v[2:5], v[168:171], v[208:211], v[2:5]
	s_barrier
	s_add_i32 s49, s49, 2
	s_add_u32 s40, s40, 0x100
	s_addc_u32 s41, s41, 0
	s_cmp_gt_u32 s49, 5
	s_mov_b64 s[14:15], s[16:17]
	s_cbranch_scc0 .LBB0_1739
	s_and_b64 vcc, exec, s[6:7]
	s_cbranch_vccz .LBB0_1742
	s_barrier
